# K-loop micro-trims: priority raise before segment barrier, dropped redundant post-barrier lgkmcnt(0) and mid-segment setprio pairs
# speedup vs baseline: 1.0290x; 1.0064x over previous
.LBB0_140:
	s_ashr_i32 s37, s36, 31
	s_lshl_b64 s[42:43], s[36:37], 19
	s_add_u32 s42, s62, s42
	s_addc_u32 s43, s63, s43
	s_and_b64 s[44:45], s[0:1], exec
	s_cselect_b32 s37, s43, s49
	s_cselect_b32 s77, s42, s48
	s_ashr_i32 s39, s38, 31
	s_lshl_b64 s[44:45], s[38:39], 19
	s_add_u32 s44, s54, s44
	s_addc_u32 s45, s55, s45
	s_and_b64 s[52:53], s[0:1], exec
	s_cselect_b32 s39, s45, s51
	s_cselect_b32 s78, s44, s50
	s_add_u32 s48, s48, 0x40080
	s_addc_u32 s49, s49, 0
	s_add_u32 s79, s50, 0x100
	s_addc_u32 s80, s51, 0
	s_mov_b32 s81, -2
	ds_read_b128 v[150:153], v147
	ds_read_b128 v[154:157], v147 offset:1024
	ds_read_b128 v[158:161], v147 offset:2048
	ds_read_b128 v[162:165], v147 offset:3072
	ds_read_b128 v[166:169], v148
	ds_read_b128 v[170:173], v148 offset:1024
	ds_read_b128 v[174:177], v148 offset:2048
	ds_read_b128 v[178:181], v148 offset:3072
	s_add_u32 s50, s48, 0xfffc0080
	s_addc_u32 s51, s49, -1
	s_cmp_eq_u32 s81, 12
	s_cselect_b32 s53, s37, s51
	s_cselect_b32 s52, s77, s50
	s_cselect_b32 s51, s39, s80
	s_cselect_b32 s50, s78, s79
	v_lshl_add_u64 v[214:215], s[48:49], 0, v[136:137]
	s_add_i32 m0, s47, 0xc000
	ds_read_b128 v[182:185], v149
	ds_read_b128 v[186:189], v149 offset:1024
	ds_read_b128 v[190:193], v149 offset:2048
	ds_read_b128 v[194:197], v149 offset:3072
	ds_read_b128 v[198:201], v149 offset:4096
	ds_read_b128 v[202:205], v149 offset:5120
	ds_read_b128 v[206:209], v149 offset:6144
	ds_read_b128 v[210:213], v149 offset:7168
	global_load_lds_dwordx4 v[214:215], off
	v_lshl_add_u64 v[214:215], s[48:49], 0, v[138:139]
	s_add_i32 m0, s47, 0xe000
	s_nop 0
	global_load_lds_dwordx4 v[214:215], off
	s_waitcnt vmcnt(8)
	s_waitcnt lgkmcnt(0)
	s_setprio 1
	s_barrier
	v_mfma_f32_16x16x32_bf16 v[124:127], v[150:153], v[182:185], 0
	v_mfma_f32_16x16x32_bf16 v[116:119], v[158:161], v[182:185], 0
	v_mfma_f32_16x16x32_bf16 v[108:111], v[150:153], v[190:193], 0
	v_mfma_f32_16x16x32_bf16 v[100:103], v[158:161], v[190:193], 0
	v_mfma_f32_16x16x32_bf16 v[92:95], v[150:153], v[198:201], 0
	v_mfma_f32_16x16x32_bf16 v[84:87], v[158:161], v[198:201], 0
	v_mfma_f32_16x16x32_bf16 v[76:79], v[150:153], v[206:209], 0
	v_mfma_f32_16x16x32_bf16 v[68:71], v[158:161], v[206:209], 0
	v_mfma_f32_16x16x32_bf16 v[124:127], v[154:157], v[186:189], v[124:127]
	v_mfma_f32_16x16x32_bf16 v[116:119], v[162:165], v[186:189], v[116:119]
	v_mfma_f32_16x16x32_bf16 v[108:111], v[154:157], v[194:197], v[108:111]
	v_mfma_f32_16x16x32_bf16 v[100:103], v[162:165], v[194:197], v[100:103]
	v_mfma_f32_16x16x32_bf16 v[92:95], v[154:157], v[202:205], v[92:95]
	v_mfma_f32_16x16x32_bf16 v[84:87], v[162:165], v[202:205], v[84:87]
	v_mfma_f32_16x16x32_bf16 v[76:79], v[154:157], v[210:213], v[76:79]
	v_mfma_f32_16x16x32_bf16 v[68:71], v[162:165], v[210:213], v[68:71]
	v_mfma_f32_16x16x32_bf16 v[120:123], v[166:169], v[182:185], 0
	v_mfma_f32_16x16x32_bf16 v[112:115], v[174:177], v[182:185], 0
	v_mfma_f32_16x16x32_bf16 v[104:107], v[166:169], v[190:193], 0
	v_mfma_f32_16x16x32_bf16 v[96:99], v[174:177], v[190:193], 0
	v_mfma_f32_16x16x32_bf16 v[88:91], v[166:169], v[198:201], 0
	v_mfma_f32_16x16x32_bf16 v[80:83], v[174:177], v[198:201], 0
	v_mfma_f32_16x16x32_bf16 v[72:75], v[166:169], v[206:209], 0
	v_mfma_f32_16x16x32_bf16 v[64:67], v[174:177], v[206:209], 0
	v_mfma_f32_16x16x32_bf16 v[120:123], v[170:173], v[186:189], v[120:123]
	v_mfma_f32_16x16x32_bf16 v[112:115], v[178:181], v[186:189], v[112:115]
	v_mfma_f32_16x16x32_bf16 v[104:107], v[170:173], v[194:197], v[104:107]
	v_mfma_f32_16x16x32_bf16 v[96:99], v[178:181], v[194:197], v[96:99]
	v_mfma_f32_16x16x32_bf16 v[88:91], v[170:173], v[202:205], v[88:91]
	v_mfma_f32_16x16x32_bf16 v[80:83], v[178:181], v[202:205], v[80:83]
	v_mfma_f32_16x16x32_bf16 v[72:75], v[170:173], v[210:213], v[72:75]
	v_mfma_f32_16x16x32_bf16 v[64:67], v[178:181], v[210:213], v[64:67]
	s_barrier
	s_setprio 0
	s_add_i32 s82, s73, s56
	v_lshl_add_u64 v[214:215], s[50:51], 0, v[132:133]
	s_mov_b32 m0, s82
	ds_read_b128 v[182:185], v149 offset:16384
	ds_read_b128 v[186:189], v149 offset:17408
	ds_read_b128 v[190:193], v149 offset:18432
	ds_read_b128 v[194:197], v149 offset:19456
	ds_read_b128 v[198:201], v149 offset:20480
	ds_read_b128 v[202:205], v149 offset:21504
	ds_read_b128 v[206:209], v149 offset:22528
	ds_read_b128 v[210:213], v149 offset:23552
	global_load_lds_dwordx4 v[214:215], off
	s_add_i32 m0, s82, 0x2000
	s_add_u32 s88, s50, 0x40000
	v_lshl_add_u64 v[216:217], s[50:51], 0, v[128:129]
	s_addc_u32 s89, s51, 0
	s_add_i32 s82, s74, s56
	global_load_lds_dwordx4 v[216:217], off
	v_lshl_add_u64 v[218:219], s[88:89], 0, v[132:133]
	s_mov_b32 m0, s82
	v_lshl_add_u64 v[220:221], s[52:53], 0, v[130:131]
	global_load_lds_dwordx4 v[218:219], off
	v_lshl_add_u64 v[218:219], s[88:89], 0, v[128:129]
	s_add_i32 m0, s82, 0x2000
	s_nop 0
	global_load_lds_dwordx4 v[218:219], off
	v_lshl_add_u64 v[218:219], s[52:53], 0, v[134:135]
	s_mov_b32 m0, s47
	s_nop 0
	global_load_lds_dwordx4 v[218:219], off
	s_mov_b32 m0, s59
	s_nop 0
	global_load_lds_dwordx4 v[220:221], off
	s_waitcnt vmcnt(8)
	s_waitcnt lgkmcnt(0)
	s_setprio 1
	s_barrier
	v_mfma_f32_16x16x32_bf16 v[60:63], v[150:153], v[182:185], 0
	v_mfma_f32_16x16x32_bf16 v[52:55], v[158:161], v[182:185], 0
	v_mfma_f32_16x16x32_bf16 v[44:47], v[150:153], v[190:193], 0
	v_mfma_f32_16x16x32_bf16 v[36:39], v[158:161], v[190:193], 0
	v_mfma_f32_16x16x32_bf16 v[28:31], v[150:153], v[198:201], 0
	v_mfma_f32_16x16x32_bf16 v[20:23], v[158:161], v[198:201], 0
	v_mfma_f32_16x16x32_bf16 v[12:15], v[150:153], v[206:209], 0
	v_mfma_f32_16x16x32_bf16 v[4:7], v[158:161], v[206:209], 0
	v_mfma_f32_16x16x32_bf16 v[60:63], v[154:157], v[186:189], v[60:63]
	v_mfma_f32_16x16x32_bf16 v[52:55], v[162:165], v[186:189], v[52:55]
	v_mfma_f32_16x16x32_bf16 v[44:47], v[154:157], v[194:197], v[44:47]
	v_mfma_f32_16x16x32_bf16 v[36:39], v[162:165], v[194:197], v[36:39]
	v_mfma_f32_16x16x32_bf16 v[28:31], v[154:157], v[202:205], v[28:31]
	v_mfma_f32_16x16x32_bf16 v[20:23], v[162:165], v[202:205], v[20:23]
	v_mfma_f32_16x16x32_bf16 v[12:15], v[154:157], v[210:213], v[12:15]
	v_mfma_f32_16x16x32_bf16 v[4:7], v[162:165], v[210:213], v[4:7]
	v_mfma_f32_16x16x32_bf16 v[56:59], v[166:169], v[182:185], 0
	v_mfma_f32_16x16x32_bf16 v[48:51], v[174:177], v[182:185], 0
	v_mfma_f32_16x16x32_bf16 v[40:43], v[166:169], v[190:193], 0
	v_mfma_f32_16x16x32_bf16 v[32:35], v[174:177], v[190:193], 0
	v_mfma_f32_16x16x32_bf16 v[24:27], v[166:169], v[198:201], 0
	v_mfma_f32_16x16x32_bf16 v[16:19], v[174:177], v[198:201], 0
	v_mfma_f32_16x16x32_bf16 v[8:11], v[166:169], v[206:209], 0
	v_mfma_f32_16x16x32_bf16 v[0:3], v[174:177], v[206:209], 0
	v_mfma_f32_16x16x32_bf16 v[56:59], v[170:173], v[186:189], v[56:59]
	v_mfma_f32_16x16x32_bf16 v[48:51], v[178:181], v[186:189], v[48:51]
	v_mfma_f32_16x16x32_bf16 v[40:43], v[170:173], v[194:197], v[40:43]
	v_mfma_f32_16x16x32_bf16 v[32:35], v[178:181], v[194:197], v[32:35]
	v_mfma_f32_16x16x32_bf16 v[24:27], v[170:173], v[202:205], v[24:27]
	v_mfma_f32_16x16x32_bf16 v[16:19], v[178:181], v[202:205], v[16:19]
	v_mfma_f32_16x16x32_bf16 v[8:11], v[170:173], v[210:213], v[8:11]
	v_mfma_f32_16x16x32_bf16 v[0:3], v[178:181], v[210:213], v[0:3]
	s_barrier
	s_setprio 0
	s_add_i32 s82, 0, 0x18000
	s_add_i32 s85, 0, 0x1c000
	v_add_u32_e32 v162, s82, v145
	v_add_u32_e32 v178, s85, v145
	ds_read_b128 v[150:153], v162
	ds_read_b128 v[154:157], v162 offset:1024
	ds_read_b128 v[158:161], v162 offset:2048
	ds_read_b128 v[162:165], v162 offset:3072
	ds_read_b128 v[166:169], v178
	ds_read_b128 v[170:173], v178 offset:1024
	ds_read_b128 v[174:177], v178 offset:2048
	ds_read_b128 v[178:181], v178 offset:3072
	s_add_u32 s52, s52, 0x40000
	s_addc_u32 s53, s53, 0
	s_mov_b32 m0, s66
	v_lshl_add_u64 v[222:223], s[52:53], 0, v[134:135]
	ds_read_b128 v[182:185], v149 offset:32768
	ds_read_b128 v[186:189], v149 offset:33792
	ds_read_b128 v[190:193], v149 offset:34816
	ds_read_b128 v[194:197], v149 offset:35840
	ds_read_b128 v[198:201], v149 offset:36864
	ds_read_b128 v[202:205], v149 offset:37888
	ds_read_b128 v[206:209], v149 offset:38912
	ds_read_b128 v[210:213], v149 offset:39936
	global_load_lds_dwordx4 v[222:223], off
	v_lshl_add_u64 v[222:223], s[52:53], 0, v[130:131]
	s_mov_b32 m0, s67
	s_nop 0
	global_load_lds_dwordx4 v[222:223], off
	s_waitcnt vmcnt(8)
	s_waitcnt lgkmcnt(0)
	s_setprio 1
	s_barrier
	v_mfma_f32_16x16x32_bf16 v[124:127], v[150:153], v[182:185], v[124:127]
	v_mfma_f32_16x16x32_bf16 v[116:119], v[158:161], v[182:185], v[116:119]
	v_mfma_f32_16x16x32_bf16 v[108:111], v[150:153], v[190:193], v[108:111]
	v_mfma_f32_16x16x32_bf16 v[100:103], v[158:161], v[190:193], v[100:103]
	v_mfma_f32_16x16x32_bf16 v[92:95], v[150:153], v[198:201], v[92:95]
	v_mfma_f32_16x16x32_bf16 v[84:87], v[158:161], v[198:201], v[84:87]
	v_mfma_f32_16x16x32_bf16 v[76:79], v[150:153], v[206:209], v[76:79]
	v_mfma_f32_16x16x32_bf16 v[68:71], v[158:161], v[206:209], v[68:71]
	v_mfma_f32_16x16x32_bf16 v[124:127], v[154:157], v[186:189], v[124:127]
	v_mfma_f32_16x16x32_bf16 v[116:119], v[162:165], v[186:189], v[116:119]
	v_mfma_f32_16x16x32_bf16 v[108:111], v[154:157], v[194:197], v[108:111]
	v_mfma_f32_16x16x32_bf16 v[100:103], v[162:165], v[194:197], v[100:103]
	v_mfma_f32_16x16x32_bf16 v[92:95], v[154:157], v[202:205], v[92:95]
	v_mfma_f32_16x16x32_bf16 v[84:87], v[162:165], v[202:205], v[84:87]
	v_mfma_f32_16x16x32_bf16 v[76:79], v[154:157], v[210:213], v[76:79]
	v_mfma_f32_16x16x32_bf16 v[68:71], v[162:165], v[210:213], v[68:71]
	v_mfma_f32_16x16x32_bf16 v[120:123], v[166:169], v[182:185], v[120:123]
	v_mfma_f32_16x16x32_bf16 v[112:115], v[174:177], v[182:185], v[112:115]
	v_mfma_f32_16x16x32_bf16 v[104:107], v[166:169], v[190:193], v[104:107]
	v_mfma_f32_16x16x32_bf16 v[96:99], v[174:177], v[190:193], v[96:99]
	v_mfma_f32_16x16x32_bf16 v[88:91], v[166:169], v[198:201], v[88:91]
	v_mfma_f32_16x16x32_bf16 v[80:83], v[174:177], v[198:201], v[80:83]
	v_mfma_f32_16x16x32_bf16 v[72:75], v[166:169], v[206:209], v[72:75]
	v_mfma_f32_16x16x32_bf16 v[64:67], v[174:177], v[206:209], v[64:67]
	v_mfma_f32_16x16x32_bf16 v[120:123], v[170:173], v[186:189], v[120:123]
	v_mfma_f32_16x16x32_bf16 v[112:115], v[178:181], v[186:189], v[112:115]
	v_mfma_f32_16x16x32_bf16 v[104:107], v[170:173], v[194:197], v[104:107]
	v_mfma_f32_16x16x32_bf16 v[96:99], v[178:181], v[194:197], v[96:99]
	v_mfma_f32_16x16x32_bf16 v[88:91], v[170:173], v[202:205], v[88:91]
	v_mfma_f32_16x16x32_bf16 v[80:83], v[178:181], v[202:205], v[80:83]
	v_mfma_f32_16x16x32_bf16 v[72:75], v[170:173], v[210:213], v[72:75]
	v_mfma_f32_16x16x32_bf16 v[64:67], v[178:181], v[210:213], v[64:67]
	s_barrier
	s_setprio 0
	s_add_i32 s52, s82, s56
	v_lshl_add_u64 v[214:215], v[214:215], 0, s[10:11]
	s_mov_b32 m0, s52
	ds_read_b128 v[182:185], v149 offset:49152
	ds_read_b128 v[186:189], v149 offset:50176
	ds_read_b128 v[190:193], v149 offset:51200
	ds_read_b128 v[194:197], v149 offset:52224
	ds_read_b128 v[198:201], v149 offset:53248
	ds_read_b128 v[202:205], v149 offset:54272
	ds_read_b128 v[206:209], v149 offset:55296
	ds_read_b128 v[210:213], v149 offset:56320
	global_load_lds_dwordx4 v[214:215], off
	s_add_i32 m0, s52, 0x2000
	s_add_u32 s50, s50, 0x40080
	v_lshl_add_u64 v[214:215], v[216:217], 0, s[10:11]
	s_addc_u32 s51, s51, 0
	s_add_i32 s52, s85, s56
	global_load_lds_dwordx4 v[214:215], off
	v_lshl_add_u64 v[214:215], s[50:51], 0, v[132:133]
	s_mov_b32 m0, s52
	s_nop 0
	global_load_lds_dwordx4 v[214:215], off
	v_lshl_add_u64 v[214:215], s[50:51], 0, v[128:129]
	s_add_i32 m0, s52, 0x2000
	s_nop 0
	global_load_lds_dwordx4 v[214:215], off
	v_lshl_add_u64 v[214:215], v[218:219], 0, s[10:11]
	s_mov_b32 m0, s69
	s_nop 0
	global_load_lds_dwordx4 v[214:215], off
	v_lshl_add_u64 v[214:215], v[220:221], 0, s[10:11]
	s_mov_b32 m0, s70
	s_nop 0
	global_load_lds_dwordx4 v[214:215], off
	s_waitcnt vmcnt(8)
	s_waitcnt lgkmcnt(0)
	s_setprio 1
	s_barrier
	v_mfma_f32_16x16x32_bf16 v[60:63], v[150:153], v[182:185], v[60:63]
	v_mfma_f32_16x16x32_bf16 v[52:55], v[158:161], v[182:185], v[52:55]
	v_mfma_f32_16x16x32_bf16 v[44:47], v[150:153], v[190:193], v[44:47]
	v_mfma_f32_16x16x32_bf16 v[36:39], v[158:161], v[190:193], v[36:39]
	v_mfma_f32_16x16x32_bf16 v[28:31], v[150:153], v[198:201], v[28:31]
	v_mfma_f32_16x16x32_bf16 v[20:23], v[158:161], v[198:201], v[20:23]
	v_mfma_f32_16x16x32_bf16 v[12:15], v[150:153], v[206:209], v[12:15]
	v_mfma_f32_16x16x32_bf16 v[4:7], v[158:161], v[206:209], v[4:7]
	v_mfma_f32_16x16x32_bf16 v[60:63], v[154:157], v[186:189], v[60:63]
	v_mfma_f32_16x16x32_bf16 v[52:55], v[162:165], v[186:189], v[52:55]
	v_mfma_f32_16x16x32_bf16 v[44:47], v[154:157], v[194:197], v[44:47]
	v_mfma_f32_16x16x32_bf16 v[36:39], v[162:165], v[194:197], v[36:39]
	v_mfma_f32_16x16x32_bf16 v[28:31], v[154:157], v[202:205], v[28:31]
	v_mfma_f32_16x16x32_bf16 v[20:23], v[162:165], v[202:205], v[20:23]
	v_mfma_f32_16x16x32_bf16 v[12:15], v[154:157], v[210:213], v[12:15]
	v_mfma_f32_16x16x32_bf16 v[4:7], v[162:165], v[210:213], v[4:7]
	v_mfma_f32_16x16x32_bf16 v[56:59], v[166:169], v[182:185], v[56:59]
	v_mfma_f32_16x16x32_bf16 v[48:51], v[174:177], v[182:185], v[48:51]
	v_mfma_f32_16x16x32_bf16 v[40:43], v[166:169], v[190:193], v[40:43]
	v_mfma_f32_16x16x32_bf16 v[32:35], v[174:177], v[190:193], v[32:35]
	v_mfma_f32_16x16x32_bf16 v[24:27], v[166:169], v[198:201], v[24:27]
	v_mfma_f32_16x16x32_bf16 v[16:19], v[174:177], v[198:201], v[16:19]
	v_mfma_f32_16x16x32_bf16 v[8:11], v[166:169], v[206:209], v[8:11]
	v_mfma_f32_16x16x32_bf16 v[0:3], v[174:177], v[206:209], v[0:3]
	v_mfma_f32_16x16x32_bf16 v[56:59], v[170:173], v[186:189], v[56:59]
	v_mfma_f32_16x16x32_bf16 v[48:51], v[178:181], v[186:189], v[48:51]
	v_mfma_f32_16x16x32_bf16 v[40:43], v[170:173], v[194:197], v[40:43]
	v_mfma_f32_16x16x32_bf16 v[32:35], v[178:181], v[194:197], v[32:35]
	v_mfma_f32_16x16x32_bf16 v[24:27], v[170:173], v[202:205], v[24:27]
	v_mfma_f32_16x16x32_bf16 v[16:19], v[178:181], v[202:205], v[16:19]
	v_mfma_f32_16x16x32_bf16 v[8:11], v[170:173], v[210:213], v[8:11]
	v_mfma_f32_16x16x32_bf16 v[0:3], v[178:181], v[210:213], v[0:3]
	s_barrier
	s_setprio 0
	s_add_i32 s81, s81, 2
	s_add_u32 s48, s48, 0x100
	s_addc_u32 s49, s49, 0
	s_add_u32 s79, s79, 0x100
	s_addc_u32 s80, s80, 0
	s_cmp_gt_u32 s81, 13
.LBB0_141:
	ds_read_b128 v[150:153], v147
	ds_read_b128 v[154:157], v147 offset:1024
	ds_read_b128 v[158:161], v147 offset:2048
	ds_read_b128 v[162:165], v147 offset:3072
	ds_read_b128 v[166:169], v148
	ds_read_b128 v[170:173], v148 offset:1024
	ds_read_b128 v[174:177], v148 offset:2048
	ds_read_b128 v[178:181], v148 offset:3072
	s_add_u32 s50, s48, 0xfffc0080
	s_addc_u32 s51, s49, -1
	s_cmp_eq_u32 s81, 12
	s_cselect_b32 s53, s37, s51
	s_cselect_b32 s52, s77, s50
	s_cselect_b32 s51, s39, s80
	s_cselect_b32 s50, s78, s79
	v_lshl_add_u64 v[214:215], s[48:49], 0, v[136:137]
	s_add_i32 m0, s47, 0xc000
	ds_read_b128 v[182:185], v149
	ds_read_b128 v[186:189], v149 offset:1024
	ds_read_b128 v[190:193], v149 offset:2048
	ds_read_b128 v[194:197], v149 offset:3072
	ds_read_b128 v[198:201], v149 offset:4096
	ds_read_b128 v[202:205], v149 offset:5120
	ds_read_b128 v[206:209], v149 offset:6144
	ds_read_b128 v[210:213], v149 offset:7168
	global_load_lds_dwordx4 v[214:215], off
	v_lshl_add_u64 v[214:215], s[48:49], 0, v[138:139]
	s_add_i32 m0, s47, 0xe000
	s_nop 0
	global_load_lds_dwordx4 v[214:215], off
	s_waitcnt vmcnt(8)
	s_waitcnt lgkmcnt(0)
	s_setprio 1
	s_barrier
	v_mfma_f32_16x16x32_bf16 v[124:127], v[150:153], v[182:185], v[124:127]
	v_mfma_f32_16x16x32_bf16 v[116:119], v[158:161], v[182:185], v[116:119]
	v_mfma_f32_16x16x32_bf16 v[108:111], v[150:153], v[190:193], v[108:111]
	v_mfma_f32_16x16x32_bf16 v[100:103], v[158:161], v[190:193], v[100:103]
	v_mfma_f32_16x16x32_bf16 v[92:95], v[150:153], v[198:201], v[92:95]
	v_mfma_f32_16x16x32_bf16 v[84:87], v[158:161], v[198:201], v[84:87]
	v_mfma_f32_16x16x32_bf16 v[76:79], v[150:153], v[206:209], v[76:79]
	v_mfma_f32_16x16x32_bf16 v[68:71], v[158:161], v[206:209], v[68:71]
	v_mfma_f32_16x16x32_bf16 v[124:127], v[154:157], v[186:189], v[124:127]
	v_mfma_f32_16x16x32_bf16 v[116:119], v[162:165], v[186:189], v[116:119]
	v_mfma_f32_16x16x32_bf16 v[108:111], v[154:157], v[194:197], v[108:111]
	v_mfma_f32_16x16x32_bf16 v[100:103], v[162:165], v[194:197], v[100:103]
	v_mfma_f32_16x16x32_bf16 v[92:95], v[154:157], v[202:205], v[92:95]
	v_mfma_f32_16x16x32_bf16 v[84:87], v[162:165], v[202:205], v[84:87]
	v_mfma_f32_16x16x32_bf16 v[76:79], v[154:157], v[210:213], v[76:79]
	v_mfma_f32_16x16x32_bf16 v[68:71], v[162:165], v[210:213], v[68:71]
	v_mfma_f32_16x16x32_bf16 v[120:123], v[166:169], v[182:185], v[120:123]
	v_mfma_f32_16x16x32_bf16 v[112:115], v[174:177], v[182:185], v[112:115]
	v_mfma_f32_16x16x32_bf16 v[104:107], v[166:169], v[190:193], v[104:107]
	v_mfma_f32_16x16x32_bf16 v[96:99], v[174:177], v[190:193], v[96:99]
	v_mfma_f32_16x16x32_bf16 v[88:91], v[166:169], v[198:201], v[88:91]
	v_mfma_f32_16x16x32_bf16 v[80:83], v[174:177], v[198:201], v[80:83]
	v_mfma_f32_16x16x32_bf16 v[72:75], v[166:169], v[206:209], v[72:75]
	v_mfma_f32_16x16x32_bf16 v[64:67], v[174:177], v[206:209], v[64:67]
	v_mfma_f32_16x16x32_bf16 v[120:123], v[170:173], v[186:189], v[120:123]
	v_mfma_f32_16x16x32_bf16 v[112:115], v[178:181], v[186:189], v[112:115]
	v_mfma_f32_16x16x32_bf16 v[104:107], v[170:173], v[194:197], v[104:107]
	v_mfma_f32_16x16x32_bf16 v[96:99], v[178:181], v[194:197], v[96:99]
	v_mfma_f32_16x16x32_bf16 v[88:91], v[170:173], v[202:205], v[88:91]
	v_mfma_f32_16x16x32_bf16 v[80:83], v[178:181], v[202:205], v[80:83]
	v_mfma_f32_16x16x32_bf16 v[72:75], v[170:173], v[210:213], v[72:75]
	v_mfma_f32_16x16x32_bf16 v[64:67], v[178:181], v[210:213], v[64:67]
	s_barrier
	s_setprio 0
	s_add_i32 s82, s73, s56
	v_lshl_add_u64 v[214:215], s[50:51], 0, v[132:133]
	s_mov_b32 m0, s82
	ds_read_b128 v[182:185], v149 offset:16384
	ds_read_b128 v[186:189], v149 offset:17408
	ds_read_b128 v[190:193], v149 offset:18432
	ds_read_b128 v[194:197], v149 offset:19456
	ds_read_b128 v[198:201], v149 offset:20480
	ds_read_b128 v[202:205], v149 offset:21504
	ds_read_b128 v[206:209], v149 offset:22528
	ds_read_b128 v[210:213], v149 offset:23552
	global_load_lds_dwordx4 v[214:215], off
	s_add_i32 m0, s82, 0x2000
	s_add_u32 s88, s50, 0x40000
	v_lshl_add_u64 v[216:217], s[50:51], 0, v[128:129]
	s_addc_u32 s89, s51, 0
	s_add_i32 s82, s74, s56
	global_load_lds_dwordx4 v[216:217], off
	v_lshl_add_u64 v[218:219], s[88:89], 0, v[132:133]
	s_mov_b32 m0, s82
	v_lshl_add_u64 v[220:221], s[52:53], 0, v[130:131]
	global_load_lds_dwordx4 v[218:219], off
	v_lshl_add_u64 v[218:219], s[88:89], 0, v[128:129]
	s_add_i32 m0, s82, 0x2000
	s_nop 0
	global_load_lds_dwordx4 v[218:219], off
	v_lshl_add_u64 v[218:219], s[52:53], 0, v[134:135]
	s_mov_b32 m0, s47
	s_nop 0
	global_load_lds_dwordx4 v[218:219], off
	s_mov_b32 m0, s59
	s_nop 0
	global_load_lds_dwordx4 v[220:221], off
	s_waitcnt vmcnt(8)
	s_waitcnt lgkmcnt(0)
	s_setprio 1
	s_barrier
	v_mfma_f32_16x16x32_bf16 v[60:63], v[150:153], v[182:185], v[60:63]
	v_mfma_f32_16x16x32_bf16 v[52:55], v[158:161], v[182:185], v[52:55]
	v_mfma_f32_16x16x32_bf16 v[44:47], v[150:153], v[190:193], v[44:47]
	v_mfma_f32_16x16x32_bf16 v[36:39], v[158:161], v[190:193], v[36:39]
	v_mfma_f32_16x16x32_bf16 v[28:31], v[150:153], v[198:201], v[28:31]
	v_mfma_f32_16x16x32_bf16 v[20:23], v[158:161], v[198:201], v[20:23]
	v_mfma_f32_16x16x32_bf16 v[12:15], v[150:153], v[206:209], v[12:15]
	v_mfma_f32_16x16x32_bf16 v[4:7], v[158:161], v[206:209], v[4:7]
	v_mfma_f32_16x16x32_bf16 v[60:63], v[154:157], v[186:189], v[60:63]
	v_mfma_f32_16x16x32_bf16 v[52:55], v[162:165], v[186:189], v[52:55]
	v_mfma_f32_16x16x32_bf16 v[44:47], v[154:157], v[194:197], v[44:47]
	v_mfma_f32_16x16x32_bf16 v[36:39], v[162:165], v[194:197], v[36:39]
	v_mfma_f32_16x16x32_bf16 v[28:31], v[154:157], v[202:205], v[28:31]
	v_mfma_f32_16x16x32_bf16 v[20:23], v[162:165], v[202:205], v[20:23]
	v_mfma_f32_16x16x32_bf16 v[12:15], v[154:157], v[210:213], v[12:15]
	v_mfma_f32_16x16x32_bf16 v[4:7], v[162:165], v[210:213], v[4:7]
	v_mfma_f32_16x16x32_bf16 v[56:59], v[166:169], v[182:185], v[56:59]
	v_mfma_f32_16x16x32_bf16 v[48:51], v[174:177], v[182:185], v[48:51]
	v_mfma_f32_16x16x32_bf16 v[40:43], v[166:169], v[190:193], v[40:43]
	v_mfma_f32_16x16x32_bf16 v[32:35], v[174:177], v[190:193], v[32:35]
	v_mfma_f32_16x16x32_bf16 v[24:27], v[166:169], v[198:201], v[24:27]
	v_mfma_f32_16x16x32_bf16 v[16:19], v[174:177], v[198:201], v[16:19]
	v_mfma_f32_16x16x32_bf16 v[8:11], v[166:169], v[206:209], v[8:11]
	v_mfma_f32_16x16x32_bf16 v[0:3], v[174:177], v[206:209], v[0:3]
	v_mfma_f32_16x16x32_bf16 v[56:59], v[170:173], v[186:189], v[56:59]
	v_mfma_f32_16x16x32_bf16 v[48:51], v[178:181], v[186:189], v[48:51]
	v_mfma_f32_16x16x32_bf16 v[40:43], v[170:173], v[194:197], v[40:43]
	v_mfma_f32_16x16x32_bf16 v[32:35], v[178:181], v[194:197], v[32:35]
	v_mfma_f32_16x16x32_bf16 v[24:27], v[170:173], v[202:205], v[24:27]
	v_mfma_f32_16x16x32_bf16 v[16:19], v[178:181], v[202:205], v[16:19]
	v_mfma_f32_16x16x32_bf16 v[8:11], v[170:173], v[210:213], v[8:11]
	v_mfma_f32_16x16x32_bf16 v[0:3], v[178:181], v[210:213], v[0:3]
	s_barrier
	s_setprio 0
	s_add_i32 s82, 0, 0x18000
	s_add_i32 s85, 0, 0x1c000
	v_add_u32_e32 v162, s82, v145
	v_add_u32_e32 v178, s85, v145
	ds_read_b128 v[150:153], v162
	ds_read_b128 v[154:157], v162 offset:1024
	ds_read_b128 v[158:161], v162 offset:2048
	ds_read_b128 v[162:165], v162 offset:3072
	ds_read_b128 v[166:169], v178
	ds_read_b128 v[170:173], v178 offset:1024
	ds_read_b128 v[174:177], v178 offset:2048
	ds_read_b128 v[178:181], v178 offset:3072
	s_add_u32 s52, s52, 0x40000
	s_addc_u32 s53, s53, 0
	s_mov_b32 m0, s66
	v_lshl_add_u64 v[222:223], s[52:53], 0, v[134:135]
	ds_read_b128 v[182:185], v149 offset:32768
	ds_read_b128 v[186:189], v149 offset:33792
	ds_read_b128 v[190:193], v149 offset:34816
	ds_read_b128 v[194:197], v149 offset:35840
	ds_read_b128 v[198:201], v149 offset:36864
	ds_read_b128 v[202:205], v149 offset:37888
	ds_read_b128 v[206:209], v149 offset:38912
	ds_read_b128 v[210:213], v149 offset:39936
	global_load_lds_dwordx4 v[222:223], off
	v_lshl_add_u64 v[222:223], s[52:53], 0, v[130:131]
	s_mov_b32 m0, s67
	s_nop 0
	global_load_lds_dwordx4 v[222:223], off
	s_waitcnt vmcnt(8)
	s_waitcnt lgkmcnt(0)
	s_setprio 1
	s_barrier
	v_mfma_f32_16x16x32_bf16 v[124:127], v[150:153], v[182:185], v[124:127]
	v_mfma_f32_16x16x32_bf16 v[116:119], v[158:161], v[182:185], v[116:119]
	v_mfma_f32_16x16x32_bf16 v[108:111], v[150:153], v[190:193], v[108:111]
	v_mfma_f32_16x16x32_bf16 v[100:103], v[158:161], v[190:193], v[100:103]
	v_mfma_f32_16x16x32_bf16 v[92:95], v[150:153], v[198:201], v[92:95]
	v_mfma_f32_16x16x32_bf16 v[84:87], v[158:161], v[198:201], v[84:87]
	v_mfma_f32_16x16x32_bf16 v[76:79], v[150:153], v[206:209], v[76:79]
	v_mfma_f32_16x16x32_bf16 v[68:71], v[158:161], v[206:209], v[68:71]
	v_mfma_f32_16x16x32_bf16 v[124:127], v[154:157], v[186:189], v[124:127]
	v_mfma_f32_16x16x32_bf16 v[116:119], v[162:165], v[186:189], v[116:119]
	v_mfma_f32_16x16x32_bf16 v[108:111], v[154:157], v[194:197], v[108:111]
	v_mfma_f32_16x16x32_bf16 v[100:103], v[162:165], v[194:197], v[100:103]
	v_mfma_f32_16x16x32_bf16 v[92:95], v[154:157], v[202:205], v[92:95]
	v_mfma_f32_16x16x32_bf16 v[84:87], v[162:165], v[202:205], v[84:87]
	v_mfma_f32_16x16x32_bf16 v[76:79], v[154:157], v[210:213], v[76:79]
	v_mfma_f32_16x16x32_bf16 v[68:71], v[162:165], v[210:213], v[68:71]
	v_mfma_f32_16x16x32_bf16 v[120:123], v[166:169], v[182:185], v[120:123]
	v_mfma_f32_16x16x32_bf16 v[112:115], v[174:177], v[182:185], v[112:115]
	v_mfma_f32_16x16x32_bf16 v[104:107], v[166:169], v[190:193], v[104:107]
	v_mfma_f32_16x16x32_bf16 v[96:99], v[174:177], v[190:193], v[96:99]
	v_mfma_f32_16x16x32_bf16 v[88:91], v[166:169], v[198:201], v[88:91]
	v_mfma_f32_16x16x32_bf16 v[80:83], v[174:177], v[198:201], v[80:83]
	v_mfma_f32_16x16x32_bf16 v[72:75], v[166:169], v[206:209], v[72:75]
	v_mfma_f32_16x16x32_bf16 v[64:67], v[174:177], v[206:209], v[64:67]
	v_mfma_f32_16x16x32_bf16 v[120:123], v[170:173], v[186:189], v[120:123]
	v_mfma_f32_16x16x32_bf16 v[112:115], v[178:181], v[186:189], v[112:115]
	v_mfma_f32_16x16x32_bf16 v[104:107], v[170:173], v[194:197], v[104:107]
	v_mfma_f32_16x16x32_bf16 v[96:99], v[178:181], v[194:197], v[96:99]
	v_mfma_f32_16x16x32_bf16 v[88:91], v[170:173], v[202:205], v[88:91]
	v_mfma_f32_16x16x32_bf16 v[80:83], v[178:181], v[202:205], v[80:83]
	v_mfma_f32_16x16x32_bf16 v[72:75], v[170:173], v[210:213], v[72:75]
	v_mfma_f32_16x16x32_bf16 v[64:67], v[178:181], v[210:213], v[64:67]
	s_barrier
	s_setprio 0
	s_add_i32 s52, s82, s56
	v_lshl_add_u64 v[214:215], v[214:215], 0, s[10:11]
	s_mov_b32 m0, s52
	ds_read_b128 v[182:185], v149 offset:49152
	ds_read_b128 v[186:189], v149 offset:50176
	ds_read_b128 v[190:193], v149 offset:51200
	ds_read_b128 v[194:197], v149 offset:52224
	ds_read_b128 v[198:201], v149 offset:53248
	ds_read_b128 v[202:205], v149 offset:54272
	ds_read_b128 v[206:209], v149 offset:55296
	ds_read_b128 v[210:213], v149 offset:56320
	global_load_lds_dwordx4 v[214:215], off
	s_add_i32 m0, s52, 0x2000
	s_add_u32 s50, s50, 0x40080
	v_lshl_add_u64 v[214:215], v[216:217], 0, s[10:11]
	s_addc_u32 s51, s51, 0
	s_add_i32 s52, s85, s56
	global_load_lds_dwordx4 v[214:215], off
	v_lshl_add_u64 v[214:215], s[50:51], 0, v[132:133]
	s_mov_b32 m0, s52
	s_nop 0
	global_load_lds_dwordx4 v[214:215], off
	v_lshl_add_u64 v[214:215], s[50:51], 0, v[128:129]
	s_add_i32 m0, s52, 0x2000
	s_nop 0
	global_load_lds_dwordx4 v[214:215], off
	v_lshl_add_u64 v[214:215], v[218:219], 0, s[10:11]
	s_mov_b32 m0, s69
	s_nop 0
	global_load_lds_dwordx4 v[214:215], off
	v_lshl_add_u64 v[214:215], v[220:221], 0, s[10:11]
	s_mov_b32 m0, s70
	s_nop 0
	global_load_lds_dwordx4 v[214:215], off
	s_waitcnt vmcnt(8)
	s_waitcnt lgkmcnt(0)
	s_setprio 1
	s_barrier
	v_mfma_f32_16x16x32_bf16 v[60:63], v[150:153], v[182:185], v[60:63]
	v_mfma_f32_16x16x32_bf16 v[52:55], v[158:161], v[182:185], v[52:55]
	v_mfma_f32_16x16x32_bf16 v[44:47], v[150:153], v[190:193], v[44:47]
	v_mfma_f32_16x16x32_bf16 v[36:39], v[158:161], v[190:193], v[36:39]
	v_mfma_f32_16x16x32_bf16 v[28:31], v[150:153], v[198:201], v[28:31]
	v_mfma_f32_16x16x32_bf16 v[20:23], v[158:161], v[198:201], v[20:23]
	v_mfma_f32_16x16x32_bf16 v[12:15], v[150:153], v[206:209], v[12:15]
	v_mfma_f32_16x16x32_bf16 v[4:7], v[158:161], v[206:209], v[4:7]
	v_mfma_f32_16x16x32_bf16 v[60:63], v[154:157], v[186:189], v[60:63]
	v_mfma_f32_16x16x32_bf16 v[52:55], v[162:165], v[186:189], v[52:55]
	v_mfma_f32_16x16x32_bf16 v[44:47], v[154:157], v[194:197], v[44:47]
	v_mfma_f32_16x16x32_bf16 v[36:39], v[162:165], v[194:197], v[36:39]
	v_mfma_f32_16x16x32_bf16 v[28:31], v[154:157], v[202:205], v[28:31]
	v_mfma_f32_16x16x32_bf16 v[20:23], v[162:165], v[202:205], v[20:23]
	v_mfma_f32_16x16x32_bf16 v[12:15], v[154:157], v[210:213], v[12:15]
	v_mfma_f32_16x16x32_bf16 v[4:7], v[162:165], v[210:213], v[4:7]
	v_mfma_f32_16x16x32_bf16 v[56:59], v[166:169], v[182:185], v[56:59]
	v_mfma_f32_16x16x32_bf16 v[48:51], v[174:177], v[182:185], v[48:51]
	v_mfma_f32_16x16x32_bf16 v[40:43], v[166:169], v[190:193], v[40:43]
	v_mfma_f32_16x16x32_bf16 v[32:35], v[174:177], v[190:193], v[32:35]
	v_mfma_f32_16x16x32_bf16 v[24:27], v[166:169], v[198:201], v[24:27]
	v_mfma_f32_16x16x32_bf16 v[16:19], v[174:177], v[198:201], v[16:19]
	v_mfma_f32_16x16x32_bf16 v[8:11], v[166:169], v[206:209], v[8:11]
	v_mfma_f32_16x16x32_bf16 v[0:3], v[174:177], v[206:209], v[0:3]
	v_mfma_f32_16x16x32_bf16 v[56:59], v[170:173], v[186:189], v[56:59]
	v_mfma_f32_16x16x32_bf16 v[48:51], v[178:181], v[186:189], v[48:51]
	v_mfma_f32_16x16x32_bf16 v[40:43], v[170:173], v[194:197], v[40:43]
	v_mfma_f32_16x16x32_bf16 v[32:35], v[178:181], v[194:197], v[32:35]
	v_mfma_f32_16x16x32_bf16 v[24:27], v[170:173], v[202:205], v[24:27]
	v_mfma_f32_16x16x32_bf16 v[16:19], v[178:181], v[202:205], v[16:19]
	v_mfma_f32_16x16x32_bf16 v[8:11], v[170:173], v[210:213], v[8:11]
	v_mfma_f32_16x16x32_bf16 v[0:3], v[178:181], v[210:213], v[0:3]
	s_barrier
	s_setprio 0
	s_add_i32 s81, s81, 2
	s_add_u32 s48, s48, 0x100
	s_addc_u32 s49, s49, 0
	s_add_u32 s79, s79, 0x100
	s_addc_u32 s80, s80, 0
	s_cmp_gt_u32 s81, 13
	s_cbranch_scc0 .LBB0_141
	s_and_b64 vcc, exec, s[26:27]
	s_cbranch_vccz .LBB0_144
	s_barrier

.LBB0_220:
	s_add_u32 s95, s52, 0x100
	s_addc_u32 s96, s53, 0
	s_mov_b32 s97, -2
	ds_read_b128 v[88:91], v233
	ds_read_b128 v[92:95], v233 offset:1024
	ds_read_b128 v[112:115], v233 offset:2048
	ds_read_b128 v[116:119], v233 offset:3072
	ds_read_b128 v[132:135], v234
	ds_read_b128 v[136:139], v234 offset:1024
	ds_read_b128 v[152:155], v234 offset:2048
	ds_read_b128 v[156:159], v234 offset:3072
	s_add_u32 s52, s50, 0x100
	s_addc_u32 s53, s51, 0
	s_cmp_eq_u32 s97, 40
	s_cselect_b32 s57, s9, s53
	s_cselect_b32 s56, s8, s52
	s_cselect_b32 s55, s41, s96
	s_cselect_b32 s54, s40, s95
	v_lshl_add_u64 v[216:217], s[50:51], 0, v[196:197]
	s_add_i32 m0, s67, 0xc000
	ds_read_b128 v[160:163], v235
	ds_read_b128 v[164:167], v235 offset:1024
	ds_read_b128 v[168:171], v235 offset:2048
	ds_read_b128 v[172:175], v235 offset:3072
	ds_read_b128 v[176:179], v235 offset:4096
	ds_read_b128 v[180:183], v235 offset:5120
	ds_read_b128 v[208:211], v235 offset:6144
	ds_read_b128 v[212:215], v235 offset:7168
	global_load_lds_dwordx4 v[216:217], off
	v_lshl_add_u64 v[216:217], s[50:51], 0, v[198:199]
	s_add_i32 m0, s67, 0xe000
	s_nop 0
	global_load_lds_dwordx4 v[216:217], off
	s_waitcnt vmcnt(8)
	s_waitcnt lgkmcnt(0)
	s_setprio 1
	s_barrier
	v_mfma_f32_16x16x32_bf16 v[148:151], v[88:91], v[160:163], 0
	v_mfma_f32_16x16x32_bf16 v[144:147], v[112:115], v[160:163], 0
	v_mfma_f32_16x16x32_bf16 v[124:127], v[88:91], v[168:171], 0
	v_mfma_f32_16x16x32_bf16 v[120:123], v[112:115], v[168:171], 0
	v_mfma_f32_16x16x32_bf16 v[100:103], v[88:91], v[176:179], 0
	v_mfma_f32_16x16x32_bf16 v[96:99], v[112:115], v[176:179], 0
	v_mfma_f32_16x16x32_bf16 v[76:79], v[88:91], v[208:211], 0
	v_mfma_f32_16x16x32_bf16 v[72:75], v[112:115], v[208:211], 0
	v_mfma_f32_16x16x32_bf16 v[148:151], v[92:95], v[164:167], v[148:151]
	v_mfma_f32_16x16x32_bf16 v[144:147], v[116:119], v[164:167], v[144:147]
	v_mfma_f32_16x16x32_bf16 v[124:127], v[92:95], v[172:175], v[124:127]
	v_mfma_f32_16x16x32_bf16 v[120:123], v[116:119], v[172:175], v[120:123]
	v_mfma_f32_16x16x32_bf16 v[100:103], v[92:95], v[180:183], v[100:103]
	v_mfma_f32_16x16x32_bf16 v[96:99], v[116:119], v[180:183], v[96:99]
	v_mfma_f32_16x16x32_bf16 v[76:79], v[92:95], v[212:215], v[76:79]
	v_mfma_f32_16x16x32_bf16 v[72:75], v[116:119], v[212:215], v[72:75]
	v_mfma_f32_16x16x32_bf16 v[140:143], v[132:135], v[160:163], 0
	v_mfma_f32_16x16x32_bf16 v[128:131], v[152:155], v[160:163], 0
	v_mfma_f32_16x16x32_bf16 v[108:111], v[132:135], v[168:171], 0
	v_mfma_f32_16x16x32_bf16 v[104:107], v[152:155], v[168:171], 0
	v_mfma_f32_16x16x32_bf16 v[84:87], v[132:135], v[176:179], 0
	v_mfma_f32_16x16x32_bf16 v[80:83], v[152:155], v[176:179], 0
	v_mfma_f32_16x16x32_bf16 v[68:71], v[132:135], v[208:211], 0
	v_mfma_f32_16x16x32_bf16 v[64:67], v[152:155], v[208:211], 0
	v_mfma_f32_16x16x32_bf16 v[140:143], v[136:139], v[164:167], v[140:143]
	v_mfma_f32_16x16x32_bf16 v[128:131], v[156:159], v[164:167], v[128:131]
	v_mfma_f32_16x16x32_bf16 v[108:111], v[136:139], v[172:175], v[108:111]
	v_mfma_f32_16x16x32_bf16 v[104:107], v[156:159], v[172:175], v[104:107]
	v_mfma_f32_16x16x32_bf16 v[84:87], v[136:139], v[180:183], v[84:87]
	v_mfma_f32_16x16x32_bf16 v[80:83], v[156:159], v[180:183], v[80:83]
	v_mfma_f32_16x16x32_bf16 v[68:71], v[136:139], v[212:215], v[68:71]
	v_mfma_f32_16x16x32_bf16 v[64:67], v[156:159], v[212:215], v[64:67]
	s_barrier
	s_setprio 0
	s_add_i32 s50, s82, s66
	v_lshl_add_u64 v[216:217], s[54:55], 0, v[186:187]
	s_mov_b32 m0, s50
	ds_read_b128 v[160:163], v235 offset:16384
	ds_read_b128 v[164:167], v235 offset:17408
	ds_read_b128 v[168:171], v235 offset:18432
	ds_read_b128 v[172:175], v235 offset:19456
	ds_read_b128 v[176:179], v235 offset:20480
	ds_read_b128 v[180:183], v235 offset:21504
	ds_read_b128 v[208:211], v235 offset:22528
	ds_read_b128 v[212:215], v235 offset:23552
	global_load_lds_dwordx4 v[216:217], off
	s_add_i32 m0, s50, 0x2000
	s_add_u32 s50, s54, 0xb0000
	v_lshl_add_u64 v[218:219], s[54:55], 0, v[190:191]
	s_addc_u32 s51, s55, 0
	s_add_i32 vcc_lo, s85, s66
	global_load_lds_dwordx4 v[218:219], off
	v_lshl_add_u64 v[220:221], s[50:51], 0, v[186:187]
	s_mov_b32 m0, vcc_lo
	v_lshl_add_u64 v[222:223], s[56:57], 0, v[188:189]
	global_load_lds_dwordx4 v[220:221], off
	v_lshl_add_u64 v[220:221], s[50:51], 0, v[190:191]
	s_add_i32 m0, vcc_lo, 0x2000
	s_nop 0
	global_load_lds_dwordx4 v[220:221], off
	v_lshl_add_u64 v[220:221], s[56:57], 0, v[184:185]
	s_mov_b32 m0, s67
	s_nop 0
	global_load_lds_dwordx4 v[220:221], off
	s_mov_b32 m0, s68
	s_nop 0
	global_load_lds_dwordx4 v[222:223], off
	s_waitcnt vmcnt(8)
	s_waitcnt lgkmcnt(0)
	s_setprio 1
	s_barrier
	v_mfma_f32_16x16x32_bf16 v[60:63], v[88:91], v[160:163], 0
	v_mfma_f32_16x16x32_bf16 v[56:59], v[112:115], v[160:163], 0
	v_mfma_f32_16x16x32_bf16 v[44:47], v[88:91], v[168:171], 0
	v_mfma_f32_16x16x32_bf16 v[40:43], v[112:115], v[168:171], 0
	v_mfma_f32_16x16x32_bf16 v[28:31], v[88:91], v[176:179], 0
	v_mfma_f32_16x16x32_bf16 v[24:27], v[112:115], v[176:179], 0
	v_mfma_f32_16x16x32_bf16 v[12:15], v[88:91], v[208:211], 0
	v_mfma_f32_16x16x32_bf16 v[8:11], v[112:115], v[208:211], 0
	v_mfma_f32_16x16x32_bf16 v[60:63], v[92:95], v[164:167], v[60:63]
	v_mfma_f32_16x16x32_bf16 v[56:59], v[116:119], v[164:167], v[56:59]
	v_mfma_f32_16x16x32_bf16 v[44:47], v[92:95], v[172:175], v[44:47]
	v_mfma_f32_16x16x32_bf16 v[40:43], v[116:119], v[172:175], v[40:43]
	v_mfma_f32_16x16x32_bf16 v[28:31], v[92:95], v[180:183], v[28:31]
	v_mfma_f32_16x16x32_bf16 v[24:27], v[116:119], v[180:183], v[24:27]
	v_mfma_f32_16x16x32_bf16 v[12:15], v[92:95], v[212:215], v[12:15]
	v_mfma_f32_16x16x32_bf16 v[8:11], v[116:119], v[212:215], v[8:11]
	v_mfma_f32_16x16x32_bf16 v[52:55], v[132:135], v[160:163], 0
	v_mfma_f32_16x16x32_bf16 v[48:51], v[152:155], v[160:163], 0
	v_mfma_f32_16x16x32_bf16 v[36:39], v[132:135], v[168:171], 0
	v_mfma_f32_16x16x32_bf16 v[32:35], v[152:155], v[168:171], 0
	v_mfma_f32_16x16x32_bf16 v[20:23], v[132:135], v[176:179], 0
	v_mfma_f32_16x16x32_bf16 v[16:19], v[152:155], v[176:179], 0
	v_mfma_f32_16x16x32_bf16 v[4:7], v[132:135], v[208:211], 0
	v_mfma_f32_16x16x32_bf16 v[0:3], v[152:155], v[208:211], 0
	v_mfma_f32_16x16x32_bf16 v[52:55], v[136:139], v[164:167], v[52:55]
	v_mfma_f32_16x16x32_bf16 v[48:51], v[156:159], v[164:167], v[48:51]
	v_mfma_f32_16x16x32_bf16 v[36:39], v[136:139], v[172:175], v[36:39]
	v_mfma_f32_16x16x32_bf16 v[32:35], v[156:159], v[172:175], v[32:35]
	v_mfma_f32_16x16x32_bf16 v[20:23], v[136:139], v[180:183], v[20:23]
	v_mfma_f32_16x16x32_bf16 v[16:19], v[156:159], v[180:183], v[16:19]
	v_mfma_f32_16x16x32_bf16 v[4:7], v[136:139], v[212:215], v[4:7]
	v_mfma_f32_16x16x32_bf16 v[0:3], v[156:159], v[212:215], v[0:3]
	s_barrier
	s_setprio 0
	s_add_i32 vcc_lo, 0, 0x18000
	s_add_i32 vcc_hi, 0, 0x1c000
	v_add_u32_e32 v116, vcc_lo, v230
	v_add_u32_e32 v156, vcc_hi, v230
	ds_read_b128 v[88:91], v116
	ds_read_b128 v[92:95], v116 offset:1024
	ds_read_b128 v[112:115], v116 offset:2048
	ds_read_b128 v[116:119], v116 offset:3072
	ds_read_b128 v[132:135], v156
	ds_read_b128 v[136:139], v156 offset:1024
	ds_read_b128 v[152:155], v156 offset:2048
	ds_read_b128 v[156:159], v156 offset:3072
	s_add_u32 s50, s56, 0xb0000
	s_addc_u32 s51, s57, 0
	s_mov_b32 m0, s69
	v_lshl_add_u64 v[224:225], s[50:51], 0, v[184:185]
	ds_read_b128 v[160:163], v235 offset:32768
	ds_read_b128 v[164:167], v235 offset:33792
	ds_read_b128 v[168:171], v235 offset:34816
	ds_read_b128 v[172:175], v235 offset:35840
	ds_read_b128 v[176:179], v235 offset:36864
	ds_read_b128 v[180:183], v235 offset:37888
	ds_read_b128 v[208:211], v235 offset:38912
	ds_read_b128 v[212:215], v235 offset:39936
	global_load_lds_dwordx4 v[224:225], off
	v_lshl_add_u64 v[224:225], s[50:51], 0, v[188:189]
	s_mov_b32 m0, s70
	s_nop 0
	global_load_lds_dwordx4 v[224:225], off
	s_waitcnt vmcnt(8)
	s_waitcnt lgkmcnt(0)
	s_setprio 1
	s_barrier
	v_mfma_f32_16x16x32_bf16 v[148:151], v[88:91], v[160:163], v[148:151]
	v_mfma_f32_16x16x32_bf16 v[144:147], v[112:115], v[160:163], v[144:147]
	v_mfma_f32_16x16x32_bf16 v[124:127], v[88:91], v[168:171], v[124:127]
	v_mfma_f32_16x16x32_bf16 v[120:123], v[112:115], v[168:171], v[120:123]
	v_mfma_f32_16x16x32_bf16 v[100:103], v[88:91], v[176:179], v[100:103]
	v_mfma_f32_16x16x32_bf16 v[96:99], v[112:115], v[176:179], v[96:99]
	v_mfma_f32_16x16x32_bf16 v[76:79], v[88:91], v[208:211], v[76:79]
	v_mfma_f32_16x16x32_bf16 v[72:75], v[112:115], v[208:211], v[72:75]
	v_mfma_f32_16x16x32_bf16 v[148:151], v[92:95], v[164:167], v[148:151]
	v_mfma_f32_16x16x32_bf16 v[144:147], v[116:119], v[164:167], v[144:147]
	v_mfma_f32_16x16x32_bf16 v[124:127], v[92:95], v[172:175], v[124:127]
	v_mfma_f32_16x16x32_bf16 v[120:123], v[116:119], v[172:175], v[120:123]
	v_mfma_f32_16x16x32_bf16 v[100:103], v[92:95], v[180:183], v[100:103]
	v_mfma_f32_16x16x32_bf16 v[96:99], v[116:119], v[180:183], v[96:99]
	v_mfma_f32_16x16x32_bf16 v[76:79], v[92:95], v[212:215], v[76:79]
	v_mfma_f32_16x16x32_bf16 v[72:75], v[116:119], v[212:215], v[72:75]
	v_mfma_f32_16x16x32_bf16 v[140:143], v[132:135], v[160:163], v[140:143]
	v_mfma_f32_16x16x32_bf16 v[128:131], v[152:155], v[160:163], v[128:131]
	v_mfma_f32_16x16x32_bf16 v[108:111], v[132:135], v[168:171], v[108:111]
	v_mfma_f32_16x16x32_bf16 v[104:107], v[152:155], v[168:171], v[104:107]
	v_mfma_f32_16x16x32_bf16 v[84:87], v[132:135], v[176:179], v[84:87]
	v_mfma_f32_16x16x32_bf16 v[80:83], v[152:155], v[176:179], v[80:83]
	v_mfma_f32_16x16x32_bf16 v[68:71], v[132:135], v[208:211], v[68:71]
	v_mfma_f32_16x16x32_bf16 v[64:67], v[152:155], v[208:211], v[64:67]
	v_mfma_f32_16x16x32_bf16 v[140:143], v[136:139], v[164:167], v[140:143]
	v_mfma_f32_16x16x32_bf16 v[128:131], v[156:159], v[164:167], v[128:131]
	v_mfma_f32_16x16x32_bf16 v[108:111], v[136:139], v[172:175], v[108:111]
	v_mfma_f32_16x16x32_bf16 v[104:107], v[156:159], v[172:175], v[104:107]
	v_mfma_f32_16x16x32_bf16 v[84:87], v[136:139], v[180:183], v[84:87]
	v_mfma_f32_16x16x32_bf16 v[80:83], v[156:159], v[180:183], v[80:83]
	v_mfma_f32_16x16x32_bf16 v[68:71], v[136:139], v[212:215], v[68:71]
	v_mfma_f32_16x16x32_bf16 v[64:67], v[156:159], v[212:215], v[64:67]
	s_barrier
	s_setprio 0
	s_add_i32 s50, vcc_lo, s66
	v_lshl_add_u64 v[216:217], v[216:217], 0, s[46:47]
	s_mov_b32 m0, s50
	ds_read_b128 v[160:163], v235 offset:49152
	ds_read_b128 v[164:167], v235 offset:50176
	ds_read_b128 v[168:171], v235 offset:51200
	ds_read_b128 v[172:175], v235 offset:52224
	ds_read_b128 v[176:179], v235 offset:53248
	ds_read_b128 v[180:183], v235 offset:54272
	ds_read_b128 v[208:211], v235 offset:55296
	ds_read_b128 v[212:215], v235 offset:56320
	global_load_lds_dwordx4 v[216:217], off
	s_add_i32 m0, s50, 0x2000
	s_add_u32 s50, s54, 0xb0080
	v_lshl_add_u64 v[216:217], v[218:219], 0, s[46:47]
	s_addc_u32 s51, s55, 0
	s_add_i32 s54, vcc_hi, s66
	global_load_lds_dwordx4 v[216:217], off
	v_lshl_add_u64 v[216:217], s[50:51], 0, v[186:187]
	s_mov_b32 m0, s54
	s_nop 0
	global_load_lds_dwordx4 v[216:217], off
	v_lshl_add_u64 v[216:217], s[50:51], 0, v[190:191]
	s_add_i32 m0, s54, 0x2000
	s_nop 0
	global_load_lds_dwordx4 v[216:217], off
	v_lshl_add_u64 v[216:217], v[220:221], 0, s[46:47]
	s_mov_b32 m0, s74
	s_nop 0
	global_load_lds_dwordx4 v[216:217], off
	v_lshl_add_u64 v[216:217], v[222:223], 0, s[46:47]
	s_mov_b32 m0, s75
	s_nop 0
	global_load_lds_dwordx4 v[216:217], off
	s_waitcnt vmcnt(8)
	s_waitcnt lgkmcnt(0)
	s_setprio 1
	s_barrier
	v_mfma_f32_16x16x32_bf16 v[60:63], v[88:91], v[160:163], v[60:63]
	v_mfma_f32_16x16x32_bf16 v[56:59], v[112:115], v[160:163], v[56:59]
	v_mfma_f32_16x16x32_bf16 v[44:47], v[88:91], v[168:171], v[44:47]
	v_mfma_f32_16x16x32_bf16 v[40:43], v[112:115], v[168:171], v[40:43]
	v_mfma_f32_16x16x32_bf16 v[28:31], v[88:91], v[176:179], v[28:31]
	v_mfma_f32_16x16x32_bf16 v[24:27], v[112:115], v[176:179], v[24:27]
	v_mfma_f32_16x16x32_bf16 v[12:15], v[88:91], v[208:211], v[12:15]
	v_mfma_f32_16x16x32_bf16 v[8:11], v[112:115], v[208:211], v[8:11]
	v_mfma_f32_16x16x32_bf16 v[60:63], v[92:95], v[164:167], v[60:63]
	v_mfma_f32_16x16x32_bf16 v[56:59], v[116:119], v[164:167], v[56:59]
	v_mfma_f32_16x16x32_bf16 v[44:47], v[92:95], v[172:175], v[44:47]
	v_mfma_f32_16x16x32_bf16 v[40:43], v[116:119], v[172:175], v[40:43]
	v_mfma_f32_16x16x32_bf16 v[28:31], v[92:95], v[180:183], v[28:31]
	v_mfma_f32_16x16x32_bf16 v[24:27], v[116:119], v[180:183], v[24:27]
	v_mfma_f32_16x16x32_bf16 v[12:15], v[92:95], v[212:215], v[12:15]
	v_mfma_f32_16x16x32_bf16 v[8:11], v[116:119], v[212:215], v[8:11]
	v_mfma_f32_16x16x32_bf16 v[52:55], v[132:135], v[160:163], v[52:55]
	v_mfma_f32_16x16x32_bf16 v[48:51], v[152:155], v[160:163], v[48:51]
	v_mfma_f32_16x16x32_bf16 v[36:39], v[132:135], v[168:171], v[36:39]
	v_mfma_f32_16x16x32_bf16 v[32:35], v[152:155], v[168:171], v[32:35]
	v_mfma_f32_16x16x32_bf16 v[20:23], v[132:135], v[176:179], v[20:23]
	v_mfma_f32_16x16x32_bf16 v[16:19], v[152:155], v[176:179], v[16:19]
	v_mfma_f32_16x16x32_bf16 v[4:7], v[132:135], v[208:211], v[4:7]
	v_mfma_f32_16x16x32_bf16 v[0:3], v[152:155], v[208:211], v[0:3]
	v_mfma_f32_16x16x32_bf16 v[52:55], v[136:139], v[164:167], v[52:55]
	v_mfma_f32_16x16x32_bf16 v[48:51], v[156:159], v[164:167], v[48:51]
	v_mfma_f32_16x16x32_bf16 v[36:39], v[136:139], v[172:175], v[36:39]
	v_mfma_f32_16x16x32_bf16 v[32:35], v[156:159], v[172:175], v[32:35]
	v_mfma_f32_16x16x32_bf16 v[20:23], v[136:139], v[180:183], v[20:23]
	v_mfma_f32_16x16x32_bf16 v[16:19], v[156:159], v[180:183], v[16:19]
	v_mfma_f32_16x16x32_bf16 v[4:7], v[136:139], v[212:215], v[4:7]
	v_mfma_f32_16x16x32_bf16 v[0:3], v[156:159], v[212:215], v[0:3]
	s_barrier
	s_setprio 0
	s_add_i32 s97, s97, 2
	s_add_u32 s95, s95, 0x100
	s_addc_u32 s96, s96, 0
	s_cmp_gt_u32 s97, 41
	s_mov_b64 s[50:51], s[52:53]
.LBB0_221:
	ds_read_b128 v[88:91], v233
	ds_read_b128 v[92:95], v233 offset:1024
	ds_read_b128 v[112:115], v233 offset:2048
	ds_read_b128 v[116:119], v233 offset:3072
	ds_read_b128 v[132:135], v234
	ds_read_b128 v[136:139], v234 offset:1024
	ds_read_b128 v[152:155], v234 offset:2048
	ds_read_b128 v[156:159], v234 offset:3072
	s_add_u32 s52, s50, 0x100
	s_addc_u32 s53, s51, 0
	s_cmp_eq_u32 s97, 40
	s_cselect_b32 s57, s9, s53
	s_cselect_b32 s56, s8, s52
	s_cselect_b32 s55, s41, s96
	s_cselect_b32 s54, s40, s95
	v_lshl_add_u64 v[216:217], s[50:51], 0, v[196:197]
	s_add_i32 m0, s67, 0xc000
	ds_read_b128 v[160:163], v235
	ds_read_b128 v[164:167], v235 offset:1024
	ds_read_b128 v[168:171], v235 offset:2048
	ds_read_b128 v[172:175], v235 offset:3072
	ds_read_b128 v[176:179], v235 offset:4096
	ds_read_b128 v[180:183], v235 offset:5120
	ds_read_b128 v[208:211], v235 offset:6144
	ds_read_b128 v[212:215], v235 offset:7168
	global_load_lds_dwordx4 v[216:217], off
	v_lshl_add_u64 v[216:217], s[50:51], 0, v[198:199]
	s_add_i32 m0, s67, 0xe000
	s_nop 0
	global_load_lds_dwordx4 v[216:217], off
	s_waitcnt vmcnt(8)
	s_waitcnt lgkmcnt(0)
	s_setprio 1
	s_barrier
	v_mfma_f32_16x16x32_bf16 v[148:151], v[88:91], v[160:163], v[148:151]
	v_mfma_f32_16x16x32_bf16 v[144:147], v[112:115], v[160:163], v[144:147]
	v_mfma_f32_16x16x32_bf16 v[124:127], v[88:91], v[168:171], v[124:127]
	v_mfma_f32_16x16x32_bf16 v[120:123], v[112:115], v[168:171], v[120:123]
	v_mfma_f32_16x16x32_bf16 v[100:103], v[88:91], v[176:179], v[100:103]
	v_mfma_f32_16x16x32_bf16 v[96:99], v[112:115], v[176:179], v[96:99]
	v_mfma_f32_16x16x32_bf16 v[76:79], v[88:91], v[208:211], v[76:79]
	v_mfma_f32_16x16x32_bf16 v[72:75], v[112:115], v[208:211], v[72:75]
	v_mfma_f32_16x16x32_bf16 v[148:151], v[92:95], v[164:167], v[148:151]
	v_mfma_f32_16x16x32_bf16 v[144:147], v[116:119], v[164:167], v[144:147]
	v_mfma_f32_16x16x32_bf16 v[124:127], v[92:95], v[172:175], v[124:127]
	v_mfma_f32_16x16x32_bf16 v[120:123], v[116:119], v[172:175], v[120:123]
	v_mfma_f32_16x16x32_bf16 v[100:103], v[92:95], v[180:183], v[100:103]
	v_mfma_f32_16x16x32_bf16 v[96:99], v[116:119], v[180:183], v[96:99]
	v_mfma_f32_16x16x32_bf16 v[76:79], v[92:95], v[212:215], v[76:79]
	v_mfma_f32_16x16x32_bf16 v[72:75], v[116:119], v[212:215], v[72:75]
	v_mfma_f32_16x16x32_bf16 v[140:143], v[132:135], v[160:163], v[140:143]
	v_mfma_f32_16x16x32_bf16 v[128:131], v[152:155], v[160:163], v[128:131]
	v_mfma_f32_16x16x32_bf16 v[108:111], v[132:135], v[168:171], v[108:111]
	v_mfma_f32_16x16x32_bf16 v[104:107], v[152:155], v[168:171], v[104:107]
	v_mfma_f32_16x16x32_bf16 v[84:87], v[132:135], v[176:179], v[84:87]
	v_mfma_f32_16x16x32_bf16 v[80:83], v[152:155], v[176:179], v[80:83]
	v_mfma_f32_16x16x32_bf16 v[68:71], v[132:135], v[208:211], v[68:71]
	v_mfma_f32_16x16x32_bf16 v[64:67], v[152:155], v[208:211], v[64:67]
	v_mfma_f32_16x16x32_bf16 v[140:143], v[136:139], v[164:167], v[140:143]
	v_mfma_f32_16x16x32_bf16 v[128:131], v[156:159], v[164:167], v[128:131]
	v_mfma_f32_16x16x32_bf16 v[108:111], v[136:139], v[172:175], v[108:111]
	v_mfma_f32_16x16x32_bf16 v[104:107], v[156:159], v[172:175], v[104:107]
	v_mfma_f32_16x16x32_bf16 v[84:87], v[136:139], v[180:183], v[84:87]
	v_mfma_f32_16x16x32_bf16 v[80:83], v[156:159], v[180:183], v[80:83]
	v_mfma_f32_16x16x32_bf16 v[68:71], v[136:139], v[212:215], v[68:71]
	v_mfma_f32_16x16x32_bf16 v[64:67], v[156:159], v[212:215], v[64:67]
	s_barrier
	s_setprio 0
	s_add_i32 s50, s82, s66
	v_lshl_add_u64 v[216:217], s[54:55], 0, v[186:187]
	s_mov_b32 m0, s50
	ds_read_b128 v[160:163], v235 offset:16384
	ds_read_b128 v[164:167], v235 offset:17408
	ds_read_b128 v[168:171], v235 offset:18432
	ds_read_b128 v[172:175], v235 offset:19456
	ds_read_b128 v[176:179], v235 offset:20480
	ds_read_b128 v[180:183], v235 offset:21504
	ds_read_b128 v[208:211], v235 offset:22528
	ds_read_b128 v[212:215], v235 offset:23552
	global_load_lds_dwordx4 v[216:217], off
	s_add_i32 m0, s50, 0x2000
	s_add_u32 s50, s54, 0xb0000
	v_lshl_add_u64 v[218:219], s[54:55], 0, v[190:191]
	s_addc_u32 s51, s55, 0
	s_add_i32 vcc_lo, s85, s66
	global_load_lds_dwordx4 v[218:219], off
	v_lshl_add_u64 v[220:221], s[50:51], 0, v[186:187]
	s_mov_b32 m0, vcc_lo
	v_lshl_add_u64 v[222:223], s[56:57], 0, v[188:189]
	global_load_lds_dwordx4 v[220:221], off
	v_lshl_add_u64 v[220:221], s[50:51], 0, v[190:191]
	s_add_i32 m0, vcc_lo, 0x2000
	s_nop 0
	global_load_lds_dwordx4 v[220:221], off
	v_lshl_add_u64 v[220:221], s[56:57], 0, v[184:185]
	s_mov_b32 m0, s67
	s_nop 0
	global_load_lds_dwordx4 v[220:221], off
	s_mov_b32 m0, s68
	s_nop 0
	global_load_lds_dwordx4 v[222:223], off
	s_waitcnt vmcnt(8)
	s_waitcnt lgkmcnt(0)
	s_setprio 1
	s_barrier
	v_mfma_f32_16x16x32_bf16 v[60:63], v[88:91], v[160:163], v[60:63]
	v_mfma_f32_16x16x32_bf16 v[56:59], v[112:115], v[160:163], v[56:59]
	v_mfma_f32_16x16x32_bf16 v[44:47], v[88:91], v[168:171], v[44:47]
	v_mfma_f32_16x16x32_bf16 v[40:43], v[112:115], v[168:171], v[40:43]
	v_mfma_f32_16x16x32_bf16 v[28:31], v[88:91], v[176:179], v[28:31]
	v_mfma_f32_16x16x32_bf16 v[24:27], v[112:115], v[176:179], v[24:27]
	v_mfma_f32_16x16x32_bf16 v[12:15], v[88:91], v[208:211], v[12:15]
	v_mfma_f32_16x16x32_bf16 v[8:11], v[112:115], v[208:211], v[8:11]
	v_mfma_f32_16x16x32_bf16 v[60:63], v[92:95], v[164:167], v[60:63]
	v_mfma_f32_16x16x32_bf16 v[56:59], v[116:119], v[164:167], v[56:59]
	v_mfma_f32_16x16x32_bf16 v[44:47], v[92:95], v[172:175], v[44:47]
	v_mfma_f32_16x16x32_bf16 v[40:43], v[116:119], v[172:175], v[40:43]
	v_mfma_f32_16x16x32_bf16 v[28:31], v[92:95], v[180:183], v[28:31]
	v_mfma_f32_16x16x32_bf16 v[24:27], v[116:119], v[180:183], v[24:27]
	v_mfma_f32_16x16x32_bf16 v[12:15], v[92:95], v[212:215], v[12:15]
	v_mfma_f32_16x16x32_bf16 v[8:11], v[116:119], v[212:215], v[8:11]
	v_mfma_f32_16x16x32_bf16 v[52:55], v[132:135], v[160:163], v[52:55]
	v_mfma_f32_16x16x32_bf16 v[48:51], v[152:155], v[160:163], v[48:51]
	v_mfma_f32_16x16x32_bf16 v[36:39], v[132:135], v[168:171], v[36:39]
	v_mfma_f32_16x16x32_bf16 v[32:35], v[152:155], v[168:171], v[32:35]
	v_mfma_f32_16x16x32_bf16 v[20:23], v[132:135], v[176:179], v[20:23]
	v_mfma_f32_16x16x32_bf16 v[16:19], v[152:155], v[176:179], v[16:19]
	v_mfma_f32_16x16x32_bf16 v[4:7], v[132:135], v[208:211], v[4:7]
	v_mfma_f32_16x16x32_bf16 v[0:3], v[152:155], v[208:211], v[0:3]
	v_mfma_f32_16x16x32_bf16 v[52:55], v[136:139], v[164:167], v[52:55]
	v_mfma_f32_16x16x32_bf16 v[48:51], v[156:159], v[164:167], v[48:51]
	v_mfma_f32_16x16x32_bf16 v[36:39], v[136:139], v[172:175], v[36:39]
	v_mfma_f32_16x16x32_bf16 v[32:35], v[156:159], v[172:175], v[32:35]
	v_mfma_f32_16x16x32_bf16 v[20:23], v[136:139], v[180:183], v[20:23]
	v_mfma_f32_16x16x32_bf16 v[16:19], v[156:159], v[180:183], v[16:19]
	v_mfma_f32_16x16x32_bf16 v[4:7], v[136:139], v[212:215], v[4:7]
	v_mfma_f32_16x16x32_bf16 v[0:3], v[156:159], v[212:215], v[0:3]
	s_barrier
	s_setprio 0
	s_add_i32 vcc_lo, 0, 0x18000
	s_add_i32 vcc_hi, 0, 0x1c000
	v_add_u32_e32 v116, vcc_lo, v230
	v_add_u32_e32 v156, vcc_hi, v230
	ds_read_b128 v[88:91], v116
	ds_read_b128 v[92:95], v116 offset:1024
	ds_read_b128 v[112:115], v116 offset:2048
	ds_read_b128 v[116:119], v116 offset:3072
	ds_read_b128 v[132:135], v156
	ds_read_b128 v[136:139], v156 offset:1024
	ds_read_b128 v[152:155], v156 offset:2048
	ds_read_b128 v[156:159], v156 offset:3072
	s_add_u32 s50, s56, 0xb0000
	s_addc_u32 s51, s57, 0
	s_mov_b32 m0, s69
	v_lshl_add_u64 v[224:225], s[50:51], 0, v[184:185]
	ds_read_b128 v[160:163], v235 offset:32768
	ds_read_b128 v[164:167], v235 offset:33792
	ds_read_b128 v[168:171], v235 offset:34816
	ds_read_b128 v[172:175], v235 offset:35840
	ds_read_b128 v[176:179], v235 offset:36864
	ds_read_b128 v[180:183], v235 offset:37888
	ds_read_b128 v[208:211], v235 offset:38912
	ds_read_b128 v[212:215], v235 offset:39936
	global_load_lds_dwordx4 v[224:225], off
	v_lshl_add_u64 v[224:225], s[50:51], 0, v[188:189]
	s_mov_b32 m0, s70
	s_nop 0
	global_load_lds_dwordx4 v[224:225], off
	s_waitcnt vmcnt(8)
	s_waitcnt lgkmcnt(0)
	s_setprio 1
	s_barrier
	v_mfma_f32_16x16x32_bf16 v[148:151], v[88:91], v[160:163], v[148:151]
	v_mfma_f32_16x16x32_bf16 v[144:147], v[112:115], v[160:163], v[144:147]
	v_mfma_f32_16x16x32_bf16 v[124:127], v[88:91], v[168:171], v[124:127]
	v_mfma_f32_16x16x32_bf16 v[120:123], v[112:115], v[168:171], v[120:123]
	v_mfma_f32_16x16x32_bf16 v[100:103], v[88:91], v[176:179], v[100:103]
	v_mfma_f32_16x16x32_bf16 v[96:99], v[112:115], v[176:179], v[96:99]
	v_mfma_f32_16x16x32_bf16 v[76:79], v[88:91], v[208:211], v[76:79]
	v_mfma_f32_16x16x32_bf16 v[72:75], v[112:115], v[208:211], v[72:75]
	v_mfma_f32_16x16x32_bf16 v[148:151], v[92:95], v[164:167], v[148:151]
	v_mfma_f32_16x16x32_bf16 v[144:147], v[116:119], v[164:167], v[144:147]
	v_mfma_f32_16x16x32_bf16 v[124:127], v[92:95], v[172:175], v[124:127]
	v_mfma_f32_16x16x32_bf16 v[120:123], v[116:119], v[172:175], v[120:123]
	v_mfma_f32_16x16x32_bf16 v[100:103], v[92:95], v[180:183], v[100:103]
	v_mfma_f32_16x16x32_bf16 v[96:99], v[116:119], v[180:183], v[96:99]
	v_mfma_f32_16x16x32_bf16 v[76:79], v[92:95], v[212:215], v[76:79]
	v_mfma_f32_16x16x32_bf16 v[72:75], v[116:119], v[212:215], v[72:75]
	v_mfma_f32_16x16x32_bf16 v[140:143], v[132:135], v[160:163], v[140:143]
	v_mfma_f32_16x16x32_bf16 v[128:131], v[152:155], v[160:163], v[128:131]
	v_mfma_f32_16x16x32_bf16 v[108:111], v[132:135], v[168:171], v[108:111]
	v_mfma_f32_16x16x32_bf16 v[104:107], v[152:155], v[168:171], v[104:107]
	v_mfma_f32_16x16x32_bf16 v[84:87], v[132:135], v[176:179], v[84:87]
	v_mfma_f32_16x16x32_bf16 v[80:83], v[152:155], v[176:179], v[80:83]
	v_mfma_f32_16x16x32_bf16 v[68:71], v[132:135], v[208:211], v[68:71]
	v_mfma_f32_16x16x32_bf16 v[64:67], v[152:155], v[208:211], v[64:67]
	v_mfma_f32_16x16x32_bf16 v[140:143], v[136:139], v[164:167], v[140:143]
	v_mfma_f32_16x16x32_bf16 v[128:131], v[156:159], v[164:167], v[128:131]
	v_mfma_f32_16x16x32_bf16 v[108:111], v[136:139], v[172:175], v[108:111]
	v_mfma_f32_16x16x32_bf16 v[104:107], v[156:159], v[172:175], v[104:107]
	v_mfma_f32_16x16x32_bf16 v[84:87], v[136:139], v[180:183], v[84:87]
	v_mfma_f32_16x16x32_bf16 v[80:83], v[156:159], v[180:183], v[80:83]
	v_mfma_f32_16x16x32_bf16 v[68:71], v[136:139], v[212:215], v[68:71]
	v_mfma_f32_16x16x32_bf16 v[64:67], v[156:159], v[212:215], v[64:67]
	s_barrier
	s_setprio 0
	s_add_i32 s50, vcc_lo, s66
	v_lshl_add_u64 v[216:217], v[216:217], 0, s[46:47]
	s_mov_b32 m0, s50
	ds_read_b128 v[160:163], v235 offset:49152
	ds_read_b128 v[164:167], v235 offset:50176
	ds_read_b128 v[168:171], v235 offset:51200
	ds_read_b128 v[172:175], v235 offset:52224
	ds_read_b128 v[176:179], v235 offset:53248
	ds_read_b128 v[180:183], v235 offset:54272
	ds_read_b128 v[208:211], v235 offset:55296
	ds_read_b128 v[212:215], v235 offset:56320
	global_load_lds_dwordx4 v[216:217], off
	s_add_i32 m0, s50, 0x2000
	s_add_u32 s50, s54, 0xb0080
	v_lshl_add_u64 v[216:217], v[218:219], 0, s[46:47]
	s_addc_u32 s51, s55, 0
	s_add_i32 s54, vcc_hi, s66
	global_load_lds_dwordx4 v[216:217], off
	v_lshl_add_u64 v[216:217], s[50:51], 0, v[186:187]
	s_mov_b32 m0, s54
	s_nop 0
	global_load_lds_dwordx4 v[216:217], off
	v_lshl_add_u64 v[216:217], s[50:51], 0, v[190:191]
	s_add_i32 m0, s54, 0x2000
	s_nop 0
	global_load_lds_dwordx4 v[216:217], off
	v_lshl_add_u64 v[216:217], v[220:221], 0, s[46:47]
	s_mov_b32 m0, s74
	s_nop 0
	global_load_lds_dwordx4 v[216:217], off
	v_lshl_add_u64 v[216:217], v[222:223], 0, s[46:47]
	s_mov_b32 m0, s75
	s_nop 0
	global_load_lds_dwordx4 v[216:217], off
	s_waitcnt vmcnt(8)
	s_waitcnt lgkmcnt(0)
	s_setprio 1
	s_barrier
	v_mfma_f32_16x16x32_bf16 v[60:63], v[88:91], v[160:163], v[60:63]
	v_mfma_f32_16x16x32_bf16 v[56:59], v[112:115], v[160:163], v[56:59]
	v_mfma_f32_16x16x32_bf16 v[44:47], v[88:91], v[168:171], v[44:47]
	v_mfma_f32_16x16x32_bf16 v[40:43], v[112:115], v[168:171], v[40:43]
	v_mfma_f32_16x16x32_bf16 v[28:31], v[88:91], v[176:179], v[28:31]
	v_mfma_f32_16x16x32_bf16 v[24:27], v[112:115], v[176:179], v[24:27]
	v_mfma_f32_16x16x32_bf16 v[12:15], v[88:91], v[208:211], v[12:15]
	v_mfma_f32_16x16x32_bf16 v[8:11], v[112:115], v[208:211], v[8:11]
	v_mfma_f32_16x16x32_bf16 v[60:63], v[92:95], v[164:167], v[60:63]
	v_mfma_f32_16x16x32_bf16 v[56:59], v[116:119], v[164:167], v[56:59]
	v_mfma_f32_16x16x32_bf16 v[44:47], v[92:95], v[172:175], v[44:47]
	v_mfma_f32_16x16x32_bf16 v[40:43], v[116:119], v[172:175], v[40:43]
	v_mfma_f32_16x16x32_bf16 v[28:31], v[92:95], v[180:183], v[28:31]
	v_mfma_f32_16x16x32_bf16 v[24:27], v[116:119], v[180:183], v[24:27]
	v_mfma_f32_16x16x32_bf16 v[12:15], v[92:95], v[212:215], v[12:15]
	v_mfma_f32_16x16x32_bf16 v[8:11], v[116:119], v[212:215], v[8:11]
	v_mfma_f32_16x16x32_bf16 v[52:55], v[132:135], v[160:163], v[52:55]
	v_mfma_f32_16x16x32_bf16 v[48:51], v[152:155], v[160:163], v[48:51]
	v_mfma_f32_16x16x32_bf16 v[36:39], v[132:135], v[168:171], v[36:39]
	v_mfma_f32_16x16x32_bf16 v[32:35], v[152:155], v[168:171], v[32:35]
	v_mfma_f32_16x16x32_bf16 v[20:23], v[132:135], v[176:179], v[20:23]
	v_mfma_f32_16x16x32_bf16 v[16:19], v[152:155], v[176:179], v[16:19]
	v_mfma_f32_16x16x32_bf16 v[4:7], v[132:135], v[208:211], v[4:7]
	v_mfma_f32_16x16x32_bf16 v[0:3], v[152:155], v[208:211], v[0:3]
	v_mfma_f32_16x16x32_bf16 v[52:55], v[136:139], v[164:167], v[52:55]
	v_mfma_f32_16x16x32_bf16 v[48:51], v[156:159], v[164:167], v[48:51]
	v_mfma_f32_16x16x32_bf16 v[36:39], v[136:139], v[172:175], v[36:39]
	v_mfma_f32_16x16x32_bf16 v[32:35], v[156:159], v[172:175], v[32:35]
	v_mfma_f32_16x16x32_bf16 v[20:23], v[136:139], v[180:183], v[20:23]
	v_mfma_f32_16x16x32_bf16 v[16:19], v[156:159], v[180:183], v[16:19]
	v_mfma_f32_16x16x32_bf16 v[4:7], v[136:139], v[212:215], v[4:7]
	v_mfma_f32_16x16x32_bf16 v[0:3], v[156:159], v[212:215], v[0:3]
	s_barrier
	s_setprio 0
	s_add_i32 s97, s97, 2
	s_add_u32 s95, s95, 0x100
	s_addc_u32 s96, s96, 0
	s_cmp_gt_u32 s97, 41
	s_mov_b64 s[50:51], s[52:53]
	s_cbranch_scc0 .LBB0_221
	s_and_b64 vcc, exec, s[48:49]
	s_cbranch_vccz .LBB0_224
	s_barrier

.LBB0_312:
	s_ashr_i32 s43, s42, 31
	s_lshl_b64 s[46:47], s[42:43], 19
	s_add_u32 s46, s62, s46
	s_addc_u32 s47, s63, s47
	s_and_b64 s[48:49], s[4:5], exec
	s_cselect_b32 s10, s47, s53
	s_cselect_b32 s43, s46, s52
	s_ashr_i32 s45, s44, 31
	s_lshl_b64 s[48:49], s[44:45], 19
	s_add_u32 s48, s70, s48
	s_addc_u32 s49, s71, s49
	s_and_b64 s[56:57], s[4:5], exec
	s_cselect_b32 s45, s49, s55
	s_cselect_b32 s51, s48, s54
	s_add_u32 s52, s52, 0x40080
	s_addc_u32 s53, s53, 0
	s_add_u32 s67, s54, 0x100
	s_addc_u32 s68, s55, 0
	s_mov_b32 s69, -2
	ds_read_b128 v[128:131], v179
	ds_read_b128 v[132:135], v179 offset:1024
	ds_read_b128 v[136:139], v179 offset:2048
	ds_read_b128 v[140:143], v179 offset:3072
	ds_read_b128 v[188:191], v181
	ds_read_b128 v[192:195], v181 offset:1024
	ds_read_b128 v[196:199], v181 offset:2048
	ds_read_b128 v[200:203], v181 offset:3072
	s_add_u32 s54, s52, 0xfffc0080
	s_addc_u32 s55, s53, -1
	s_cmp_eq_u32 s69, 12
	s_cselect_b32 s57, s10, s55
	s_cselect_b32 s56, s43, s54
	s_cselect_b32 s55, s45, s68
	s_cselect_b32 s54, s51, s67
	v_lshl_add_u64 v[238:239], s[52:53], 0, v[162:163]
	s_add_i32 m0, s75, 0xc000
	ds_read_b128 v[204:207], v183
	ds_read_b128 v[208:211], v183 offset:1024
	ds_read_b128 v[212:215], v183 offset:2048
	ds_read_b128 v[216:219], v183 offset:3072
	ds_read_b128 v[220:223], v183 offset:4096
	ds_read_b128 v[224:227], v183 offset:5120
	ds_read_b128 v[230:233], v183 offset:6144
	ds_read_b128 v[234:237], v183 offset:7168
	global_load_lds_dwordx4 v[238:239], off
	v_lshl_add_u64 v[238:239], s[52:53], 0, v[164:165]
	s_add_i32 m0, s75, 0xe000
	s_nop 0
	global_load_lds_dwordx4 v[238:239], off
	s_waitcnt vmcnt(8)
	s_waitcnt lgkmcnt(0)
	s_setprio 1
	s_barrier
	v_mfma_f32_16x16x32_bf16 v[124:127], v[128:131], v[204:207], 0
	v_mfma_f32_16x16x32_bf16 v[120:123], v[136:139], v[204:207], 0
	v_mfma_f32_16x16x32_bf16 v[108:111], v[128:131], v[212:215], 0
	v_mfma_f32_16x16x32_bf16 v[104:107], v[136:139], v[212:215], 0
	v_mfma_f32_16x16x32_bf16 v[92:95], v[128:131], v[220:223], 0
	v_mfma_f32_16x16x32_bf16 v[88:91], v[136:139], v[220:223], 0
	v_mfma_f32_16x16x32_bf16 v[76:79], v[128:131], v[230:233], 0
	v_mfma_f32_16x16x32_bf16 v[72:75], v[136:139], v[230:233], 0
	v_mfma_f32_16x16x32_bf16 v[124:127], v[132:135], v[208:211], v[124:127]
	v_mfma_f32_16x16x32_bf16 v[120:123], v[140:143], v[208:211], v[120:123]
	v_mfma_f32_16x16x32_bf16 v[108:111], v[132:135], v[216:219], v[108:111]
	v_mfma_f32_16x16x32_bf16 v[104:107], v[140:143], v[216:219], v[104:107]
	v_mfma_f32_16x16x32_bf16 v[92:95], v[132:135], v[224:227], v[92:95]
	v_mfma_f32_16x16x32_bf16 v[88:91], v[140:143], v[224:227], v[88:91]
	v_mfma_f32_16x16x32_bf16 v[76:79], v[132:135], v[234:237], v[76:79]
	v_mfma_f32_16x16x32_bf16 v[72:75], v[140:143], v[234:237], v[72:75]
	v_mfma_f32_16x16x32_bf16 v[116:119], v[188:191], v[204:207], 0
	v_mfma_f32_16x16x32_bf16 v[112:115], v[196:199], v[204:207], 0
	v_mfma_f32_16x16x32_bf16 v[100:103], v[188:191], v[212:215], 0
	v_mfma_f32_16x16x32_bf16 v[96:99], v[196:199], v[212:215], 0
	v_mfma_f32_16x16x32_bf16 v[84:87], v[188:191], v[220:223], 0
	v_mfma_f32_16x16x32_bf16 v[80:83], v[196:199], v[220:223], 0
	v_mfma_f32_16x16x32_bf16 v[68:71], v[188:191], v[230:233], 0
	v_mfma_f32_16x16x32_bf16 v[64:67], v[196:199], v[230:233], 0
	v_mfma_f32_16x16x32_bf16 v[116:119], v[192:195], v[208:211], v[116:119]
	v_mfma_f32_16x16x32_bf16 v[112:115], v[200:203], v[208:211], v[112:115]
	v_mfma_f32_16x16x32_bf16 v[100:103], v[192:195], v[216:219], v[100:103]
	v_mfma_f32_16x16x32_bf16 v[96:99], v[200:203], v[216:219], v[96:99]
	v_mfma_f32_16x16x32_bf16 v[84:87], v[192:195], v[224:227], v[84:87]
	v_mfma_f32_16x16x32_bf16 v[80:83], v[200:203], v[224:227], v[80:83]
	v_mfma_f32_16x16x32_bf16 v[68:71], v[192:195], v[234:237], v[68:71]
	v_mfma_f32_16x16x32_bf16 v[64:67], v[200:203], v[234:237], v[64:67]
	s_barrier
	s_setprio 0
	s_add_i32 vcc_lo, s92, s72
	v_lshl_add_u64 v[238:239], s[54:55], 0, v[148:149]
	s_mov_b32 m0, vcc_lo
	ds_read_b128 v[204:207], v183 offset:16384
	ds_read_b128 v[208:211], v183 offset:17408
	ds_read_b128 v[212:215], v183 offset:18432
	ds_read_b128 v[216:219], v183 offset:19456
	ds_read_b128 v[220:223], v183 offset:20480
	ds_read_b128 v[224:227], v183 offset:21504
	ds_read_b128 v[230:233], v183 offset:22528
	ds_read_b128 v[234:237], v183 offset:23552
	global_load_lds_dwordx4 v[238:239], off
	s_add_i32 m0, vcc_lo, 0x2000
	s_add_u32 vcc_lo, s54, 0x40000
	v_lshl_add_u64 v[240:241], s[54:55], 0, v[144:145]
	s_addc_u32 vcc_hi, s55, 0
	s_add_i32 s83, s93, s72
	global_load_lds_dwordx4 v[240:241], off
	v_lshl_add_u64 v[242:243], vcc, 0, v[148:149]
	s_mov_b32 m0, s83
	v_lshl_add_u64 v[244:245], s[56:57], 0, v[146:147]
	global_load_lds_dwordx4 v[242:243], off
	v_lshl_add_u64 v[242:243], vcc, 0, v[144:145]
	s_add_i32 m0, s83, 0x2000
	s_nop 0
	global_load_lds_dwordx4 v[242:243], off
	v_lshl_add_u64 v[242:243], s[56:57], 0, v[150:151]
	s_mov_b32 m0, s75
	s_nop 0
	global_load_lds_dwordx4 v[242:243], off
	s_mov_b32 m0, s76
	s_nop 0
	global_load_lds_dwordx4 v[244:245], off
	s_waitcnt vmcnt(8)
	s_waitcnt lgkmcnt(0)
	s_setprio 1
	s_barrier
	v_mfma_f32_16x16x32_bf16 v[60:63], v[128:131], v[204:207], 0
	v_mfma_f32_16x16x32_bf16 v[56:59], v[136:139], v[204:207], 0
	v_mfma_f32_16x16x32_bf16 v[44:47], v[128:131], v[212:215], 0
	v_mfma_f32_16x16x32_bf16 v[40:43], v[136:139], v[212:215], 0
	v_mfma_f32_16x16x32_bf16 v[28:31], v[128:131], v[220:223], 0
	v_mfma_f32_16x16x32_bf16 v[24:27], v[136:139], v[220:223], 0
	v_mfma_f32_16x16x32_bf16 v[12:15], v[128:131], v[230:233], 0
	v_mfma_f32_16x16x32_bf16 v[8:11], v[136:139], v[230:233], 0
	v_mfma_f32_16x16x32_bf16 v[60:63], v[132:135], v[208:211], v[60:63]
	v_mfma_f32_16x16x32_bf16 v[56:59], v[140:143], v[208:211], v[56:59]
	v_mfma_f32_16x16x32_bf16 v[44:47], v[132:135], v[216:219], v[44:47]
	v_mfma_f32_16x16x32_bf16 v[40:43], v[140:143], v[216:219], v[40:43]
	v_mfma_f32_16x16x32_bf16 v[28:31], v[132:135], v[224:227], v[28:31]
	v_mfma_f32_16x16x32_bf16 v[24:27], v[140:143], v[224:227], v[24:27]
	v_mfma_f32_16x16x32_bf16 v[12:15], v[132:135], v[234:237], v[12:15]
	v_mfma_f32_16x16x32_bf16 v[8:11], v[140:143], v[234:237], v[8:11]
	v_mfma_f32_16x16x32_bf16 v[52:55], v[188:191], v[204:207], 0
	v_mfma_f32_16x16x32_bf16 v[48:51], v[196:199], v[204:207], 0
	v_mfma_f32_16x16x32_bf16 v[36:39], v[188:191], v[212:215], 0
	v_mfma_f32_16x16x32_bf16 v[32:35], v[196:199], v[212:215], 0
	v_mfma_f32_16x16x32_bf16 v[20:23], v[188:191], v[220:223], 0
	v_mfma_f32_16x16x32_bf16 v[16:19], v[196:199], v[220:223], 0
	v_mfma_f32_16x16x32_bf16 v[4:7], v[188:191], v[230:233], 0
	v_mfma_f32_16x16x32_bf16 v[0:3], v[196:199], v[230:233], 0
	v_mfma_f32_16x16x32_bf16 v[52:55], v[192:195], v[208:211], v[52:55]
	v_mfma_f32_16x16x32_bf16 v[48:51], v[200:203], v[208:211], v[48:51]
	v_mfma_f32_16x16x32_bf16 v[36:39], v[192:195], v[216:219], v[36:39]
	v_mfma_f32_16x16x32_bf16 v[32:35], v[200:203], v[216:219], v[32:35]
	v_mfma_f32_16x16x32_bf16 v[20:23], v[192:195], v[224:227], v[20:23]
	v_mfma_f32_16x16x32_bf16 v[16:19], v[200:203], v[224:227], v[16:19]
	v_mfma_f32_16x16x32_bf16 v[4:7], v[192:195], v[234:237], v[4:7]
	v_mfma_f32_16x16x32_bf16 v[0:3], v[200:203], v[234:237], v[0:3]
	s_barrier
	s_setprio 0
	s_add_i32 s83, 0, 0x18000
	s_add_i32 vcc_lo, 0, 0x1c000
	v_add_u32_e32 v140, s83, v157
	v_add_u32_e32 v171, vcc_lo, v157
	ds_read_b128 v[128:131], v140
	ds_read_b128 v[132:135], v140 offset:1024
	ds_read_b128 v[136:139], v140 offset:2048
	ds_read_b128 v[140:143], v140 offset:3072
	ds_read_b128 v[188:191], v171
	ds_read_b128 v[192:195], v171 offset:1024
	ds_read_b128 v[196:199], v171 offset:2048
	ds_read_b128 v[200:203], v171 offset:3072
	s_add_u32 s56, s56, 0x40000
	s_addc_u32 s57, s57, 0
	s_mov_b32 m0, s77
	v_lshl_add_u64 v[246:247], s[56:57], 0, v[150:151]
	ds_read_b128 v[204:207], v183 offset:32768
	ds_read_b128 v[208:211], v183 offset:33792
	ds_read_b128 v[212:215], v183 offset:34816
	ds_read_b128 v[216:219], v183 offset:35840
	ds_read_b128 v[220:223], v183 offset:36864
	ds_read_b128 v[224:227], v183 offset:37888
	ds_read_b128 v[230:233], v183 offset:38912
	ds_read_b128 v[234:237], v183 offset:39936
	global_load_lds_dwordx4 v[246:247], off
	v_lshl_add_u64 v[246:247], s[56:57], 0, v[146:147]
	s_mov_b32 m0, s78
	s_nop 0
	global_load_lds_dwordx4 v[246:247], off
	s_waitcnt vmcnt(8)
	s_waitcnt lgkmcnt(0)
	s_setprio 1
	s_barrier
	v_mfma_f32_16x16x32_bf16 v[124:127], v[128:131], v[204:207], v[124:127]
	v_mfma_f32_16x16x32_bf16 v[120:123], v[136:139], v[204:207], v[120:123]
	v_mfma_f32_16x16x32_bf16 v[108:111], v[128:131], v[212:215], v[108:111]
	v_mfma_f32_16x16x32_bf16 v[104:107], v[136:139], v[212:215], v[104:107]
	v_mfma_f32_16x16x32_bf16 v[92:95], v[128:131], v[220:223], v[92:95]
	v_mfma_f32_16x16x32_bf16 v[88:91], v[136:139], v[220:223], v[88:91]
	v_mfma_f32_16x16x32_bf16 v[76:79], v[128:131], v[230:233], v[76:79]
	v_mfma_f32_16x16x32_bf16 v[72:75], v[136:139], v[230:233], v[72:75]
	v_mfma_f32_16x16x32_bf16 v[124:127], v[132:135], v[208:211], v[124:127]
	v_mfma_f32_16x16x32_bf16 v[120:123], v[140:143], v[208:211], v[120:123]
	v_mfma_f32_16x16x32_bf16 v[108:111], v[132:135], v[216:219], v[108:111]
	v_mfma_f32_16x16x32_bf16 v[104:107], v[140:143], v[216:219], v[104:107]
	v_mfma_f32_16x16x32_bf16 v[92:95], v[132:135], v[224:227], v[92:95]
	v_mfma_f32_16x16x32_bf16 v[88:91], v[140:143], v[224:227], v[88:91]
	v_mfma_f32_16x16x32_bf16 v[76:79], v[132:135], v[234:237], v[76:79]
	v_mfma_f32_16x16x32_bf16 v[72:75], v[140:143], v[234:237], v[72:75]
	v_mfma_f32_16x16x32_bf16 v[116:119], v[188:191], v[204:207], v[116:119]
	v_mfma_f32_16x16x32_bf16 v[112:115], v[196:199], v[204:207], v[112:115]
	v_mfma_f32_16x16x32_bf16 v[100:103], v[188:191], v[212:215], v[100:103]
	v_mfma_f32_16x16x32_bf16 v[96:99], v[196:199], v[212:215], v[96:99]
	v_mfma_f32_16x16x32_bf16 v[84:87], v[188:191], v[220:223], v[84:87]
	v_mfma_f32_16x16x32_bf16 v[80:83], v[196:199], v[220:223], v[80:83]
	v_mfma_f32_16x16x32_bf16 v[68:71], v[188:191], v[230:233], v[68:71]
	v_mfma_f32_16x16x32_bf16 v[64:67], v[196:199], v[230:233], v[64:67]
	v_mfma_f32_16x16x32_bf16 v[116:119], v[192:195], v[208:211], v[116:119]
	v_mfma_f32_16x16x32_bf16 v[112:115], v[200:203], v[208:211], v[112:115]
	v_mfma_f32_16x16x32_bf16 v[100:103], v[192:195], v[216:219], v[100:103]
	v_mfma_f32_16x16x32_bf16 v[96:99], v[200:203], v[216:219], v[96:99]
	v_mfma_f32_16x16x32_bf16 v[84:87], v[192:195], v[224:227], v[84:87]
	v_mfma_f32_16x16x32_bf16 v[80:83], v[200:203], v[224:227], v[80:83]
	v_mfma_f32_16x16x32_bf16 v[68:71], v[192:195], v[234:237], v[68:71]
	v_mfma_f32_16x16x32_bf16 v[64:67], v[200:203], v[234:237], v[64:67]
	s_barrier
	s_setprio 0
	s_add_i32 s56, s83, s72
	v_lshl_add_u64 v[238:239], v[238:239], 0, s[38:39]
	s_mov_b32 m0, s56
	ds_read_b128 v[204:207], v183 offset:49152
	ds_read_b128 v[208:211], v183 offset:50176
	ds_read_b128 v[212:215], v183 offset:51200
	ds_read_b128 v[216:219], v183 offset:52224
	ds_read_b128 v[220:223], v183 offset:53248
	ds_read_b128 v[224:227], v183 offset:54272
	ds_read_b128 v[230:233], v183 offset:55296
	ds_read_b128 v[234:237], v183 offset:56320
	global_load_lds_dwordx4 v[238:239], off
	s_add_i32 m0, s56, 0x2000
	s_add_u32 s54, s54, 0x40080
	v_lshl_add_u64 v[238:239], v[240:241], 0, s[38:39]
	s_addc_u32 s55, s55, 0
	s_add_i32 s56, vcc_lo, s72
	global_load_lds_dwordx4 v[238:239], off
	v_lshl_add_u64 v[238:239], s[54:55], 0, v[148:149]
	s_mov_b32 m0, s56
	s_nop 0
	global_load_lds_dwordx4 v[238:239], off
	v_lshl_add_u64 v[238:239], s[54:55], 0, v[144:145]
	s_add_i32 m0, s56, 0x2000
	s_nop 0
	global_load_lds_dwordx4 v[238:239], off
	v_lshl_add_u64 v[238:239], v[242:243], 0, s[38:39]
	s_mov_b32 m0, s87
	s_nop 0
	global_load_lds_dwordx4 v[238:239], off
	v_lshl_add_u64 v[238:239], v[244:245], 0, s[38:39]
	s_mov_b32 m0, s88
	s_nop 0
	global_load_lds_dwordx4 v[238:239], off
	s_waitcnt vmcnt(8)
	s_waitcnt lgkmcnt(0)
	s_setprio 1
	s_barrier
	v_mfma_f32_16x16x32_bf16 v[60:63], v[128:131], v[204:207], v[60:63]
	v_mfma_f32_16x16x32_bf16 v[56:59], v[136:139], v[204:207], v[56:59]
	v_mfma_f32_16x16x32_bf16 v[44:47], v[128:131], v[212:215], v[44:47]
	v_mfma_f32_16x16x32_bf16 v[40:43], v[136:139], v[212:215], v[40:43]
	v_mfma_f32_16x16x32_bf16 v[28:31], v[128:131], v[220:223], v[28:31]
	v_mfma_f32_16x16x32_bf16 v[24:27], v[136:139], v[220:223], v[24:27]
	v_mfma_f32_16x16x32_bf16 v[12:15], v[128:131], v[230:233], v[12:15]
	v_mfma_f32_16x16x32_bf16 v[8:11], v[136:139], v[230:233], v[8:11]
	v_mfma_f32_16x16x32_bf16 v[60:63], v[132:135], v[208:211], v[60:63]
	v_mfma_f32_16x16x32_bf16 v[56:59], v[140:143], v[208:211], v[56:59]
	v_mfma_f32_16x16x32_bf16 v[44:47], v[132:135], v[216:219], v[44:47]
	v_mfma_f32_16x16x32_bf16 v[40:43], v[140:143], v[216:219], v[40:43]
	v_mfma_f32_16x16x32_bf16 v[28:31], v[132:135], v[224:227], v[28:31]
	v_mfma_f32_16x16x32_bf16 v[24:27], v[140:143], v[224:227], v[24:27]
	v_mfma_f32_16x16x32_bf16 v[12:15], v[132:135], v[234:237], v[12:15]
	v_mfma_f32_16x16x32_bf16 v[8:11], v[140:143], v[234:237], v[8:11]
	v_mfma_f32_16x16x32_bf16 v[52:55], v[188:191], v[204:207], v[52:55]
	v_mfma_f32_16x16x32_bf16 v[48:51], v[196:199], v[204:207], v[48:51]
	v_mfma_f32_16x16x32_bf16 v[36:39], v[188:191], v[212:215], v[36:39]
	v_mfma_f32_16x16x32_bf16 v[32:35], v[196:199], v[212:215], v[32:35]
	v_mfma_f32_16x16x32_bf16 v[20:23], v[188:191], v[220:223], v[20:23]
	v_mfma_f32_16x16x32_bf16 v[16:19], v[196:199], v[220:223], v[16:19]
	v_mfma_f32_16x16x32_bf16 v[4:7], v[188:191], v[230:233], v[4:7]
	v_mfma_f32_16x16x32_bf16 v[0:3], v[196:199], v[230:233], v[0:3]
	v_mfma_f32_16x16x32_bf16 v[52:55], v[192:195], v[208:211], v[52:55]
	v_mfma_f32_16x16x32_bf16 v[48:51], v[200:203], v[208:211], v[48:51]
	v_mfma_f32_16x16x32_bf16 v[36:39], v[192:195], v[216:219], v[36:39]
	v_mfma_f32_16x16x32_bf16 v[32:35], v[200:203], v[216:219], v[32:35]
	v_mfma_f32_16x16x32_bf16 v[20:23], v[192:195], v[224:227], v[20:23]
	v_mfma_f32_16x16x32_bf16 v[16:19], v[200:203], v[224:227], v[16:19]
	v_mfma_f32_16x16x32_bf16 v[4:7], v[192:195], v[234:237], v[4:7]
	v_mfma_f32_16x16x32_bf16 v[0:3], v[200:203], v[234:237], v[0:3]
	s_barrier
	s_setprio 0
	s_add_i32 s69, s69, 2
	s_add_u32 s52, s52, 0x100
	s_addc_u32 s53, s53, 0
	s_add_u32 s67, s67, 0x100
	s_addc_u32 s68, s68, 0
	s_cmp_gt_u32 s69, 13
.LBB0_313:
	ds_read_b128 v[128:131], v179
	ds_read_b128 v[132:135], v179 offset:1024
	ds_read_b128 v[136:139], v179 offset:2048
	ds_read_b128 v[140:143], v179 offset:3072
	ds_read_b128 v[188:191], v181
	ds_read_b128 v[192:195], v181 offset:1024
	ds_read_b128 v[196:199], v181 offset:2048
	ds_read_b128 v[200:203], v181 offset:3072
	s_add_u32 s54, s52, 0xfffc0080
	s_addc_u32 s55, s53, -1
	s_cmp_eq_u32 s69, 12
	s_cselect_b32 s57, s10, s55
	s_cselect_b32 s56, s43, s54
	s_cselect_b32 s55, s45, s68
	s_cselect_b32 s54, s51, s67
	v_lshl_add_u64 v[238:239], s[52:53], 0, v[162:163]
	s_add_i32 m0, s75, 0xc000
	ds_read_b128 v[204:207], v183
	ds_read_b128 v[208:211], v183 offset:1024
	ds_read_b128 v[212:215], v183 offset:2048
	ds_read_b128 v[216:219], v183 offset:3072
	ds_read_b128 v[220:223], v183 offset:4096
	ds_read_b128 v[224:227], v183 offset:5120
	ds_read_b128 v[230:233], v183 offset:6144
	ds_read_b128 v[234:237], v183 offset:7168
	global_load_lds_dwordx4 v[238:239], off
	v_lshl_add_u64 v[238:239], s[52:53], 0, v[164:165]
	s_add_i32 m0, s75, 0xe000
	s_nop 0
	global_load_lds_dwordx4 v[238:239], off
	s_waitcnt vmcnt(8)
	s_waitcnt lgkmcnt(0)
	s_setprio 1
	s_barrier
	v_mfma_f32_16x16x32_bf16 v[124:127], v[128:131], v[204:207], v[124:127]
	v_mfma_f32_16x16x32_bf16 v[120:123], v[136:139], v[204:207], v[120:123]
	v_mfma_f32_16x16x32_bf16 v[108:111], v[128:131], v[212:215], v[108:111]
	v_mfma_f32_16x16x32_bf16 v[104:107], v[136:139], v[212:215], v[104:107]
	v_mfma_f32_16x16x32_bf16 v[92:95], v[128:131], v[220:223], v[92:95]
	v_mfma_f32_16x16x32_bf16 v[88:91], v[136:139], v[220:223], v[88:91]
	v_mfma_f32_16x16x32_bf16 v[76:79], v[128:131], v[230:233], v[76:79]
	v_mfma_f32_16x16x32_bf16 v[72:75], v[136:139], v[230:233], v[72:75]
	v_mfma_f32_16x16x32_bf16 v[124:127], v[132:135], v[208:211], v[124:127]
	v_mfma_f32_16x16x32_bf16 v[120:123], v[140:143], v[208:211], v[120:123]
	v_mfma_f32_16x16x32_bf16 v[108:111], v[132:135], v[216:219], v[108:111]
	v_mfma_f32_16x16x32_bf16 v[104:107], v[140:143], v[216:219], v[104:107]
	v_mfma_f32_16x16x32_bf16 v[92:95], v[132:135], v[224:227], v[92:95]
	v_mfma_f32_16x16x32_bf16 v[88:91], v[140:143], v[224:227], v[88:91]
	v_mfma_f32_16x16x32_bf16 v[76:79], v[132:135], v[234:237], v[76:79]
	v_mfma_f32_16x16x32_bf16 v[72:75], v[140:143], v[234:237], v[72:75]
	v_mfma_f32_16x16x32_bf16 v[116:119], v[188:191], v[204:207], v[116:119]
	v_mfma_f32_16x16x32_bf16 v[112:115], v[196:199], v[204:207], v[112:115]
	v_mfma_f32_16x16x32_bf16 v[100:103], v[188:191], v[212:215], v[100:103]
	v_mfma_f32_16x16x32_bf16 v[96:99], v[196:199], v[212:215], v[96:99]
	v_mfma_f32_16x16x32_bf16 v[84:87], v[188:191], v[220:223], v[84:87]
	v_mfma_f32_16x16x32_bf16 v[80:83], v[196:199], v[220:223], v[80:83]
	v_mfma_f32_16x16x32_bf16 v[68:71], v[188:191], v[230:233], v[68:71]
	v_mfma_f32_16x16x32_bf16 v[64:67], v[196:199], v[230:233], v[64:67]
	v_mfma_f32_16x16x32_bf16 v[116:119], v[192:195], v[208:211], v[116:119]
	v_mfma_f32_16x16x32_bf16 v[112:115], v[200:203], v[208:211], v[112:115]
	v_mfma_f32_16x16x32_bf16 v[100:103], v[192:195], v[216:219], v[100:103]
	v_mfma_f32_16x16x32_bf16 v[96:99], v[200:203], v[216:219], v[96:99]
	v_mfma_f32_16x16x32_bf16 v[84:87], v[192:195], v[224:227], v[84:87]
	v_mfma_f32_16x16x32_bf16 v[80:83], v[200:203], v[224:227], v[80:83]
	v_mfma_f32_16x16x32_bf16 v[68:71], v[192:195], v[234:237], v[68:71]
	v_mfma_f32_16x16x32_bf16 v[64:67], v[200:203], v[234:237], v[64:67]
	s_barrier
	s_setprio 0
	s_add_i32 vcc_lo, s92, s72
	v_lshl_add_u64 v[238:239], s[54:55], 0, v[148:149]
	s_mov_b32 m0, vcc_lo
	ds_read_b128 v[204:207], v183 offset:16384
	ds_read_b128 v[208:211], v183 offset:17408
	ds_read_b128 v[212:215], v183 offset:18432
	ds_read_b128 v[216:219], v183 offset:19456
	ds_read_b128 v[220:223], v183 offset:20480
	ds_read_b128 v[224:227], v183 offset:21504
	ds_read_b128 v[230:233], v183 offset:22528
	ds_read_b128 v[234:237], v183 offset:23552
	global_load_lds_dwordx4 v[238:239], off
	s_add_i32 m0, vcc_lo, 0x2000
	s_add_u32 vcc_lo, s54, 0x40000
	v_lshl_add_u64 v[240:241], s[54:55], 0, v[144:145]
	s_addc_u32 vcc_hi, s55, 0
	s_add_i32 s83, s93, s72
	global_load_lds_dwordx4 v[240:241], off
	v_lshl_add_u64 v[242:243], vcc, 0, v[148:149]
	s_mov_b32 m0, s83
	v_lshl_add_u64 v[244:245], s[56:57], 0, v[146:147]
	global_load_lds_dwordx4 v[242:243], off
	v_lshl_add_u64 v[242:243], vcc, 0, v[144:145]
	s_add_i32 m0, s83, 0x2000
	s_nop 0
	global_load_lds_dwordx4 v[242:243], off
	v_lshl_add_u64 v[242:243], s[56:57], 0, v[150:151]
	s_mov_b32 m0, s75
	s_nop 0
	global_load_lds_dwordx4 v[242:243], off
	s_mov_b32 m0, s76
	s_nop 0
	global_load_lds_dwordx4 v[244:245], off
	s_waitcnt vmcnt(8)
	s_waitcnt lgkmcnt(0)
	s_setprio 1
	s_barrier
	v_mfma_f32_16x16x32_bf16 v[60:63], v[128:131], v[204:207], v[60:63]
	v_mfma_f32_16x16x32_bf16 v[56:59], v[136:139], v[204:207], v[56:59]
	v_mfma_f32_16x16x32_bf16 v[44:47], v[128:131], v[212:215], v[44:47]
	v_mfma_f32_16x16x32_bf16 v[40:43], v[136:139], v[212:215], v[40:43]
	v_mfma_f32_16x16x32_bf16 v[28:31], v[128:131], v[220:223], v[28:31]
	v_mfma_f32_16x16x32_bf16 v[24:27], v[136:139], v[220:223], v[24:27]
	v_mfma_f32_16x16x32_bf16 v[12:15], v[128:131], v[230:233], v[12:15]
	v_mfma_f32_16x16x32_bf16 v[8:11], v[136:139], v[230:233], v[8:11]
	v_mfma_f32_16x16x32_bf16 v[60:63], v[132:135], v[208:211], v[60:63]
	v_mfma_f32_16x16x32_bf16 v[56:59], v[140:143], v[208:211], v[56:59]
	v_mfma_f32_16x16x32_bf16 v[44:47], v[132:135], v[216:219], v[44:47]
	v_mfma_f32_16x16x32_bf16 v[40:43], v[140:143], v[216:219], v[40:43]
	v_mfma_f32_16x16x32_bf16 v[28:31], v[132:135], v[224:227], v[28:31]
	v_mfma_f32_16x16x32_bf16 v[24:27], v[140:143], v[224:227], v[24:27]
	v_mfma_f32_16x16x32_bf16 v[12:15], v[132:135], v[234:237], v[12:15]
	v_mfma_f32_16x16x32_bf16 v[8:11], v[140:143], v[234:237], v[8:11]
	v_mfma_f32_16x16x32_bf16 v[52:55], v[188:191], v[204:207], v[52:55]
	v_mfma_f32_16x16x32_bf16 v[48:51], v[196:199], v[204:207], v[48:51]
	v_mfma_f32_16x16x32_bf16 v[36:39], v[188:191], v[212:215], v[36:39]
	v_mfma_f32_16x16x32_bf16 v[32:35], v[196:199], v[212:215], v[32:35]
	v_mfma_f32_16x16x32_bf16 v[20:23], v[188:191], v[220:223], v[20:23]
	v_mfma_f32_16x16x32_bf16 v[16:19], v[196:199], v[220:223], v[16:19]
	v_mfma_f32_16x16x32_bf16 v[4:7], v[188:191], v[230:233], v[4:7]
	v_mfma_f32_16x16x32_bf16 v[0:3], v[196:199], v[230:233], v[0:3]
	v_mfma_f32_16x16x32_bf16 v[52:55], v[192:195], v[208:211], v[52:55]
	v_mfma_f32_16x16x32_bf16 v[48:51], v[200:203], v[208:211], v[48:51]
	v_mfma_f32_16x16x32_bf16 v[36:39], v[192:195], v[216:219], v[36:39]
	v_mfma_f32_16x16x32_bf16 v[32:35], v[200:203], v[216:219], v[32:35]
	v_mfma_f32_16x16x32_bf16 v[20:23], v[192:195], v[224:227], v[20:23]
	v_mfma_f32_16x16x32_bf16 v[16:19], v[200:203], v[224:227], v[16:19]
	v_mfma_f32_16x16x32_bf16 v[4:7], v[192:195], v[234:237], v[4:7]
	v_mfma_f32_16x16x32_bf16 v[0:3], v[200:203], v[234:237], v[0:3]
	s_barrier
	s_setprio 0
	s_add_i32 s83, 0, 0x18000
	s_add_i32 vcc_lo, 0, 0x1c000
	v_add_u32_e32 v140, s83, v157
	v_add_u32_e32 v171, vcc_lo, v157
	ds_read_b128 v[128:131], v140
	ds_read_b128 v[132:135], v140 offset:1024
	ds_read_b128 v[136:139], v140 offset:2048
	ds_read_b128 v[140:143], v140 offset:3072
	ds_read_b128 v[188:191], v171
	ds_read_b128 v[192:195], v171 offset:1024
	ds_read_b128 v[196:199], v171 offset:2048
	ds_read_b128 v[200:203], v171 offset:3072
	s_add_u32 s56, s56, 0x40000
	s_addc_u32 s57, s57, 0
	s_mov_b32 m0, s77
	v_lshl_add_u64 v[246:247], s[56:57], 0, v[150:151]
	ds_read_b128 v[204:207], v183 offset:32768
	ds_read_b128 v[208:211], v183 offset:33792
	ds_read_b128 v[212:215], v183 offset:34816
	ds_read_b128 v[216:219], v183 offset:35840
	ds_read_b128 v[220:223], v183 offset:36864
	ds_read_b128 v[224:227], v183 offset:37888
	ds_read_b128 v[230:233], v183 offset:38912
	ds_read_b128 v[234:237], v183 offset:39936
	global_load_lds_dwordx4 v[246:247], off
	v_lshl_add_u64 v[246:247], s[56:57], 0, v[146:147]
	s_mov_b32 m0, s78
	s_nop 0
	global_load_lds_dwordx4 v[246:247], off
	s_waitcnt vmcnt(8)
	s_waitcnt lgkmcnt(0)
	s_setprio 1
	s_barrier
	v_mfma_f32_16x16x32_bf16 v[124:127], v[128:131], v[204:207], v[124:127]
	v_mfma_f32_16x16x32_bf16 v[120:123], v[136:139], v[204:207], v[120:123]
	v_mfma_f32_16x16x32_bf16 v[108:111], v[128:131], v[212:215], v[108:111]
	v_mfma_f32_16x16x32_bf16 v[104:107], v[136:139], v[212:215], v[104:107]
	v_mfma_f32_16x16x32_bf16 v[92:95], v[128:131], v[220:223], v[92:95]
	v_mfma_f32_16x16x32_bf16 v[88:91], v[136:139], v[220:223], v[88:91]
	v_mfma_f32_16x16x32_bf16 v[76:79], v[128:131], v[230:233], v[76:79]
	v_mfma_f32_16x16x32_bf16 v[72:75], v[136:139], v[230:233], v[72:75]
	v_mfma_f32_16x16x32_bf16 v[124:127], v[132:135], v[208:211], v[124:127]
	v_mfma_f32_16x16x32_bf16 v[120:123], v[140:143], v[208:211], v[120:123]
	v_mfma_f32_16x16x32_bf16 v[108:111], v[132:135], v[216:219], v[108:111]
	v_mfma_f32_16x16x32_bf16 v[104:107], v[140:143], v[216:219], v[104:107]
	v_mfma_f32_16x16x32_bf16 v[92:95], v[132:135], v[224:227], v[92:95]
	v_mfma_f32_16x16x32_bf16 v[88:91], v[140:143], v[224:227], v[88:91]
	v_mfma_f32_16x16x32_bf16 v[76:79], v[132:135], v[234:237], v[76:79]
	v_mfma_f32_16x16x32_bf16 v[72:75], v[140:143], v[234:237], v[72:75]
	v_mfma_f32_16x16x32_bf16 v[116:119], v[188:191], v[204:207], v[116:119]
	v_mfma_f32_16x16x32_bf16 v[112:115], v[196:199], v[204:207], v[112:115]
	v_mfma_f32_16x16x32_bf16 v[100:103], v[188:191], v[212:215], v[100:103]
	v_mfma_f32_16x16x32_bf16 v[96:99], v[196:199], v[212:215], v[96:99]
	v_mfma_f32_16x16x32_bf16 v[84:87], v[188:191], v[220:223], v[84:87]
	v_mfma_f32_16x16x32_bf16 v[80:83], v[196:199], v[220:223], v[80:83]
	v_mfma_f32_16x16x32_bf16 v[68:71], v[188:191], v[230:233], v[68:71]
	v_mfma_f32_16x16x32_bf16 v[64:67], v[196:199], v[230:233], v[64:67]
	v_mfma_f32_16x16x32_bf16 v[116:119], v[192:195], v[208:211], v[116:119]
	v_mfma_f32_16x16x32_bf16 v[112:115], v[200:203], v[208:211], v[112:115]
	v_mfma_f32_16x16x32_bf16 v[100:103], v[192:195], v[216:219], v[100:103]
	v_mfma_f32_16x16x32_bf16 v[96:99], v[200:203], v[216:219], v[96:99]
	v_mfma_f32_16x16x32_bf16 v[84:87], v[192:195], v[224:227], v[84:87]
	v_mfma_f32_16x16x32_bf16 v[80:83], v[200:203], v[224:227], v[80:83]
	v_mfma_f32_16x16x32_bf16 v[68:71], v[192:195], v[234:237], v[68:71]
	v_mfma_f32_16x16x32_bf16 v[64:67], v[200:203], v[234:237], v[64:67]
	s_barrier
	s_setprio 0
	s_add_i32 s56, s83, s72
	v_lshl_add_u64 v[238:239], v[238:239], 0, s[38:39]
	s_mov_b32 m0, s56
	ds_read_b128 v[204:207], v183 offset:49152
	ds_read_b128 v[208:211], v183 offset:50176
	ds_read_b128 v[212:215], v183 offset:51200
	ds_read_b128 v[216:219], v183 offset:52224
	ds_read_b128 v[220:223], v183 offset:53248
	ds_read_b128 v[224:227], v183 offset:54272
	ds_read_b128 v[230:233], v183 offset:55296
	ds_read_b128 v[234:237], v183 offset:56320
	global_load_lds_dwordx4 v[238:239], off
	s_add_i32 m0, s56, 0x2000
	s_add_u32 s54, s54, 0x40080
	v_lshl_add_u64 v[238:239], v[240:241], 0, s[38:39]
	s_addc_u32 s55, s55, 0
	s_add_i32 s56, vcc_lo, s72
	global_load_lds_dwordx4 v[238:239], off
	v_lshl_add_u64 v[238:239], s[54:55], 0, v[148:149]
	s_mov_b32 m0, s56
	s_nop 0
	global_load_lds_dwordx4 v[238:239], off
	v_lshl_add_u64 v[238:239], s[54:55], 0, v[144:145]
	s_add_i32 m0, s56, 0x2000
	s_nop 0
	global_load_lds_dwordx4 v[238:239], off
	v_lshl_add_u64 v[238:239], v[242:243], 0, s[38:39]
	s_mov_b32 m0, s87
	s_nop 0
	global_load_lds_dwordx4 v[238:239], off
	v_lshl_add_u64 v[238:239], v[244:245], 0, s[38:39]
	s_mov_b32 m0, s88
	s_nop 0
	global_load_lds_dwordx4 v[238:239], off
	s_waitcnt vmcnt(8)
	s_waitcnt lgkmcnt(0)
	s_setprio 1
	s_barrier
	v_mfma_f32_16x16x32_bf16 v[60:63], v[128:131], v[204:207], v[60:63]
	v_mfma_f32_16x16x32_bf16 v[56:59], v[136:139], v[204:207], v[56:59]
	v_mfma_f32_16x16x32_bf16 v[44:47], v[128:131], v[212:215], v[44:47]
	v_mfma_f32_16x16x32_bf16 v[40:43], v[136:139], v[212:215], v[40:43]
	v_mfma_f32_16x16x32_bf16 v[28:31], v[128:131], v[220:223], v[28:31]
	v_mfma_f32_16x16x32_bf16 v[24:27], v[136:139], v[220:223], v[24:27]
	v_mfma_f32_16x16x32_bf16 v[12:15], v[128:131], v[230:233], v[12:15]
	v_mfma_f32_16x16x32_bf16 v[8:11], v[136:139], v[230:233], v[8:11]
	v_mfma_f32_16x16x32_bf16 v[60:63], v[132:135], v[208:211], v[60:63]
	v_mfma_f32_16x16x32_bf16 v[56:59], v[140:143], v[208:211], v[56:59]
	v_mfma_f32_16x16x32_bf16 v[44:47], v[132:135], v[216:219], v[44:47]
	v_mfma_f32_16x16x32_bf16 v[40:43], v[140:143], v[216:219], v[40:43]
	v_mfma_f32_16x16x32_bf16 v[28:31], v[132:135], v[224:227], v[28:31]
	v_mfma_f32_16x16x32_bf16 v[24:27], v[140:143], v[224:227], v[24:27]
	v_mfma_f32_16x16x32_bf16 v[12:15], v[132:135], v[234:237], v[12:15]
	v_mfma_f32_16x16x32_bf16 v[8:11], v[140:143], v[234:237], v[8:11]
	v_mfma_f32_16x16x32_bf16 v[52:55], v[188:191], v[204:207], v[52:55]
	v_mfma_f32_16x16x32_bf16 v[48:51], v[196:199], v[204:207], v[48:51]
	v_mfma_f32_16x16x32_bf16 v[36:39], v[188:191], v[212:215], v[36:39]
	v_mfma_f32_16x16x32_bf16 v[32:35], v[196:199], v[212:215], v[32:35]
	v_mfma_f32_16x16x32_bf16 v[20:23], v[188:191], v[220:223], v[20:23]
	v_mfma_f32_16x16x32_bf16 v[16:19], v[196:199], v[220:223], v[16:19]
	v_mfma_f32_16x16x32_bf16 v[4:7], v[188:191], v[230:233], v[4:7]
	v_mfma_f32_16x16x32_bf16 v[0:3], v[196:199], v[230:233], v[0:3]
	v_mfma_f32_16x16x32_bf16 v[52:55], v[192:195], v[208:211], v[52:55]
	v_mfma_f32_16x16x32_bf16 v[48:51], v[200:203], v[208:211], v[48:51]
	v_mfma_f32_16x16x32_bf16 v[36:39], v[192:195], v[216:219], v[36:39]
	v_mfma_f32_16x16x32_bf16 v[32:35], v[200:203], v[216:219], v[32:35]
	v_mfma_f32_16x16x32_bf16 v[20:23], v[192:195], v[224:227], v[20:23]
	v_mfma_f32_16x16x32_bf16 v[16:19], v[200:203], v[224:227], v[16:19]
	v_mfma_f32_16x16x32_bf16 v[4:7], v[192:195], v[234:237], v[4:7]
	v_mfma_f32_16x16x32_bf16 v[0:3], v[200:203], v[234:237], v[0:3]
	s_barrier
	s_setprio 0
	s_add_i32 s69, s69, 2
	s_add_u32 s52, s52, 0x100
	s_addc_u32 s53, s53, 0
	s_add_u32 s67, s67, 0x100
	s_addc_u32 s68, s68, 0
	s_cmp_gt_u32 s69, 13
	s_cbranch_scc0 .LBB0_313
	s_and_b64 vcc, exec, s[40:41]
	s_cbranch_vccz .LBB0_316
	s_barrier

.LBB0_667:
	s_ashr_i32 s23, s22, 31
	s_lshl_b64 s[38:39], s[22:23], 19
	s_add_u32 s38, s26, s38
	s_addc_u32 s39, s27, s39
	s_and_b64 s[40:41], s[6:7], exec
	s_cselect_b32 s23, s39, s45
	s_cselect_b32 s43, s38, s44
	s_ashr_i32 s37, s36, 31
	s_lshl_b64 s[40:41], s[36:37], 19
	s_add_u32 s40, s50, s40
	s_addc_u32 s41, s51, s41
	s_and_b64 s[48:49], s[6:7], exec
	s_cselect_b32 s37, s41, s47
	s_cselect_b32 s92, s40, s46
	s_add_u32 s44, s44, 0x40080
	s_addc_u32 s45, s45, 0
	s_add_u32 s93, s46, 0x100
	s_addc_u32 s94, s47, 0
	s_mov_b32 s95, -2
	s_waitcnt lgkmcnt(0)
	ds_read_b128 v[80:83], v216
	ds_read_b128 v[84:87], v216 offset:1024
	ds_read_b128 v[104:107], v216 offset:2048
	ds_read_b128 v[108:111], v216 offset:3072
	ds_read_b128 v[128:131], v217
	ds_read_b128 v[132:135], v217 offset:1024
	ds_read_b128 v[152:155], v217 offset:2048
	ds_read_b128 v[156:159], v217 offset:3072
	s_add_u32 s46, s44, 0xfffc0080
	s_addc_u32 s47, s45, -1
	s_cmp_eq_u32 s95, 12
	s_cselect_b32 s49, s23, s47
	s_cselect_b32 s48, s43, s46
	s_cselect_b32 s47, s37, s94
	s_cselect_b32 s46, s92, s93
	v_lshl_add_u64 v[224:225], s[44:45], 0, v[194:195]
	s_add_i32 m0, s53, 0xc000
	ds_read_b128 v[160:163], v218
	ds_read_b128 v[164:167], v218 offset:1024
	ds_read_b128 v[168:171], v218 offset:2048
	ds_read_b128 v[172:175], v218 offset:3072
	ds_read_b128 v[176:179], v218 offset:4096
	ds_read_b128 v[180:183], v218 offset:5120
	ds_read_b128 v[208:211], v218 offset:6144
	ds_read_b128 v[220:223], v218 offset:7168
	global_load_lds_dwordx4 v[224:225], off
	v_lshl_add_u64 v[224:225], s[44:45], 0, v[196:197]
	s_add_i32 m0, s53, 0xe000
	s_nop 0
	global_load_lds_dwordx4 v[224:225], off
	s_waitcnt vmcnt(8)
	s_waitcnt lgkmcnt(0)
	s_setprio 1
	s_barrier
	v_mfma_f32_16x16x32_bf16 v[148:151], v[80:83], v[160:163], 0
	v_mfma_f32_16x16x32_bf16 v[144:147], v[104:107], v[160:163], 0
	v_mfma_f32_16x16x32_bf16 v[124:127], v[80:83], v[168:171], 0
	v_mfma_f32_16x16x32_bf16 v[120:123], v[104:107], v[168:171], 0
	v_mfma_f32_16x16x32_bf16 v[100:103], v[80:83], v[176:179], 0
	v_mfma_f32_16x16x32_bf16 v[96:99], v[104:107], v[176:179], 0
	v_mfma_f32_16x16x32_bf16 v[76:79], v[80:83], v[208:211], 0
	v_mfma_f32_16x16x32_bf16 v[72:75], v[104:107], v[208:211], 0
	v_mfma_f32_16x16x32_bf16 v[148:151], v[84:87], v[164:167], v[148:151]
	v_mfma_f32_16x16x32_bf16 v[144:147], v[108:111], v[164:167], v[144:147]
	v_mfma_f32_16x16x32_bf16 v[124:127], v[84:87], v[172:175], v[124:127]
	v_mfma_f32_16x16x32_bf16 v[120:123], v[108:111], v[172:175], v[120:123]
	v_mfma_f32_16x16x32_bf16 v[100:103], v[84:87], v[180:183], v[100:103]
	v_mfma_f32_16x16x32_bf16 v[96:99], v[108:111], v[180:183], v[96:99]
	v_mfma_f32_16x16x32_bf16 v[76:79], v[84:87], v[220:223], v[76:79]
	v_mfma_f32_16x16x32_bf16 v[72:75], v[108:111], v[220:223], v[72:75]
	v_mfma_f32_16x16x32_bf16 v[140:143], v[128:131], v[160:163], 0
	v_mfma_f32_16x16x32_bf16 v[136:139], v[152:155], v[160:163], 0
	v_mfma_f32_16x16x32_bf16 v[116:119], v[128:131], v[168:171], 0
	v_mfma_f32_16x16x32_bf16 v[112:115], v[152:155], v[168:171], 0
	v_mfma_f32_16x16x32_bf16 v[92:95], v[128:131], v[176:179], 0
	v_mfma_f32_16x16x32_bf16 v[88:91], v[152:155], v[176:179], 0
	v_mfma_f32_16x16x32_bf16 v[68:71], v[128:131], v[208:211], 0
	v_mfma_f32_16x16x32_bf16 v[64:67], v[152:155], v[208:211], 0
	v_mfma_f32_16x16x32_bf16 v[140:143], v[132:135], v[164:167], v[140:143]
	v_mfma_f32_16x16x32_bf16 v[136:139], v[156:159], v[164:167], v[136:139]
	v_mfma_f32_16x16x32_bf16 v[116:119], v[132:135], v[172:175], v[116:119]
	v_mfma_f32_16x16x32_bf16 v[112:115], v[156:159], v[172:175], v[112:115]
	v_mfma_f32_16x16x32_bf16 v[92:95], v[132:135], v[180:183], v[92:95]
	v_mfma_f32_16x16x32_bf16 v[88:91], v[156:159], v[180:183], v[88:91]
	v_mfma_f32_16x16x32_bf16 v[68:71], v[132:135], v[220:223], v[68:71]
	v_mfma_f32_16x16x32_bf16 v[64:67], v[156:159], v[220:223], v[64:67]
	s_barrier
	s_setprio 0
	s_add_i32 s83, s78, s52
	v_lshl_add_u64 v[224:225], s[46:47], 0, v[186:187]
	s_mov_b32 m0, s83
	ds_read_b128 v[160:163], v218 offset:16384
	ds_read_b128 v[164:167], v218 offset:17408
	ds_read_b128 v[168:171], v218 offset:18432
	ds_read_b128 v[172:175], v218 offset:19456
	ds_read_b128 v[176:179], v218 offset:20480
	ds_read_b128 v[180:183], v218 offset:21504
	ds_read_b128 v[208:211], v218 offset:22528
	ds_read_b128 v[220:223], v218 offset:23552
	global_load_lds_dwordx4 v[224:225], off
	s_add_i32 m0, s83, 0x2000
	s_add_u32 s96, s46, 0x40000
	v_lshl_add_u64 v[226:227], s[46:47], 0, v[190:191]
	s_addc_u32 s97, s47, 0
	s_add_i32 s83, s79, s52
	global_load_lds_dwordx4 v[226:227], off
	v_lshl_add_u64 v[230:231], s[96:97], 0, v[186:187]
	s_mov_b32 m0, s83
	v_lshl_add_u64 v[232:233], s[48:49], 0, v[188:189]
	global_load_lds_dwordx4 v[230:231], off
	v_lshl_add_u64 v[230:231], s[96:97], 0, v[190:191]
	s_add_i32 m0, s83, 0x2000
	s_nop 0
	global_load_lds_dwordx4 v[230:231], off
	v_lshl_add_u64 v[230:231], s[48:49], 0, v[184:185]
	s_mov_b32 m0, s53
	s_nop 0
	global_load_lds_dwordx4 v[230:231], off
	s_mov_b32 m0, s54
	s_nop 0
	global_load_lds_dwordx4 v[232:233], off
	s_waitcnt vmcnt(8)
	s_waitcnt lgkmcnt(0)
	s_setprio 1
	s_barrier
	v_mfma_f32_16x16x32_bf16 v[60:63], v[80:83], v[160:163], 0
	v_mfma_f32_16x16x32_bf16 v[56:59], v[104:107], v[160:163], 0
	v_mfma_f32_16x16x32_bf16 v[44:47], v[80:83], v[168:171], 0
	v_mfma_f32_16x16x32_bf16 v[40:43], v[104:107], v[168:171], 0
	v_mfma_f32_16x16x32_bf16 v[28:31], v[80:83], v[176:179], 0
	v_mfma_f32_16x16x32_bf16 v[24:27], v[104:107], v[176:179], 0
	v_mfma_f32_16x16x32_bf16 v[12:15], v[80:83], v[208:211], 0
	v_mfma_f32_16x16x32_bf16 v[8:11], v[104:107], v[208:211], 0
	v_mfma_f32_16x16x32_bf16 v[60:63], v[84:87], v[164:167], v[60:63]
	v_mfma_f32_16x16x32_bf16 v[56:59], v[108:111], v[164:167], v[56:59]
	v_mfma_f32_16x16x32_bf16 v[44:47], v[84:87], v[172:175], v[44:47]
	v_mfma_f32_16x16x32_bf16 v[40:43], v[108:111], v[172:175], v[40:43]
	v_mfma_f32_16x16x32_bf16 v[28:31], v[84:87], v[180:183], v[28:31]
	v_mfma_f32_16x16x32_bf16 v[24:27], v[108:111], v[180:183], v[24:27]
	v_mfma_f32_16x16x32_bf16 v[12:15], v[84:87], v[220:223], v[12:15]
	v_mfma_f32_16x16x32_bf16 v[8:11], v[108:111], v[220:223], v[8:11]
	v_mfma_f32_16x16x32_bf16 v[52:55], v[128:131], v[160:163], 0
	v_mfma_f32_16x16x32_bf16 v[48:51], v[152:155], v[160:163], 0
	v_mfma_f32_16x16x32_bf16 v[36:39], v[128:131], v[168:171], 0
	v_mfma_f32_16x16x32_bf16 v[32:35], v[152:155], v[168:171], 0
	v_mfma_f32_16x16x32_bf16 v[20:23], v[128:131], v[176:179], 0
	v_mfma_f32_16x16x32_bf16 v[16:19], v[152:155], v[176:179], 0
	v_mfma_f32_16x16x32_bf16 v[4:7], v[128:131], v[208:211], 0
	v_mfma_f32_16x16x32_bf16 v[0:3], v[152:155], v[208:211], 0
	v_mfma_f32_16x16x32_bf16 v[52:55], v[132:135], v[164:167], v[52:55]
	v_mfma_f32_16x16x32_bf16 v[48:51], v[156:159], v[164:167], v[48:51]
	v_mfma_f32_16x16x32_bf16 v[36:39], v[132:135], v[172:175], v[36:39]
	v_mfma_f32_16x16x32_bf16 v[32:35], v[156:159], v[172:175], v[32:35]
	v_mfma_f32_16x16x32_bf16 v[20:23], v[132:135], v[180:183], v[20:23]
	v_mfma_f32_16x16x32_bf16 v[16:19], v[156:159], v[180:183], v[16:19]
	v_mfma_f32_16x16x32_bf16 v[4:7], v[132:135], v[220:223], v[4:7]
	v_mfma_f32_16x16x32_bf16 v[0:3], v[156:159], v[220:223], v[0:3]
	s_barrier
	s_setprio 0
	s_add_i32 s83, 0, 0x18000
	s_add_i32 s96, 0, 0x1c000
	v_add_u32_e32 v108, s83, v213
	v_add_u32_e32 v156, s96, v213
	ds_read_b128 v[80:83], v108
	ds_read_b128 v[84:87], v108 offset:1024
	ds_read_b128 v[104:107], v108 offset:2048
	ds_read_b128 v[108:111], v108 offset:3072
	ds_read_b128 v[128:131], v156
	ds_read_b128 v[132:135], v156 offset:1024
	ds_read_b128 v[152:155], v156 offset:2048
	ds_read_b128 v[156:159], v156 offset:3072
	s_add_u32 s48, s48, 0x40000
	s_addc_u32 s49, s49, 0
	s_mov_b32 m0, s55
	v_lshl_add_u64 v[234:235], s[48:49], 0, v[184:185]
	ds_read_b128 v[160:163], v218 offset:32768
	ds_read_b128 v[164:167], v218 offset:33792
	ds_read_b128 v[168:171], v218 offset:34816
	ds_read_b128 v[172:175], v218 offset:35840
	ds_read_b128 v[176:179], v218 offset:36864
	ds_read_b128 v[180:183], v218 offset:37888
	ds_read_b128 v[208:211], v218 offset:38912
	ds_read_b128 v[220:223], v218 offset:39936
	global_load_lds_dwordx4 v[234:235], off
	v_lshl_add_u64 v[234:235], s[48:49], 0, v[188:189]
	s_mov_b32 m0, s56
	s_nop 0
	global_load_lds_dwordx4 v[234:235], off
	s_waitcnt vmcnt(8)
	s_waitcnt lgkmcnt(0)
	s_setprio 1
	s_barrier
	v_mfma_f32_16x16x32_bf16 v[148:151], v[80:83], v[160:163], v[148:151]
	v_mfma_f32_16x16x32_bf16 v[144:147], v[104:107], v[160:163], v[144:147]
	v_mfma_f32_16x16x32_bf16 v[124:127], v[80:83], v[168:171], v[124:127]
	v_mfma_f32_16x16x32_bf16 v[120:123], v[104:107], v[168:171], v[120:123]
	v_mfma_f32_16x16x32_bf16 v[100:103], v[80:83], v[176:179], v[100:103]
	v_mfma_f32_16x16x32_bf16 v[96:99], v[104:107], v[176:179], v[96:99]
	v_mfma_f32_16x16x32_bf16 v[76:79], v[80:83], v[208:211], v[76:79]
	v_mfma_f32_16x16x32_bf16 v[72:75], v[104:107], v[208:211], v[72:75]
	v_mfma_f32_16x16x32_bf16 v[148:151], v[84:87], v[164:167], v[148:151]
	v_mfma_f32_16x16x32_bf16 v[144:147], v[108:111], v[164:167], v[144:147]
	v_mfma_f32_16x16x32_bf16 v[124:127], v[84:87], v[172:175], v[124:127]
	v_mfma_f32_16x16x32_bf16 v[120:123], v[108:111], v[172:175], v[120:123]
	v_mfma_f32_16x16x32_bf16 v[100:103], v[84:87], v[180:183], v[100:103]
	v_mfma_f32_16x16x32_bf16 v[96:99], v[108:111], v[180:183], v[96:99]
	v_mfma_f32_16x16x32_bf16 v[76:79], v[84:87], v[220:223], v[76:79]
	v_mfma_f32_16x16x32_bf16 v[72:75], v[108:111], v[220:223], v[72:75]
	v_mfma_f32_16x16x32_bf16 v[140:143], v[128:131], v[160:163], v[140:143]
	v_mfma_f32_16x16x32_bf16 v[136:139], v[152:155], v[160:163], v[136:139]
	v_mfma_f32_16x16x32_bf16 v[116:119], v[128:131], v[168:171], v[116:119]
	v_mfma_f32_16x16x32_bf16 v[112:115], v[152:155], v[168:171], v[112:115]
	v_mfma_f32_16x16x32_bf16 v[92:95], v[128:131], v[176:179], v[92:95]
	v_mfma_f32_16x16x32_bf16 v[88:91], v[152:155], v[176:179], v[88:91]
	v_mfma_f32_16x16x32_bf16 v[68:71], v[128:131], v[208:211], v[68:71]
	v_mfma_f32_16x16x32_bf16 v[64:67], v[152:155], v[208:211], v[64:67]
	v_mfma_f32_16x16x32_bf16 v[140:143], v[132:135], v[164:167], v[140:143]
	v_mfma_f32_16x16x32_bf16 v[136:139], v[156:159], v[164:167], v[136:139]
	v_mfma_f32_16x16x32_bf16 v[116:119], v[132:135], v[172:175], v[116:119]
	v_mfma_f32_16x16x32_bf16 v[112:115], v[156:159], v[172:175], v[112:115]
	v_mfma_f32_16x16x32_bf16 v[92:95], v[132:135], v[180:183], v[92:95]
	v_mfma_f32_16x16x32_bf16 v[88:91], v[156:159], v[180:183], v[88:91]
	v_mfma_f32_16x16x32_bf16 v[68:71], v[132:135], v[220:223], v[68:71]
	v_mfma_f32_16x16x32_bf16 v[64:67], v[156:159], v[220:223], v[64:67]
	s_barrier
	s_setprio 0
	s_add_i32 s48, s83, s52
	v_lshl_add_u64 v[224:225], v[224:225], 0, s[18:19]
	s_mov_b32 m0, s48
	ds_read_b128 v[160:163], v218 offset:49152
	ds_read_b128 v[164:167], v218 offset:50176
	ds_read_b128 v[168:171], v218 offset:51200
	ds_read_b128 v[172:175], v218 offset:52224
	ds_read_b128 v[176:179], v218 offset:53248
	ds_read_b128 v[180:183], v218 offset:54272
	ds_read_b128 v[208:211], v218 offset:55296
	ds_read_b128 v[220:223], v218 offset:56320
	global_load_lds_dwordx4 v[224:225], off
	s_add_i32 m0, s48, 0x2000
	s_add_u32 s46, s46, 0x40080
	v_lshl_add_u64 v[224:225], v[226:227], 0, s[18:19]
	s_addc_u32 s47, s47, 0
	s_add_i32 s48, s96, s52
	global_load_lds_dwordx4 v[224:225], off
	v_lshl_add_u64 v[224:225], s[46:47], 0, v[186:187]
	s_mov_b32 m0, s48
	s_nop 0
	global_load_lds_dwordx4 v[224:225], off
	v_lshl_add_u64 v[224:225], s[46:47], 0, v[190:191]
	s_add_i32 m0, s48, 0x2000
	s_nop 0
	global_load_lds_dwordx4 v[224:225], off
	v_lshl_add_u64 v[224:225], v[230:231], 0, s[18:19]
	s_mov_b32 m0, s68
	s_nop 0
	global_load_lds_dwordx4 v[224:225], off
	v_lshl_add_u64 v[224:225], v[232:233], 0, s[18:19]
	s_mov_b32 m0, s69
	s_nop 0
	global_load_lds_dwordx4 v[224:225], off
	s_waitcnt vmcnt(8)
	s_waitcnt lgkmcnt(0)
	s_setprio 1
	s_barrier
	v_mfma_f32_16x16x32_bf16 v[60:63], v[80:83], v[160:163], v[60:63]
	v_mfma_f32_16x16x32_bf16 v[56:59], v[104:107], v[160:163], v[56:59]
	v_mfma_f32_16x16x32_bf16 v[44:47], v[80:83], v[168:171], v[44:47]
	v_mfma_f32_16x16x32_bf16 v[40:43], v[104:107], v[168:171], v[40:43]
	v_mfma_f32_16x16x32_bf16 v[28:31], v[80:83], v[176:179], v[28:31]
	v_mfma_f32_16x16x32_bf16 v[24:27], v[104:107], v[176:179], v[24:27]
	v_mfma_f32_16x16x32_bf16 v[12:15], v[80:83], v[208:211], v[12:15]
	v_mfma_f32_16x16x32_bf16 v[8:11], v[104:107], v[208:211], v[8:11]
	v_mfma_f32_16x16x32_bf16 v[60:63], v[84:87], v[164:167], v[60:63]
	v_mfma_f32_16x16x32_bf16 v[56:59], v[108:111], v[164:167], v[56:59]
	v_mfma_f32_16x16x32_bf16 v[44:47], v[84:87], v[172:175], v[44:47]
	v_mfma_f32_16x16x32_bf16 v[40:43], v[108:111], v[172:175], v[40:43]
	v_mfma_f32_16x16x32_bf16 v[28:31], v[84:87], v[180:183], v[28:31]
	v_mfma_f32_16x16x32_bf16 v[24:27], v[108:111], v[180:183], v[24:27]
	v_mfma_f32_16x16x32_bf16 v[12:15], v[84:87], v[220:223], v[12:15]
	v_mfma_f32_16x16x32_bf16 v[8:11], v[108:111], v[220:223], v[8:11]
	v_mfma_f32_16x16x32_bf16 v[52:55], v[128:131], v[160:163], v[52:55]
	v_mfma_f32_16x16x32_bf16 v[48:51], v[152:155], v[160:163], v[48:51]
	v_mfma_f32_16x16x32_bf16 v[36:39], v[128:131], v[168:171], v[36:39]
	v_mfma_f32_16x16x32_bf16 v[32:35], v[152:155], v[168:171], v[32:35]
	v_mfma_f32_16x16x32_bf16 v[20:23], v[128:131], v[176:179], v[20:23]
	v_mfma_f32_16x16x32_bf16 v[16:19], v[152:155], v[176:179], v[16:19]
	v_mfma_f32_16x16x32_bf16 v[4:7], v[128:131], v[208:211], v[4:7]
	v_mfma_f32_16x16x32_bf16 v[0:3], v[152:155], v[208:211], v[0:3]
	v_mfma_f32_16x16x32_bf16 v[52:55], v[132:135], v[164:167], v[52:55]
	v_mfma_f32_16x16x32_bf16 v[48:51], v[156:159], v[164:167], v[48:51]
	v_mfma_f32_16x16x32_bf16 v[36:39], v[132:135], v[172:175], v[36:39]
	v_mfma_f32_16x16x32_bf16 v[32:35], v[156:159], v[172:175], v[32:35]
	v_mfma_f32_16x16x32_bf16 v[20:23], v[132:135], v[180:183], v[20:23]
	v_mfma_f32_16x16x32_bf16 v[16:19], v[156:159], v[180:183], v[16:19]
	v_mfma_f32_16x16x32_bf16 v[4:7], v[132:135], v[220:223], v[4:7]
	v_mfma_f32_16x16x32_bf16 v[0:3], v[156:159], v[220:223], v[0:3]
	s_barrier
	s_setprio 0
	s_add_i32 s95, s95, 2
	s_add_u32 s44, s44, 0x100
	s_addc_u32 s45, s45, 0
	s_add_u32 s93, s93, 0x100
	s_addc_u32 s94, s94, 0
	s_cmp_gt_u32 s95, 13
.LBB0_668:
	ds_read_b128 v[80:83], v216
	ds_read_b128 v[84:87], v216 offset:1024
	ds_read_b128 v[104:107], v216 offset:2048
	ds_read_b128 v[108:111], v216 offset:3072
	ds_read_b128 v[128:131], v217
	ds_read_b128 v[132:135], v217 offset:1024
	ds_read_b128 v[152:155], v217 offset:2048
	ds_read_b128 v[156:159], v217 offset:3072
	s_add_u32 s46, s44, 0xfffc0080
	s_addc_u32 s47, s45, -1
	s_cmp_eq_u32 s95, 12
	s_cselect_b32 s49, s23, s47
	s_cselect_b32 s48, s43, s46
	s_cselect_b32 s47, s37, s94
	s_cselect_b32 s46, s92, s93
	v_lshl_add_u64 v[224:225], s[44:45], 0, v[194:195]
	s_add_i32 m0, s53, 0xc000
	ds_read_b128 v[160:163], v218
	ds_read_b128 v[164:167], v218 offset:1024
	ds_read_b128 v[168:171], v218 offset:2048
	ds_read_b128 v[172:175], v218 offset:3072
	ds_read_b128 v[176:179], v218 offset:4096
	ds_read_b128 v[180:183], v218 offset:5120
	ds_read_b128 v[208:211], v218 offset:6144
	ds_read_b128 v[220:223], v218 offset:7168
	global_load_lds_dwordx4 v[224:225], off
	v_lshl_add_u64 v[224:225], s[44:45], 0, v[196:197]
	s_add_i32 m0, s53, 0xe000
	s_nop 0
	global_load_lds_dwordx4 v[224:225], off
	s_waitcnt vmcnt(8)
	s_waitcnt lgkmcnt(0)
	s_setprio 1
	s_barrier
	v_mfma_f32_16x16x32_bf16 v[148:151], v[80:83], v[160:163], v[148:151]
	v_mfma_f32_16x16x32_bf16 v[144:147], v[104:107], v[160:163], v[144:147]
	v_mfma_f32_16x16x32_bf16 v[124:127], v[80:83], v[168:171], v[124:127]
	v_mfma_f32_16x16x32_bf16 v[120:123], v[104:107], v[168:171], v[120:123]
	v_mfma_f32_16x16x32_bf16 v[100:103], v[80:83], v[176:179], v[100:103]
	v_mfma_f32_16x16x32_bf16 v[96:99], v[104:107], v[176:179], v[96:99]
	v_mfma_f32_16x16x32_bf16 v[76:79], v[80:83], v[208:211], v[76:79]
	v_mfma_f32_16x16x32_bf16 v[72:75], v[104:107], v[208:211], v[72:75]
	v_mfma_f32_16x16x32_bf16 v[148:151], v[84:87], v[164:167], v[148:151]
	v_mfma_f32_16x16x32_bf16 v[144:147], v[108:111], v[164:167], v[144:147]
	v_mfma_f32_16x16x32_bf16 v[124:127], v[84:87], v[172:175], v[124:127]
	v_mfma_f32_16x16x32_bf16 v[120:123], v[108:111], v[172:175], v[120:123]
	v_mfma_f32_16x16x32_bf16 v[100:103], v[84:87], v[180:183], v[100:103]
	v_mfma_f32_16x16x32_bf16 v[96:99], v[108:111], v[180:183], v[96:99]
	v_mfma_f32_16x16x32_bf16 v[76:79], v[84:87], v[220:223], v[76:79]
	v_mfma_f32_16x16x32_bf16 v[72:75], v[108:111], v[220:223], v[72:75]
	v_mfma_f32_16x16x32_bf16 v[140:143], v[128:131], v[160:163], v[140:143]
	v_mfma_f32_16x16x32_bf16 v[136:139], v[152:155], v[160:163], v[136:139]
	v_mfma_f32_16x16x32_bf16 v[116:119], v[128:131], v[168:171], v[116:119]
	v_mfma_f32_16x16x32_bf16 v[112:115], v[152:155], v[168:171], v[112:115]
	v_mfma_f32_16x16x32_bf16 v[92:95], v[128:131], v[176:179], v[92:95]
	v_mfma_f32_16x16x32_bf16 v[88:91], v[152:155], v[176:179], v[88:91]
	v_mfma_f32_16x16x32_bf16 v[68:71], v[128:131], v[208:211], v[68:71]
	v_mfma_f32_16x16x32_bf16 v[64:67], v[152:155], v[208:211], v[64:67]
	v_mfma_f32_16x16x32_bf16 v[140:143], v[132:135], v[164:167], v[140:143]
	v_mfma_f32_16x16x32_bf16 v[136:139], v[156:159], v[164:167], v[136:139]
	v_mfma_f32_16x16x32_bf16 v[116:119], v[132:135], v[172:175], v[116:119]
	v_mfma_f32_16x16x32_bf16 v[112:115], v[156:159], v[172:175], v[112:115]
	v_mfma_f32_16x16x32_bf16 v[92:95], v[132:135], v[180:183], v[92:95]
	v_mfma_f32_16x16x32_bf16 v[88:91], v[156:159], v[180:183], v[88:91]
	v_mfma_f32_16x16x32_bf16 v[68:71], v[132:135], v[220:223], v[68:71]
	v_mfma_f32_16x16x32_bf16 v[64:67], v[156:159], v[220:223], v[64:67]
	s_barrier
	s_setprio 0
	s_add_i32 s83, s78, s52
	v_lshl_add_u64 v[224:225], s[46:47], 0, v[186:187]
	s_mov_b32 m0, s83
	ds_read_b128 v[160:163], v218 offset:16384
	ds_read_b128 v[164:167], v218 offset:17408
	ds_read_b128 v[168:171], v218 offset:18432
	ds_read_b128 v[172:175], v218 offset:19456
	ds_read_b128 v[176:179], v218 offset:20480
	ds_read_b128 v[180:183], v218 offset:21504
	ds_read_b128 v[208:211], v218 offset:22528
	ds_read_b128 v[220:223], v218 offset:23552
	global_load_lds_dwordx4 v[224:225], off
	s_add_i32 m0, s83, 0x2000
	s_add_u32 s96, s46, 0x40000
	v_lshl_add_u64 v[226:227], s[46:47], 0, v[190:191]
	s_addc_u32 s97, s47, 0
	s_add_i32 s83, s79, s52
	global_load_lds_dwordx4 v[226:227], off
	v_lshl_add_u64 v[230:231], s[96:97], 0, v[186:187]
	s_mov_b32 m0, s83
	v_lshl_add_u64 v[232:233], s[48:49], 0, v[188:189]
	global_load_lds_dwordx4 v[230:231], off
	v_lshl_add_u64 v[230:231], s[96:97], 0, v[190:191]
	s_add_i32 m0, s83, 0x2000
	s_nop 0
	global_load_lds_dwordx4 v[230:231], off
	v_lshl_add_u64 v[230:231], s[48:49], 0, v[184:185]
	s_mov_b32 m0, s53
	s_nop 0
	global_load_lds_dwordx4 v[230:231], off
	s_mov_b32 m0, s54
	s_nop 0
	global_load_lds_dwordx4 v[232:233], off
	s_waitcnt vmcnt(8)
	s_waitcnt lgkmcnt(0)
	s_setprio 1
	s_barrier
	v_mfma_f32_16x16x32_bf16 v[60:63], v[80:83], v[160:163], v[60:63]
	v_mfma_f32_16x16x32_bf16 v[56:59], v[104:107], v[160:163], v[56:59]
	v_mfma_f32_16x16x32_bf16 v[44:47], v[80:83], v[168:171], v[44:47]
	v_mfma_f32_16x16x32_bf16 v[40:43], v[104:107], v[168:171], v[40:43]
	v_mfma_f32_16x16x32_bf16 v[28:31], v[80:83], v[176:179], v[28:31]
	v_mfma_f32_16x16x32_bf16 v[24:27], v[104:107], v[176:179], v[24:27]
	v_mfma_f32_16x16x32_bf16 v[12:15], v[80:83], v[208:211], v[12:15]
	v_mfma_f32_16x16x32_bf16 v[8:11], v[104:107], v[208:211], v[8:11]
	v_mfma_f32_16x16x32_bf16 v[60:63], v[84:87], v[164:167], v[60:63]
	v_mfma_f32_16x16x32_bf16 v[56:59], v[108:111], v[164:167], v[56:59]
	v_mfma_f32_16x16x32_bf16 v[44:47], v[84:87], v[172:175], v[44:47]
	v_mfma_f32_16x16x32_bf16 v[40:43], v[108:111], v[172:175], v[40:43]
	v_mfma_f32_16x16x32_bf16 v[28:31], v[84:87], v[180:183], v[28:31]
	v_mfma_f32_16x16x32_bf16 v[24:27], v[108:111], v[180:183], v[24:27]
	v_mfma_f32_16x16x32_bf16 v[12:15], v[84:87], v[220:223], v[12:15]
	v_mfma_f32_16x16x32_bf16 v[8:11], v[108:111], v[220:223], v[8:11]
	v_mfma_f32_16x16x32_bf16 v[52:55], v[128:131], v[160:163], v[52:55]
	v_mfma_f32_16x16x32_bf16 v[48:51], v[152:155], v[160:163], v[48:51]
	v_mfma_f32_16x16x32_bf16 v[36:39], v[128:131], v[168:171], v[36:39]
	v_mfma_f32_16x16x32_bf16 v[32:35], v[152:155], v[168:171], v[32:35]
	v_mfma_f32_16x16x32_bf16 v[20:23], v[128:131], v[176:179], v[20:23]
	v_mfma_f32_16x16x32_bf16 v[16:19], v[152:155], v[176:179], v[16:19]
	v_mfma_f32_16x16x32_bf16 v[4:7], v[128:131], v[208:211], v[4:7]
	v_mfma_f32_16x16x32_bf16 v[0:3], v[152:155], v[208:211], v[0:3]
	v_mfma_f32_16x16x32_bf16 v[52:55], v[132:135], v[164:167], v[52:55]
	v_mfma_f32_16x16x32_bf16 v[48:51], v[156:159], v[164:167], v[48:51]
	v_mfma_f32_16x16x32_bf16 v[36:39], v[132:135], v[172:175], v[36:39]
	v_mfma_f32_16x16x32_bf16 v[32:35], v[156:159], v[172:175], v[32:35]
	v_mfma_f32_16x16x32_bf16 v[20:23], v[132:135], v[180:183], v[20:23]
	v_mfma_f32_16x16x32_bf16 v[16:19], v[156:159], v[180:183], v[16:19]
	v_mfma_f32_16x16x32_bf16 v[4:7], v[132:135], v[220:223], v[4:7]
	v_mfma_f32_16x16x32_bf16 v[0:3], v[156:159], v[220:223], v[0:3]
	s_barrier
	s_setprio 0
	s_add_i32 s83, 0, 0x18000
	s_add_i32 s96, 0, 0x1c000
	v_add_u32_e32 v108, s83, v213
	v_add_u32_e32 v156, s96, v213
	ds_read_b128 v[80:83], v108
	ds_read_b128 v[84:87], v108 offset:1024
	ds_read_b128 v[104:107], v108 offset:2048
	ds_read_b128 v[108:111], v108 offset:3072
	ds_read_b128 v[128:131], v156
	ds_read_b128 v[132:135], v156 offset:1024
	ds_read_b128 v[152:155], v156 offset:2048
	ds_read_b128 v[156:159], v156 offset:3072
	s_add_u32 s48, s48, 0x40000
	s_addc_u32 s49, s49, 0
	s_mov_b32 m0, s55
	v_lshl_add_u64 v[234:235], s[48:49], 0, v[184:185]
	ds_read_b128 v[160:163], v218 offset:32768
	ds_read_b128 v[164:167], v218 offset:33792
	ds_read_b128 v[168:171], v218 offset:34816
	ds_read_b128 v[172:175], v218 offset:35840
	ds_read_b128 v[176:179], v218 offset:36864
	ds_read_b128 v[180:183], v218 offset:37888
	ds_read_b128 v[208:211], v218 offset:38912
	ds_read_b128 v[220:223], v218 offset:39936
	global_load_lds_dwordx4 v[234:235], off
	v_lshl_add_u64 v[234:235], s[48:49], 0, v[188:189]
	s_mov_b32 m0, s56
	s_nop 0
	global_load_lds_dwordx4 v[234:235], off
	s_waitcnt vmcnt(8)
	s_waitcnt lgkmcnt(0)
	s_setprio 1
	s_barrier
	v_mfma_f32_16x16x32_bf16 v[148:151], v[80:83], v[160:163], v[148:151]
	v_mfma_f32_16x16x32_bf16 v[144:147], v[104:107], v[160:163], v[144:147]
	v_mfma_f32_16x16x32_bf16 v[124:127], v[80:83], v[168:171], v[124:127]
	v_mfma_f32_16x16x32_bf16 v[120:123], v[104:107], v[168:171], v[120:123]
	v_mfma_f32_16x16x32_bf16 v[100:103], v[80:83], v[176:179], v[100:103]
	v_mfma_f32_16x16x32_bf16 v[96:99], v[104:107], v[176:179], v[96:99]
	v_mfma_f32_16x16x32_bf16 v[76:79], v[80:83], v[208:211], v[76:79]
	v_mfma_f32_16x16x32_bf16 v[72:75], v[104:107], v[208:211], v[72:75]
	v_mfma_f32_16x16x32_bf16 v[148:151], v[84:87], v[164:167], v[148:151]
	v_mfma_f32_16x16x32_bf16 v[144:147], v[108:111], v[164:167], v[144:147]
	v_mfma_f32_16x16x32_bf16 v[124:127], v[84:87], v[172:175], v[124:127]
	v_mfma_f32_16x16x32_bf16 v[120:123], v[108:111], v[172:175], v[120:123]
	v_mfma_f32_16x16x32_bf16 v[100:103], v[84:87], v[180:183], v[100:103]
	v_mfma_f32_16x16x32_bf16 v[96:99], v[108:111], v[180:183], v[96:99]
	v_mfma_f32_16x16x32_bf16 v[76:79], v[84:87], v[220:223], v[76:79]
	v_mfma_f32_16x16x32_bf16 v[72:75], v[108:111], v[220:223], v[72:75]
	v_mfma_f32_16x16x32_bf16 v[140:143], v[128:131], v[160:163], v[140:143]
	v_mfma_f32_16x16x32_bf16 v[136:139], v[152:155], v[160:163], v[136:139]
	v_mfma_f32_16x16x32_bf16 v[116:119], v[128:131], v[168:171], v[116:119]
	v_mfma_f32_16x16x32_bf16 v[112:115], v[152:155], v[168:171], v[112:115]
	v_mfma_f32_16x16x32_bf16 v[92:95], v[128:131], v[176:179], v[92:95]
	v_mfma_f32_16x16x32_bf16 v[88:91], v[152:155], v[176:179], v[88:91]
	v_mfma_f32_16x16x32_bf16 v[68:71], v[128:131], v[208:211], v[68:71]
	v_mfma_f32_16x16x32_bf16 v[64:67], v[152:155], v[208:211], v[64:67]
	v_mfma_f32_16x16x32_bf16 v[140:143], v[132:135], v[164:167], v[140:143]
	v_mfma_f32_16x16x32_bf16 v[136:139], v[156:159], v[164:167], v[136:139]
	v_mfma_f32_16x16x32_bf16 v[116:119], v[132:135], v[172:175], v[116:119]
	v_mfma_f32_16x16x32_bf16 v[112:115], v[156:159], v[172:175], v[112:115]
	v_mfma_f32_16x16x32_bf16 v[92:95], v[132:135], v[180:183], v[92:95]
	v_mfma_f32_16x16x32_bf16 v[88:91], v[156:159], v[180:183], v[88:91]
	v_mfma_f32_16x16x32_bf16 v[68:71], v[132:135], v[220:223], v[68:71]
	v_mfma_f32_16x16x32_bf16 v[64:67], v[156:159], v[220:223], v[64:67]
	s_barrier
	s_setprio 0
	s_add_i32 s48, s83, s52
	v_lshl_add_u64 v[224:225], v[224:225], 0, s[18:19]
	s_mov_b32 m0, s48
	ds_read_b128 v[160:163], v218 offset:49152
	ds_read_b128 v[164:167], v218 offset:50176
	ds_read_b128 v[168:171], v218 offset:51200
	ds_read_b128 v[172:175], v218 offset:52224
	ds_read_b128 v[176:179], v218 offset:53248
	ds_read_b128 v[180:183], v218 offset:54272
	ds_read_b128 v[208:211], v218 offset:55296
	ds_read_b128 v[220:223], v218 offset:56320
	global_load_lds_dwordx4 v[224:225], off
	s_add_i32 m0, s48, 0x2000
	s_add_u32 s46, s46, 0x40080
	v_lshl_add_u64 v[224:225], v[226:227], 0, s[18:19]
	s_addc_u32 s47, s47, 0
	s_add_i32 s48, s96, s52
	global_load_lds_dwordx4 v[224:225], off
	v_lshl_add_u64 v[224:225], s[46:47], 0, v[186:187]
	s_mov_b32 m0, s48
	s_nop 0
	global_load_lds_dwordx4 v[224:225], off
	v_lshl_add_u64 v[224:225], s[46:47], 0, v[190:191]
	s_add_i32 m0, s48, 0x2000
	s_nop 0
	global_load_lds_dwordx4 v[224:225], off
	v_lshl_add_u64 v[224:225], v[230:231], 0, s[18:19]
	s_mov_b32 m0, s68
	s_nop 0
	global_load_lds_dwordx4 v[224:225], off
	v_lshl_add_u64 v[224:225], v[232:233], 0, s[18:19]
	s_mov_b32 m0, s69
	s_nop 0
	global_load_lds_dwordx4 v[224:225], off
	s_waitcnt vmcnt(8)
	s_waitcnt lgkmcnt(0)
	s_setprio 1
	s_barrier
	v_mfma_f32_16x16x32_bf16 v[60:63], v[80:83], v[160:163], v[60:63]
	v_mfma_f32_16x16x32_bf16 v[56:59], v[104:107], v[160:163], v[56:59]
	v_mfma_f32_16x16x32_bf16 v[44:47], v[80:83], v[168:171], v[44:47]
	v_mfma_f32_16x16x32_bf16 v[40:43], v[104:107], v[168:171], v[40:43]
	v_mfma_f32_16x16x32_bf16 v[28:31], v[80:83], v[176:179], v[28:31]
	v_mfma_f32_16x16x32_bf16 v[24:27], v[104:107], v[176:179], v[24:27]
	v_mfma_f32_16x16x32_bf16 v[12:15], v[80:83], v[208:211], v[12:15]
	v_mfma_f32_16x16x32_bf16 v[8:11], v[104:107], v[208:211], v[8:11]
	v_mfma_f32_16x16x32_bf16 v[60:63], v[84:87], v[164:167], v[60:63]
	v_mfma_f32_16x16x32_bf16 v[56:59], v[108:111], v[164:167], v[56:59]
	v_mfma_f32_16x16x32_bf16 v[44:47], v[84:87], v[172:175], v[44:47]
	v_mfma_f32_16x16x32_bf16 v[40:43], v[108:111], v[172:175], v[40:43]
	v_mfma_f32_16x16x32_bf16 v[28:31], v[84:87], v[180:183], v[28:31]
	v_mfma_f32_16x16x32_bf16 v[24:27], v[108:111], v[180:183], v[24:27]
	v_mfma_f32_16x16x32_bf16 v[12:15], v[84:87], v[220:223], v[12:15]
	v_mfma_f32_16x16x32_bf16 v[8:11], v[108:111], v[220:223], v[8:11]
	v_mfma_f32_16x16x32_bf16 v[52:55], v[128:131], v[160:163], v[52:55]
	v_mfma_f32_16x16x32_bf16 v[48:51], v[152:155], v[160:163], v[48:51]
	v_mfma_f32_16x16x32_bf16 v[36:39], v[128:131], v[168:171], v[36:39]
	v_mfma_f32_16x16x32_bf16 v[32:35], v[152:155], v[168:171], v[32:35]
	v_mfma_f32_16x16x32_bf16 v[20:23], v[128:131], v[176:179], v[20:23]
	v_mfma_f32_16x16x32_bf16 v[16:19], v[152:155], v[176:179], v[16:19]
	v_mfma_f32_16x16x32_bf16 v[4:7], v[128:131], v[208:211], v[4:7]
	v_mfma_f32_16x16x32_bf16 v[0:3], v[152:155], v[208:211], v[0:3]
	v_mfma_f32_16x16x32_bf16 v[52:55], v[132:135], v[164:167], v[52:55]
	v_mfma_f32_16x16x32_bf16 v[48:51], v[156:159], v[164:167], v[48:51]
	v_mfma_f32_16x16x32_bf16 v[36:39], v[132:135], v[172:175], v[36:39]
	v_mfma_f32_16x16x32_bf16 v[32:35], v[156:159], v[172:175], v[32:35]
	v_mfma_f32_16x16x32_bf16 v[20:23], v[132:135], v[180:183], v[20:23]
	v_mfma_f32_16x16x32_bf16 v[16:19], v[156:159], v[180:183], v[16:19]
	v_mfma_f32_16x16x32_bf16 v[4:7], v[132:135], v[220:223], v[4:7]
	v_mfma_f32_16x16x32_bf16 v[0:3], v[156:159], v[220:223], v[0:3]
	s_barrier
	s_setprio 0
	s_add_i32 s95, s95, 2
	s_add_u32 s44, s44, 0x100
	s_addc_u32 s45, s45, 0
	s_add_u32 s93, s93, 0x100
	s_addc_u32 s94, s94, 0
	s_cmp_gt_u32 s95, 13
	s_cbranch_scc0 .LBB0_668
	s_and_b64 vcc, exec, s[20:21]
	s_cbranch_vccz .LBB0_671
	s_barrier

.LBB0_758:
	s_ashr_i32 s19, s18, 31
	s_lshl_b64 s[20:21], s[18:19], 19
	s_add_u32 s20, s62, s20
	s_addc_u32 s21, s63, s21
	s_and_b64 s[22:23], s[4:5], exec
	s_cselect_b32 s19, s21, s39
	s_cselect_b32 s57, s20, s38
	s_ashr_i32 s11, s10, 31
	s_lshl_b64 s[22:23], s[10:11], 19
	s_add_u32 s22, s40, s22
	s_addc_u32 s23, s41, s23
	s_and_b64 s[4:5], s[4:5], exec
	s_cselect_b32 s11, s23, s37
	s_cselect_b32 s58, s22, s36
	s_add_u32 s4, s38, 0x40080
	s_addc_u32 s5, s39, 0
	s_add_u32 s59, s36, 0x100
	s_addc_u32 s66, s37, 0
	s_mov_b32 s67, -2
	ds_read_b128 v[146:149], v172
	ds_read_b128 v[166:169], v172 offset:1024
	ds_read_b128 v[176:179], v172 offset:2048
	ds_read_b128 v[180:183], v172 offset:3072
	ds_read_b128 v[184:187], v173
	ds_read_b128 v[188:191], v173 offset:1024
	ds_read_b128 v[192:195], v173 offset:2048
	ds_read_b128 v[196:199], v173 offset:3072
	s_add_u32 s36, s4, 0xfffc0080
	s_addc_u32 s37, s5, -1
	s_cmp_eq_u32 s67, 12
	s_cselect_b32 s39, s19, s37
	s_cselect_b32 s38, s57, s36
	s_cselect_b32 s37, s11, s66
	s_cselect_b32 s36, s58, s59
	v_lshl_add_u64 v[150:151], s[4:5], 0, v[138:139]
	s_add_i32 m0, s27, 0xc000
	ds_read_b128 v[200:203], v174
	ds_read_b128 v[204:207], v174 offset:1024
	ds_read_b128 v[208:211], v174 offset:2048
	ds_read_b128 v[212:215], v174 offset:3072
	ds_read_b128 v[216:219], v174 offset:4096
	ds_read_b128 v[220:223], v174 offset:5120
	ds_read_b128 v[224:227], v174 offset:6144
	ds_read_b128 v[230:233], v174 offset:7168
	global_load_lds_dwordx4 v[150:151], off
	v_lshl_add_u64 v[150:151], s[4:5], 0, v[140:141]
	s_add_i32 m0, s27, 0xe000
	s_nop 0
	global_load_lds_dwordx4 v[150:151], off
	s_waitcnt vmcnt(8)
	s_waitcnt lgkmcnt(0)
	s_setprio 1
	s_barrier
	v_mfma_f32_16x16x32_bf16 v[124:127], v[146:149], v[200:203], 0
	v_mfma_f32_16x16x32_bf16 v[120:123], v[176:179], v[200:203], 0
	v_mfma_f32_16x16x32_bf16 v[108:111], v[146:149], v[208:211], 0
	v_mfma_f32_16x16x32_bf16 v[104:107], v[176:179], v[208:211], 0
	v_mfma_f32_16x16x32_bf16 v[92:95], v[146:149], v[216:219], 0
	v_mfma_f32_16x16x32_bf16 v[88:91], v[176:179], v[216:219], 0
	v_mfma_f32_16x16x32_bf16 v[76:79], v[146:149], v[224:227], 0
	v_mfma_f32_16x16x32_bf16 v[72:75], v[176:179], v[224:227], 0
	v_mfma_f32_16x16x32_bf16 v[124:127], v[166:169], v[204:207], v[124:127]
	v_mfma_f32_16x16x32_bf16 v[120:123], v[180:183], v[204:207], v[120:123]
	v_mfma_f32_16x16x32_bf16 v[108:111], v[166:169], v[212:215], v[108:111]
	v_mfma_f32_16x16x32_bf16 v[104:107], v[180:183], v[212:215], v[104:107]
	v_mfma_f32_16x16x32_bf16 v[92:95], v[166:169], v[220:223], v[92:95]
	v_mfma_f32_16x16x32_bf16 v[88:91], v[180:183], v[220:223], v[88:91]
	v_mfma_f32_16x16x32_bf16 v[76:79], v[166:169], v[230:233], v[76:79]
	v_mfma_f32_16x16x32_bf16 v[72:75], v[180:183], v[230:233], v[72:75]
	v_mfma_f32_16x16x32_bf16 v[116:119], v[184:187], v[200:203], 0
	v_mfma_f32_16x16x32_bf16 v[112:115], v[192:195], v[200:203], 0
	v_mfma_f32_16x16x32_bf16 v[100:103], v[184:187], v[208:211], 0
	v_mfma_f32_16x16x32_bf16 v[96:99], v[192:195], v[208:211], 0
	v_mfma_f32_16x16x32_bf16 v[84:87], v[184:187], v[216:219], 0
	v_mfma_f32_16x16x32_bf16 v[80:83], v[192:195], v[216:219], 0
	v_mfma_f32_16x16x32_bf16 v[68:71], v[184:187], v[224:227], 0
	v_mfma_f32_16x16x32_bf16 v[64:67], v[192:195], v[224:227], 0
	v_mfma_f32_16x16x32_bf16 v[116:119], v[188:191], v[204:207], v[116:119]
	v_mfma_f32_16x16x32_bf16 v[112:115], v[196:199], v[204:207], v[112:115]
	v_mfma_f32_16x16x32_bf16 v[100:103], v[188:191], v[212:215], v[100:103]
	v_mfma_f32_16x16x32_bf16 v[96:99], v[196:199], v[212:215], v[96:99]
	v_mfma_f32_16x16x32_bf16 v[84:87], v[188:191], v[220:223], v[84:87]
	v_mfma_f32_16x16x32_bf16 v[80:83], v[196:199], v[220:223], v[80:83]
	v_mfma_f32_16x16x32_bf16 v[68:71], v[188:191], v[230:233], v[68:71]
	v_mfma_f32_16x16x32_bf16 v[64:67], v[196:199], v[230:233], v[64:67]
	s_barrier
	s_setprio 0
	s_add_i32 s68, s53, s42
	v_lshl_add_u64 v[150:151], s[36:37], 0, v[132:133]
	s_mov_b32 m0, s68
	ds_read_b128 v[200:203], v174 offset:16384
	ds_read_b128 v[204:207], v174 offset:17408
	ds_read_b128 v[208:211], v174 offset:18432
	ds_read_b128 v[212:215], v174 offset:19456
	ds_read_b128 v[216:219], v174 offset:20480
	ds_read_b128 v[220:223], v174 offset:21504
	ds_read_b128 v[224:227], v174 offset:22528
	ds_read_b128 v[230:233], v174 offset:23552
	global_load_lds_dwordx4 v[150:151], off
	s_add_i32 m0, s68, 0x2000
	s_add_u32 s68, s36, 0x40000
	v_lshl_add_u64 v[154:155], s[36:37], 0, v[128:129]
	s_addc_u32 s69, s37, 0
	s_add_i32 s70, s54, s42
	global_load_lds_dwordx4 v[154:155], off
	v_lshl_add_u64 v[158:159], s[68:69], 0, v[132:133]
	s_mov_b32 m0, s70
	v_lshl_add_u64 v[162:163], s[38:39], 0, v[130:131]
	global_load_lds_dwordx4 v[158:159], off
	v_lshl_add_u64 v[158:159], s[68:69], 0, v[128:129]
	s_add_i32 m0, s70, 0x2000
	s_nop 0
	global_load_lds_dwordx4 v[158:159], off
	v_lshl_add_u64 v[158:159], s[38:39], 0, v[134:135]
	s_mov_b32 m0, s27
	s_nop 0
	global_load_lds_dwordx4 v[158:159], off
	s_mov_b32 m0, s45
	s_nop 0
	global_load_lds_dwordx4 v[162:163], off
	s_waitcnt vmcnt(8)
	s_waitcnt lgkmcnt(0)
	s_setprio 1
	s_barrier
	v_mfma_f32_16x16x32_bf16 v[60:63], v[146:149], v[200:203], 0
	v_mfma_f32_16x16x32_bf16 v[56:59], v[176:179], v[200:203], 0
	v_mfma_f32_16x16x32_bf16 v[44:47], v[146:149], v[208:211], 0
	v_mfma_f32_16x16x32_bf16 v[40:43], v[176:179], v[208:211], 0
	v_mfma_f32_16x16x32_bf16 v[28:31], v[146:149], v[216:219], 0
	v_mfma_f32_16x16x32_bf16 v[24:27], v[176:179], v[216:219], 0
	v_mfma_f32_16x16x32_bf16 v[12:15], v[146:149], v[224:227], 0
	v_mfma_f32_16x16x32_bf16 v[8:11], v[176:179], v[224:227], 0
	v_mfma_f32_16x16x32_bf16 v[60:63], v[166:169], v[204:207], v[60:63]
	v_mfma_f32_16x16x32_bf16 v[56:59], v[180:183], v[204:207], v[56:59]
	v_mfma_f32_16x16x32_bf16 v[44:47], v[166:169], v[212:215], v[44:47]
	v_mfma_f32_16x16x32_bf16 v[40:43], v[180:183], v[212:215], v[40:43]
	v_mfma_f32_16x16x32_bf16 v[28:31], v[166:169], v[220:223], v[28:31]
	v_mfma_f32_16x16x32_bf16 v[24:27], v[180:183], v[220:223], v[24:27]
	v_mfma_f32_16x16x32_bf16 v[12:15], v[166:169], v[230:233], v[12:15]
	v_mfma_f32_16x16x32_bf16 v[8:11], v[180:183], v[230:233], v[8:11]
	v_mfma_f32_16x16x32_bf16 v[52:55], v[184:187], v[200:203], 0
	v_mfma_f32_16x16x32_bf16 v[48:51], v[192:195], v[200:203], 0
	v_mfma_f32_16x16x32_bf16 v[36:39], v[184:187], v[208:211], 0
	v_mfma_f32_16x16x32_bf16 v[32:35], v[192:195], v[208:211], 0
	v_mfma_f32_16x16x32_bf16 v[20:23], v[184:187], v[216:219], 0
	v_mfma_f32_16x16x32_bf16 v[16:19], v[192:195], v[216:219], 0
	v_mfma_f32_16x16x32_bf16 v[4:7], v[184:187], v[224:227], 0
	v_mfma_f32_16x16x32_bf16 v[0:3], v[192:195], v[224:227], 0
	v_mfma_f32_16x16x32_bf16 v[52:55], v[188:191], v[204:207], v[52:55]
	v_mfma_f32_16x16x32_bf16 v[48:51], v[196:199], v[204:207], v[48:51]
	v_mfma_f32_16x16x32_bf16 v[36:39], v[188:191], v[212:215], v[36:39]
	v_mfma_f32_16x16x32_bf16 v[32:35], v[196:199], v[212:215], v[32:35]
	v_mfma_f32_16x16x32_bf16 v[20:23], v[188:191], v[220:223], v[20:23]
	v_mfma_f32_16x16x32_bf16 v[16:19], v[196:199], v[220:223], v[16:19]
	v_mfma_f32_16x16x32_bf16 v[4:7], v[188:191], v[230:233], v[4:7]
	v_mfma_f32_16x16x32_bf16 v[0:3], v[196:199], v[230:233], v[0:3]
	s_barrier
	s_setprio 0
	s_add_i32 s68, 0, 0x18000
	v_add_u32_e32 v152, s68, v157
	s_add_i32 s69, 0, 0x1c000
	ds_read_b128 v[146:149], v152
	ds_read_b128 v[166:169], v152 offset:1024
	ds_read_b128 v[176:179], v152 offset:2048
	ds_read_b128 v[180:183], v152 offset:3072
	v_add_u32_e32 v152, s69, v157
	ds_read_b128 v[184:187], v152
	ds_read_b128 v[188:191], v152 offset:1024
	ds_read_b128 v[192:195], v152 offset:2048
	ds_read_b128 v[196:199], v152 offset:3072
	s_add_u32 s38, s38, 0x40000
	s_addc_u32 s39, s39, 0
	s_mov_b32 m0, s46
	v_lshl_add_u64 v[234:235], s[38:39], 0, v[134:135]
	ds_read_b128 v[200:203], v174 offset:32768
	ds_read_b128 v[204:207], v174 offset:33792
	ds_read_b128 v[208:211], v174 offset:34816
	ds_read_b128 v[212:215], v174 offset:35840
	ds_read_b128 v[216:219], v174 offset:36864
	ds_read_b128 v[220:223], v174 offset:37888
	ds_read_b128 v[224:227], v174 offset:38912
	ds_read_b128 v[230:233], v174 offset:39936
	global_load_lds_dwordx4 v[234:235], off
	v_lshl_add_u64 v[234:235], s[38:39], 0, v[130:131]
	s_mov_b32 m0, s47
	s_nop 0
	global_load_lds_dwordx4 v[234:235], off
	s_waitcnt vmcnt(8)
	s_waitcnt lgkmcnt(0)
	s_setprio 1
	s_barrier
	v_mfma_f32_16x16x32_bf16 v[124:127], v[146:149], v[200:203], v[124:127]
	v_mfma_f32_16x16x32_bf16 v[120:123], v[176:179], v[200:203], v[120:123]
	v_mfma_f32_16x16x32_bf16 v[108:111], v[146:149], v[208:211], v[108:111]
	v_mfma_f32_16x16x32_bf16 v[104:107], v[176:179], v[208:211], v[104:107]
	v_mfma_f32_16x16x32_bf16 v[92:95], v[146:149], v[216:219], v[92:95]
	v_mfma_f32_16x16x32_bf16 v[88:91], v[176:179], v[216:219], v[88:91]
	v_mfma_f32_16x16x32_bf16 v[76:79], v[146:149], v[224:227], v[76:79]
	v_mfma_f32_16x16x32_bf16 v[72:75], v[176:179], v[224:227], v[72:75]
	v_mfma_f32_16x16x32_bf16 v[124:127], v[166:169], v[204:207], v[124:127]
	v_mfma_f32_16x16x32_bf16 v[120:123], v[180:183], v[204:207], v[120:123]
	v_mfma_f32_16x16x32_bf16 v[108:111], v[166:169], v[212:215], v[108:111]
	v_mfma_f32_16x16x32_bf16 v[104:107], v[180:183], v[212:215], v[104:107]
	v_mfma_f32_16x16x32_bf16 v[92:95], v[166:169], v[220:223], v[92:95]
	v_mfma_f32_16x16x32_bf16 v[88:91], v[180:183], v[220:223], v[88:91]
	v_mfma_f32_16x16x32_bf16 v[76:79], v[166:169], v[230:233], v[76:79]
	v_mfma_f32_16x16x32_bf16 v[72:75], v[180:183], v[230:233], v[72:75]
	v_mfma_f32_16x16x32_bf16 v[116:119], v[184:187], v[200:203], v[116:119]
	v_mfma_f32_16x16x32_bf16 v[112:115], v[192:195], v[200:203], v[112:115]
	v_mfma_f32_16x16x32_bf16 v[100:103], v[184:187], v[208:211], v[100:103]
	v_mfma_f32_16x16x32_bf16 v[96:99], v[192:195], v[208:211], v[96:99]
	v_mfma_f32_16x16x32_bf16 v[84:87], v[184:187], v[216:219], v[84:87]
	v_mfma_f32_16x16x32_bf16 v[80:83], v[192:195], v[216:219], v[80:83]
	v_mfma_f32_16x16x32_bf16 v[68:71], v[184:187], v[224:227], v[68:71]
	v_mfma_f32_16x16x32_bf16 v[64:67], v[192:195], v[224:227], v[64:67]
	v_mfma_f32_16x16x32_bf16 v[116:119], v[188:191], v[204:207], v[116:119]
	v_mfma_f32_16x16x32_bf16 v[112:115], v[196:199], v[204:207], v[112:115]
	v_mfma_f32_16x16x32_bf16 v[100:103], v[188:191], v[212:215], v[100:103]
	v_mfma_f32_16x16x32_bf16 v[96:99], v[196:199], v[212:215], v[96:99]
	v_mfma_f32_16x16x32_bf16 v[84:87], v[188:191], v[220:223], v[84:87]
	v_mfma_f32_16x16x32_bf16 v[80:83], v[196:199], v[220:223], v[80:83]
	v_mfma_f32_16x16x32_bf16 v[68:71], v[188:191], v[230:233], v[68:71]
	v_mfma_f32_16x16x32_bf16 v[64:67], v[196:199], v[230:233], v[64:67]
	s_barrier
	s_setprio 0
	s_add_i32 s38, s68, s42
	v_lshl_add_u64 v[150:151], v[150:151], 0, s[14:15]
	s_mov_b32 m0, s38
	ds_read_b128 v[200:203], v174 offset:49152
	ds_read_b128 v[204:207], v174 offset:50176
	ds_read_b128 v[208:211], v174 offset:51200
	ds_read_b128 v[212:215], v174 offset:52224
	ds_read_b128 v[216:219], v174 offset:53248
	ds_read_b128 v[220:223], v174 offset:54272
	ds_read_b128 v[224:227], v174 offset:55296
	ds_read_b128 v[230:233], v174 offset:56320
	global_load_lds_dwordx4 v[150:151], off
	s_add_i32 m0, s38, 0x2000
	s_add_u32 s36, s36, 0x40080
	v_lshl_add_u64 v[150:151], v[154:155], 0, s[14:15]
	s_addc_u32 s37, s37, 0
	s_add_i32 s38, s69, s42
	global_load_lds_dwordx4 v[150:151], off
	v_lshl_add_u64 v[150:151], s[36:37], 0, v[132:133]
	s_mov_b32 m0, s38
	s_nop 0
	global_load_lds_dwordx4 v[150:151], off
	v_lshl_add_u64 v[150:151], s[36:37], 0, v[128:129]
	s_add_i32 m0, s38, 0x2000
	s_nop 0
	global_load_lds_dwordx4 v[150:151], off
	v_lshl_add_u64 v[150:151], v[158:159], 0, s[14:15]
	s_mov_b32 m0, s49
	s_nop 0
	global_load_lds_dwordx4 v[150:151], off
	v_lshl_add_u64 v[150:151], v[162:163], 0, s[14:15]
	s_mov_b32 m0, s50
	s_nop 0
	global_load_lds_dwordx4 v[150:151], off
	s_waitcnt vmcnt(8)
	s_waitcnt lgkmcnt(0)
	s_setprio 1
	s_barrier
	v_mfma_f32_16x16x32_bf16 v[60:63], v[146:149], v[200:203], v[60:63]
	v_mfma_f32_16x16x32_bf16 v[56:59], v[176:179], v[200:203], v[56:59]
	v_mfma_f32_16x16x32_bf16 v[44:47], v[146:149], v[208:211], v[44:47]
	v_mfma_f32_16x16x32_bf16 v[40:43], v[176:179], v[208:211], v[40:43]
	v_mfma_f32_16x16x32_bf16 v[28:31], v[146:149], v[216:219], v[28:31]
	v_mfma_f32_16x16x32_bf16 v[24:27], v[176:179], v[216:219], v[24:27]
	v_mfma_f32_16x16x32_bf16 v[12:15], v[146:149], v[224:227], v[12:15]
	v_mfma_f32_16x16x32_bf16 v[8:11], v[176:179], v[224:227], v[8:11]
	v_mfma_f32_16x16x32_bf16 v[60:63], v[166:169], v[204:207], v[60:63]
	v_mfma_f32_16x16x32_bf16 v[56:59], v[180:183], v[204:207], v[56:59]
	v_mfma_f32_16x16x32_bf16 v[44:47], v[166:169], v[212:215], v[44:47]
	v_mfma_f32_16x16x32_bf16 v[40:43], v[180:183], v[212:215], v[40:43]
	v_mfma_f32_16x16x32_bf16 v[28:31], v[166:169], v[220:223], v[28:31]
	v_mfma_f32_16x16x32_bf16 v[24:27], v[180:183], v[220:223], v[24:27]
	v_mfma_f32_16x16x32_bf16 v[12:15], v[166:169], v[230:233], v[12:15]
	v_mfma_f32_16x16x32_bf16 v[8:11], v[180:183], v[230:233], v[8:11]
	v_mfma_f32_16x16x32_bf16 v[52:55], v[184:187], v[200:203], v[52:55]
	v_mfma_f32_16x16x32_bf16 v[48:51], v[192:195], v[200:203], v[48:51]
	v_mfma_f32_16x16x32_bf16 v[36:39], v[184:187], v[208:211], v[36:39]
	v_mfma_f32_16x16x32_bf16 v[32:35], v[192:195], v[208:211], v[32:35]
	v_mfma_f32_16x16x32_bf16 v[20:23], v[184:187], v[216:219], v[20:23]
	v_mfma_f32_16x16x32_bf16 v[16:19], v[192:195], v[216:219], v[16:19]
	v_mfma_f32_16x16x32_bf16 v[4:7], v[184:187], v[224:227], v[4:7]
	v_mfma_f32_16x16x32_bf16 v[0:3], v[192:195], v[224:227], v[0:3]
	v_mfma_f32_16x16x32_bf16 v[52:55], v[188:191], v[204:207], v[52:55]
	v_mfma_f32_16x16x32_bf16 v[48:51], v[196:199], v[204:207], v[48:51]
	v_mfma_f32_16x16x32_bf16 v[36:39], v[188:191], v[212:215], v[36:39]
	v_mfma_f32_16x16x32_bf16 v[32:35], v[196:199], v[212:215], v[32:35]
	v_mfma_f32_16x16x32_bf16 v[20:23], v[188:191], v[220:223], v[20:23]
	v_mfma_f32_16x16x32_bf16 v[16:19], v[196:199], v[220:223], v[16:19]
	v_mfma_f32_16x16x32_bf16 v[4:7], v[188:191], v[230:233], v[4:7]
	v_mfma_f32_16x16x32_bf16 v[0:3], v[196:199], v[230:233], v[0:3]
	s_barrier
	s_setprio 0
	s_add_i32 s67, s67, 2
	s_add_u32 s4, s4, 0x100
	s_addc_u32 s5, s5, 0
	s_add_u32 s59, s59, 0x100
	s_addc_u32 s66, s66, 0
	s_cmp_gt_u32 s67, 13
.LBB0_759:
	ds_read_b128 v[146:149], v172
	ds_read_b128 v[166:169], v172 offset:1024
	ds_read_b128 v[176:179], v172 offset:2048
	ds_read_b128 v[180:183], v172 offset:3072
	ds_read_b128 v[184:187], v173
	ds_read_b128 v[188:191], v173 offset:1024
	ds_read_b128 v[192:195], v173 offset:2048
	ds_read_b128 v[196:199], v173 offset:3072
	s_add_u32 s36, s4, 0xfffc0080
	s_addc_u32 s37, s5, -1
	s_cmp_eq_u32 s67, 12
	s_cselect_b32 s39, s19, s37
	s_cselect_b32 s38, s57, s36
	s_cselect_b32 s37, s11, s66
	s_cselect_b32 s36, s58, s59
	v_lshl_add_u64 v[150:151], s[4:5], 0, v[138:139]
	s_add_i32 m0, s27, 0xc000
	ds_read_b128 v[200:203], v174
	ds_read_b128 v[204:207], v174 offset:1024
	ds_read_b128 v[208:211], v174 offset:2048
	ds_read_b128 v[212:215], v174 offset:3072
	ds_read_b128 v[216:219], v174 offset:4096
	ds_read_b128 v[220:223], v174 offset:5120
	ds_read_b128 v[224:227], v174 offset:6144
	ds_read_b128 v[230:233], v174 offset:7168
	global_load_lds_dwordx4 v[150:151], off
	v_lshl_add_u64 v[150:151], s[4:5], 0, v[140:141]
	s_add_i32 m0, s27, 0xe000
	s_nop 0
	global_load_lds_dwordx4 v[150:151], off
	s_waitcnt vmcnt(8)
	s_waitcnt lgkmcnt(0)
	s_setprio 1
	s_barrier
	v_mfma_f32_16x16x32_bf16 v[124:127], v[146:149], v[200:203], v[124:127]
	v_mfma_f32_16x16x32_bf16 v[120:123], v[176:179], v[200:203], v[120:123]
	v_mfma_f32_16x16x32_bf16 v[108:111], v[146:149], v[208:211], v[108:111]
	v_mfma_f32_16x16x32_bf16 v[104:107], v[176:179], v[208:211], v[104:107]
	v_mfma_f32_16x16x32_bf16 v[92:95], v[146:149], v[216:219], v[92:95]
	v_mfma_f32_16x16x32_bf16 v[88:91], v[176:179], v[216:219], v[88:91]
	v_mfma_f32_16x16x32_bf16 v[76:79], v[146:149], v[224:227], v[76:79]
	v_mfma_f32_16x16x32_bf16 v[72:75], v[176:179], v[224:227], v[72:75]
	v_mfma_f32_16x16x32_bf16 v[124:127], v[166:169], v[204:207], v[124:127]
	v_mfma_f32_16x16x32_bf16 v[120:123], v[180:183], v[204:207], v[120:123]
	v_mfma_f32_16x16x32_bf16 v[108:111], v[166:169], v[212:215], v[108:111]
	v_mfma_f32_16x16x32_bf16 v[104:107], v[180:183], v[212:215], v[104:107]
	v_mfma_f32_16x16x32_bf16 v[92:95], v[166:169], v[220:223], v[92:95]
	v_mfma_f32_16x16x32_bf16 v[88:91], v[180:183], v[220:223], v[88:91]
	v_mfma_f32_16x16x32_bf16 v[76:79], v[166:169], v[230:233], v[76:79]
	v_mfma_f32_16x16x32_bf16 v[72:75], v[180:183], v[230:233], v[72:75]
	v_mfma_f32_16x16x32_bf16 v[116:119], v[184:187], v[200:203], v[116:119]
	v_mfma_f32_16x16x32_bf16 v[112:115], v[192:195], v[200:203], v[112:115]
	v_mfma_f32_16x16x32_bf16 v[100:103], v[184:187], v[208:211], v[100:103]
	v_mfma_f32_16x16x32_bf16 v[96:99], v[192:195], v[208:211], v[96:99]
	v_mfma_f32_16x16x32_bf16 v[84:87], v[184:187], v[216:219], v[84:87]
	v_mfma_f32_16x16x32_bf16 v[80:83], v[192:195], v[216:219], v[80:83]
	v_mfma_f32_16x16x32_bf16 v[68:71], v[184:187], v[224:227], v[68:71]
	v_mfma_f32_16x16x32_bf16 v[64:67], v[192:195], v[224:227], v[64:67]
	v_mfma_f32_16x16x32_bf16 v[116:119], v[188:191], v[204:207], v[116:119]
	v_mfma_f32_16x16x32_bf16 v[112:115], v[196:199], v[204:207], v[112:115]
	v_mfma_f32_16x16x32_bf16 v[100:103], v[188:191], v[212:215], v[100:103]
	v_mfma_f32_16x16x32_bf16 v[96:99], v[196:199], v[212:215], v[96:99]
	v_mfma_f32_16x16x32_bf16 v[84:87], v[188:191], v[220:223], v[84:87]
	v_mfma_f32_16x16x32_bf16 v[80:83], v[196:199], v[220:223], v[80:83]
	v_mfma_f32_16x16x32_bf16 v[68:71], v[188:191], v[230:233], v[68:71]
	v_mfma_f32_16x16x32_bf16 v[64:67], v[196:199], v[230:233], v[64:67]
	s_barrier
	s_setprio 0
	s_add_i32 s68, s53, s42
	v_lshl_add_u64 v[150:151], s[36:37], 0, v[132:133]
	s_mov_b32 m0, s68
	ds_read_b128 v[200:203], v174 offset:16384
	ds_read_b128 v[204:207], v174 offset:17408
	ds_read_b128 v[208:211], v174 offset:18432
	ds_read_b128 v[212:215], v174 offset:19456
	ds_read_b128 v[216:219], v174 offset:20480
	ds_read_b128 v[220:223], v174 offset:21504
	ds_read_b128 v[224:227], v174 offset:22528
	ds_read_b128 v[230:233], v174 offset:23552
	global_load_lds_dwordx4 v[150:151], off
	s_add_i32 m0, s68, 0x2000
	s_add_u32 s68, s36, 0x40000
	v_lshl_add_u64 v[154:155], s[36:37], 0, v[128:129]
	s_addc_u32 s69, s37, 0
	s_add_i32 s70, s54, s42
	global_load_lds_dwordx4 v[154:155], off
	v_lshl_add_u64 v[158:159], s[68:69], 0, v[132:133]
	s_mov_b32 m0, s70
	v_lshl_add_u64 v[162:163], s[38:39], 0, v[130:131]
	global_load_lds_dwordx4 v[158:159], off
	v_lshl_add_u64 v[158:159], s[68:69], 0, v[128:129]
	s_add_i32 m0, s70, 0x2000
	s_nop 0
	global_load_lds_dwordx4 v[158:159], off
	v_lshl_add_u64 v[158:159], s[38:39], 0, v[134:135]
	s_mov_b32 m0, s27
	s_nop 0
	global_load_lds_dwordx4 v[158:159], off
	s_mov_b32 m0, s45
	s_nop 0
	global_load_lds_dwordx4 v[162:163], off
	s_waitcnt vmcnt(8)
	s_waitcnt lgkmcnt(0)
	s_setprio 1
	s_barrier
	v_mfma_f32_16x16x32_bf16 v[60:63], v[146:149], v[200:203], v[60:63]
	v_mfma_f32_16x16x32_bf16 v[56:59], v[176:179], v[200:203], v[56:59]
	v_mfma_f32_16x16x32_bf16 v[44:47], v[146:149], v[208:211], v[44:47]
	v_mfma_f32_16x16x32_bf16 v[40:43], v[176:179], v[208:211], v[40:43]
	v_mfma_f32_16x16x32_bf16 v[28:31], v[146:149], v[216:219], v[28:31]
	v_mfma_f32_16x16x32_bf16 v[24:27], v[176:179], v[216:219], v[24:27]
	v_mfma_f32_16x16x32_bf16 v[12:15], v[146:149], v[224:227], v[12:15]
	v_mfma_f32_16x16x32_bf16 v[8:11], v[176:179], v[224:227], v[8:11]
	v_mfma_f32_16x16x32_bf16 v[60:63], v[166:169], v[204:207], v[60:63]
	v_mfma_f32_16x16x32_bf16 v[56:59], v[180:183], v[204:207], v[56:59]
	v_mfma_f32_16x16x32_bf16 v[44:47], v[166:169], v[212:215], v[44:47]
	v_mfma_f32_16x16x32_bf16 v[40:43], v[180:183], v[212:215], v[40:43]
	v_mfma_f32_16x16x32_bf16 v[28:31], v[166:169], v[220:223], v[28:31]
	v_mfma_f32_16x16x32_bf16 v[24:27], v[180:183], v[220:223], v[24:27]
	v_mfma_f32_16x16x32_bf16 v[12:15], v[166:169], v[230:233], v[12:15]
	v_mfma_f32_16x16x32_bf16 v[8:11], v[180:183], v[230:233], v[8:11]
	v_mfma_f32_16x16x32_bf16 v[52:55], v[184:187], v[200:203], v[52:55]
	v_mfma_f32_16x16x32_bf16 v[48:51], v[192:195], v[200:203], v[48:51]
	v_mfma_f32_16x16x32_bf16 v[36:39], v[184:187], v[208:211], v[36:39]
	v_mfma_f32_16x16x32_bf16 v[32:35], v[192:195], v[208:211], v[32:35]
	v_mfma_f32_16x16x32_bf16 v[20:23], v[184:187], v[216:219], v[20:23]
	v_mfma_f32_16x16x32_bf16 v[16:19], v[192:195], v[216:219], v[16:19]
	v_mfma_f32_16x16x32_bf16 v[4:7], v[184:187], v[224:227], v[4:7]
	v_mfma_f32_16x16x32_bf16 v[0:3], v[192:195], v[224:227], v[0:3]
	v_mfma_f32_16x16x32_bf16 v[52:55], v[188:191], v[204:207], v[52:55]
	v_mfma_f32_16x16x32_bf16 v[48:51], v[196:199], v[204:207], v[48:51]
	v_mfma_f32_16x16x32_bf16 v[36:39], v[188:191], v[212:215], v[36:39]
	v_mfma_f32_16x16x32_bf16 v[32:35], v[196:199], v[212:215], v[32:35]
	v_mfma_f32_16x16x32_bf16 v[20:23], v[188:191], v[220:223], v[20:23]
	v_mfma_f32_16x16x32_bf16 v[16:19], v[196:199], v[220:223], v[16:19]
	v_mfma_f32_16x16x32_bf16 v[4:7], v[188:191], v[230:233], v[4:7]
	v_mfma_f32_16x16x32_bf16 v[0:3], v[196:199], v[230:233], v[0:3]
	s_barrier
	s_setprio 0
	s_add_i32 s68, 0, 0x18000
	v_add_u32_e32 v152, s68, v157
	s_add_i32 s69, 0, 0x1c000
	ds_read_b128 v[146:149], v152
	ds_read_b128 v[166:169], v152 offset:1024
	ds_read_b128 v[176:179], v152 offset:2048
	ds_read_b128 v[180:183], v152 offset:3072
	v_add_u32_e32 v152, s69, v157
	ds_read_b128 v[184:187], v152
	ds_read_b128 v[188:191], v152 offset:1024
	ds_read_b128 v[192:195], v152 offset:2048
	ds_read_b128 v[196:199], v152 offset:3072
	s_add_u32 s38, s38, 0x40000
	s_addc_u32 s39, s39, 0
	s_mov_b32 m0, s46
	v_lshl_add_u64 v[234:235], s[38:39], 0, v[134:135]
	ds_read_b128 v[200:203], v174 offset:32768
	ds_read_b128 v[204:207], v174 offset:33792
	ds_read_b128 v[208:211], v174 offset:34816
	ds_read_b128 v[212:215], v174 offset:35840
	ds_read_b128 v[216:219], v174 offset:36864
	ds_read_b128 v[220:223], v174 offset:37888
	ds_read_b128 v[224:227], v174 offset:38912
	ds_read_b128 v[230:233], v174 offset:39936
	global_load_lds_dwordx4 v[234:235], off
	v_lshl_add_u64 v[234:235], s[38:39], 0, v[130:131]
	s_mov_b32 m0, s47
	s_nop 0
	global_load_lds_dwordx4 v[234:235], off
	s_waitcnt vmcnt(8)
	s_waitcnt lgkmcnt(0)
	s_setprio 1
	s_barrier
	v_mfma_f32_16x16x32_bf16 v[124:127], v[146:149], v[200:203], v[124:127]
	v_mfma_f32_16x16x32_bf16 v[120:123], v[176:179], v[200:203], v[120:123]
	v_mfma_f32_16x16x32_bf16 v[108:111], v[146:149], v[208:211], v[108:111]
	v_mfma_f32_16x16x32_bf16 v[104:107], v[176:179], v[208:211], v[104:107]
	v_mfma_f32_16x16x32_bf16 v[92:95], v[146:149], v[216:219], v[92:95]
	v_mfma_f32_16x16x32_bf16 v[88:91], v[176:179], v[216:219], v[88:91]
	v_mfma_f32_16x16x32_bf16 v[76:79], v[146:149], v[224:227], v[76:79]
	v_mfma_f32_16x16x32_bf16 v[72:75], v[176:179], v[224:227], v[72:75]
	v_mfma_f32_16x16x32_bf16 v[124:127], v[166:169], v[204:207], v[124:127]
	v_mfma_f32_16x16x32_bf16 v[120:123], v[180:183], v[204:207], v[120:123]
	v_mfma_f32_16x16x32_bf16 v[108:111], v[166:169], v[212:215], v[108:111]
	v_mfma_f32_16x16x32_bf16 v[104:107], v[180:183], v[212:215], v[104:107]
	v_mfma_f32_16x16x32_bf16 v[92:95], v[166:169], v[220:223], v[92:95]
	v_mfma_f32_16x16x32_bf16 v[88:91], v[180:183], v[220:223], v[88:91]
	v_mfma_f32_16x16x32_bf16 v[76:79], v[166:169], v[230:233], v[76:79]
	v_mfma_f32_16x16x32_bf16 v[72:75], v[180:183], v[230:233], v[72:75]
	v_mfma_f32_16x16x32_bf16 v[116:119], v[184:187], v[200:203], v[116:119]
	v_mfma_f32_16x16x32_bf16 v[112:115], v[192:195], v[200:203], v[112:115]
	v_mfma_f32_16x16x32_bf16 v[100:103], v[184:187], v[208:211], v[100:103]
	v_mfma_f32_16x16x32_bf16 v[96:99], v[192:195], v[208:211], v[96:99]
	v_mfma_f32_16x16x32_bf16 v[84:87], v[184:187], v[216:219], v[84:87]
	v_mfma_f32_16x16x32_bf16 v[80:83], v[192:195], v[216:219], v[80:83]
	v_mfma_f32_16x16x32_bf16 v[68:71], v[184:187], v[224:227], v[68:71]
	v_mfma_f32_16x16x32_bf16 v[64:67], v[192:195], v[224:227], v[64:67]
	v_mfma_f32_16x16x32_bf16 v[116:119], v[188:191], v[204:207], v[116:119]
	v_mfma_f32_16x16x32_bf16 v[112:115], v[196:199], v[204:207], v[112:115]
	v_mfma_f32_16x16x32_bf16 v[100:103], v[188:191], v[212:215], v[100:103]
	v_mfma_f32_16x16x32_bf16 v[96:99], v[196:199], v[212:215], v[96:99]
	v_mfma_f32_16x16x32_bf16 v[84:87], v[188:191], v[220:223], v[84:87]
	v_mfma_f32_16x16x32_bf16 v[80:83], v[196:199], v[220:223], v[80:83]
	v_mfma_f32_16x16x32_bf16 v[68:71], v[188:191], v[230:233], v[68:71]
	v_mfma_f32_16x16x32_bf16 v[64:67], v[196:199], v[230:233], v[64:67]
	s_barrier
	s_setprio 0
	s_add_i32 s38, s68, s42
	v_lshl_add_u64 v[150:151], v[150:151], 0, s[14:15]
	s_mov_b32 m0, s38
	ds_read_b128 v[200:203], v174 offset:49152
	ds_read_b128 v[204:207], v174 offset:50176
	ds_read_b128 v[208:211], v174 offset:51200
	ds_read_b128 v[212:215], v174 offset:52224
	ds_read_b128 v[216:219], v174 offset:53248
	ds_read_b128 v[220:223], v174 offset:54272
	ds_read_b128 v[224:227], v174 offset:55296
	ds_read_b128 v[230:233], v174 offset:56320
	global_load_lds_dwordx4 v[150:151], off
	s_add_i32 m0, s38, 0x2000
	s_add_u32 s36, s36, 0x40080
	v_lshl_add_u64 v[150:151], v[154:155], 0, s[14:15]
	s_addc_u32 s37, s37, 0
	s_add_i32 s38, s69, s42
	global_load_lds_dwordx4 v[150:151], off
	v_lshl_add_u64 v[150:151], s[36:37], 0, v[132:133]
	s_mov_b32 m0, s38
	s_nop 0
	global_load_lds_dwordx4 v[150:151], off
	v_lshl_add_u64 v[150:151], s[36:37], 0, v[128:129]
	s_add_i32 m0, s38, 0x2000
	s_nop 0
	global_load_lds_dwordx4 v[150:151], off
	v_lshl_add_u64 v[150:151], v[158:159], 0, s[14:15]
	s_mov_b32 m0, s49
	s_nop 0
	global_load_lds_dwordx4 v[150:151], off
	v_lshl_add_u64 v[150:151], v[162:163], 0, s[14:15]
	s_mov_b32 m0, s50
	s_nop 0
	global_load_lds_dwordx4 v[150:151], off
	s_waitcnt vmcnt(8)
	s_waitcnt lgkmcnt(0)
	s_setprio 1
	s_barrier
	v_mfma_f32_16x16x32_bf16 v[60:63], v[146:149], v[200:203], v[60:63]
	v_mfma_f32_16x16x32_bf16 v[56:59], v[176:179], v[200:203], v[56:59]
	v_mfma_f32_16x16x32_bf16 v[44:47], v[146:149], v[208:211], v[44:47]
	v_mfma_f32_16x16x32_bf16 v[40:43], v[176:179], v[208:211], v[40:43]
	v_mfma_f32_16x16x32_bf16 v[28:31], v[146:149], v[216:219], v[28:31]
	v_mfma_f32_16x16x32_bf16 v[24:27], v[176:179], v[216:219], v[24:27]
	v_mfma_f32_16x16x32_bf16 v[12:15], v[146:149], v[224:227], v[12:15]
	v_mfma_f32_16x16x32_bf16 v[8:11], v[176:179], v[224:227], v[8:11]
	v_mfma_f32_16x16x32_bf16 v[60:63], v[166:169], v[204:207], v[60:63]
	v_mfma_f32_16x16x32_bf16 v[56:59], v[180:183], v[204:207], v[56:59]
	v_mfma_f32_16x16x32_bf16 v[44:47], v[166:169], v[212:215], v[44:47]
	v_mfma_f32_16x16x32_bf16 v[40:43], v[180:183], v[212:215], v[40:43]
	v_mfma_f32_16x16x32_bf16 v[28:31], v[166:169], v[220:223], v[28:31]
	v_mfma_f32_16x16x32_bf16 v[24:27], v[180:183], v[220:223], v[24:27]
	v_mfma_f32_16x16x32_bf16 v[12:15], v[166:169], v[230:233], v[12:15]
	v_mfma_f32_16x16x32_bf16 v[8:11], v[180:183], v[230:233], v[8:11]
	v_mfma_f32_16x16x32_bf16 v[52:55], v[184:187], v[200:203], v[52:55]
	v_mfma_f32_16x16x32_bf16 v[48:51], v[192:195], v[200:203], v[48:51]
	v_mfma_f32_16x16x32_bf16 v[36:39], v[184:187], v[208:211], v[36:39]
	v_mfma_f32_16x16x32_bf16 v[32:35], v[192:195], v[208:211], v[32:35]
	v_mfma_f32_16x16x32_bf16 v[20:23], v[184:187], v[216:219], v[20:23]
	v_mfma_f32_16x16x32_bf16 v[16:19], v[192:195], v[216:219], v[16:19]
	v_mfma_f32_16x16x32_bf16 v[4:7], v[184:187], v[224:227], v[4:7]
	v_mfma_f32_16x16x32_bf16 v[0:3], v[192:195], v[224:227], v[0:3]
	v_mfma_f32_16x16x32_bf16 v[52:55], v[188:191], v[204:207], v[52:55]
	v_mfma_f32_16x16x32_bf16 v[48:51], v[196:199], v[204:207], v[48:51]
	v_mfma_f32_16x16x32_bf16 v[36:39], v[188:191], v[212:215], v[36:39]
	v_mfma_f32_16x16x32_bf16 v[32:35], v[196:199], v[212:215], v[32:35]
	v_mfma_f32_16x16x32_bf16 v[20:23], v[188:191], v[220:223], v[20:23]
	v_mfma_f32_16x16x32_bf16 v[16:19], v[196:199], v[220:223], v[16:19]
	v_mfma_f32_16x16x32_bf16 v[4:7], v[188:191], v[230:233], v[4:7]
	v_mfma_f32_16x16x32_bf16 v[0:3], v[196:199], v[230:233], v[0:3]
	s_barrier
	s_setprio 0
	s_add_i32 s67, s67, 2
	s_add_u32 s4, s4, 0x100
	s_addc_u32 s5, s5, 0
	s_add_u32 s59, s59, 0x100
	s_addc_u32 s66, s66, 0
	s_cmp_gt_u32 s67, 13
	s_cbranch_scc0 .LBB0_759
	s_and_b64 vcc, exec, s[16:17]
	s_cbranch_vccz .LBB0_762
	s_barrier

.LBB0_835:
	s_add_u32 s80, s22, 0x100
	s_addc_u32 s81, s23, 0
	s_mov_b32 s82, -2
	ds_read_b128 v[112:115], v203
	ds_read_b128 v[116:119], v203 offset:1024
	ds_read_b128 v[136:139], v203 offset:2048
	ds_read_b128 v[140:143], v203 offset:3072
	ds_read_b128 v[144:147], v204
	ds_read_b128 v[148:151], v204 offset:1024
	ds_read_b128 v[152:155], v204 offset:2048
	ds_read_b128 v[156:159], v204 offset:3072
	s_add_u32 s22, s20, 0x100
	s_addc_u32 s23, s21, 0
	s_cmp_eq_u32 s82, 40
	s_cselect_b32 s37, s7, s23
	s_cselect_b32 s36, s6, s22
	s_cselect_b32 s27, s19, s81
	s_cselect_b32 s26, s18, s80
	v_lshl_add_u64 v[200:201], s[20:21], 0, v[186:187]
	s_add_i32 m0, s43, 0xc000
	ds_read_b128 v[160:163], v205
	ds_read_b128 v[164:167], v205 offset:1024
	ds_read_b128 v[168:171], v205 offset:2048
	ds_read_b128 v[172:175], v205 offset:3072
	ds_read_b128 v[206:209], v205 offset:4096
	ds_read_b128 v[210:213], v205 offset:5120
	ds_read_b128 v[214:217], v205 offset:6144
	ds_read_b128 v[218:221], v205 offset:7168
	global_load_lds_dwordx4 v[200:201], off
	v_lshl_add_u64 v[200:201], s[20:21], 0, v[188:189]
	s_add_i32 m0, s43, 0xe000
	s_nop 0
	global_load_lds_dwordx4 v[200:201], off
	s_waitcnt vmcnt(8)
	s_waitcnt lgkmcnt(0)
	s_setprio 1
	s_barrier
	v_mfma_f32_16x16x32_bf16 v[132:135], v[112:115], v[160:163], 0
	v_mfma_f32_16x16x32_bf16 v[128:131], v[136:139], v[160:163], 0
	v_mfma_f32_16x16x32_bf16 v[108:111], v[112:115], v[168:171], 0
	v_mfma_f32_16x16x32_bf16 v[104:107], v[136:139], v[168:171], 0
	v_mfma_f32_16x16x32_bf16 v[92:95], v[112:115], v[206:209], 0
	v_mfma_f32_16x16x32_bf16 v[88:91], v[136:139], v[206:209], 0
	v_mfma_f32_16x16x32_bf16 v[76:79], v[112:115], v[214:217], 0
	v_mfma_f32_16x16x32_bf16 v[72:75], v[136:139], v[214:217], 0
	v_mfma_f32_16x16x32_bf16 v[132:135], v[116:119], v[164:167], v[132:135]
	v_mfma_f32_16x16x32_bf16 v[128:131], v[140:143], v[164:167], v[128:131]
	v_mfma_f32_16x16x32_bf16 v[108:111], v[116:119], v[172:175], v[108:111]
	v_mfma_f32_16x16x32_bf16 v[104:107], v[140:143], v[172:175], v[104:107]
	v_mfma_f32_16x16x32_bf16 v[92:95], v[116:119], v[210:213], v[92:95]
	v_mfma_f32_16x16x32_bf16 v[88:91], v[140:143], v[210:213], v[88:91]
	v_mfma_f32_16x16x32_bf16 v[76:79], v[116:119], v[218:221], v[76:79]
	v_mfma_f32_16x16x32_bf16 v[72:75], v[140:143], v[218:221], v[72:75]
	v_mfma_f32_16x16x32_bf16 v[124:127], v[144:147], v[160:163], 0
	v_mfma_f32_16x16x32_bf16 v[120:123], v[152:155], v[160:163], 0
	v_mfma_f32_16x16x32_bf16 v[100:103], v[144:147], v[168:171], 0
	v_mfma_f32_16x16x32_bf16 v[96:99], v[152:155], v[168:171], 0
	v_mfma_f32_16x16x32_bf16 v[84:87], v[144:147], v[206:209], 0
	v_mfma_f32_16x16x32_bf16 v[80:83], v[152:155], v[206:209], 0
	v_mfma_f32_16x16x32_bf16 v[68:71], v[144:147], v[214:217], 0
	v_mfma_f32_16x16x32_bf16 v[64:67], v[152:155], v[214:217], 0
	v_mfma_f32_16x16x32_bf16 v[124:127], v[148:151], v[164:167], v[124:127]
	v_mfma_f32_16x16x32_bf16 v[120:123], v[156:159], v[164:167], v[120:123]
	v_mfma_f32_16x16x32_bf16 v[100:103], v[148:151], v[172:175], v[100:103]
	v_mfma_f32_16x16x32_bf16 v[96:99], v[156:159], v[172:175], v[96:99]
	v_mfma_f32_16x16x32_bf16 v[84:87], v[148:151], v[210:213], v[84:87]
	v_mfma_f32_16x16x32_bf16 v[80:83], v[156:159], v[210:213], v[80:83]
	v_mfma_f32_16x16x32_bf16 v[68:71], v[148:151], v[218:221], v[68:71]
	v_mfma_f32_16x16x32_bf16 v[64:67], v[156:159], v[218:221], v[64:67]
	s_barrier
	s_setprio 0
	s_add_i32 s20, s59, s40
	v_lshl_add_u64 v[200:201], s[26:27], 0, v[180:181]
	s_mov_b32 m0, s20
	ds_read_b128 v[160:163], v205 offset:16384
	ds_read_b128 v[164:167], v205 offset:17408
	ds_read_b128 v[168:171], v205 offset:18432
	ds_read_b128 v[172:175], v205 offset:19456
	ds_read_b128 v[206:209], v205 offset:20480
	ds_read_b128 v[210:213], v205 offset:21504
	ds_read_b128 v[214:217], v205 offset:22528
	ds_read_b128 v[218:221], v205 offset:23552
	global_load_lds_dwordx4 v[200:201], off
	s_add_i32 m0, s20, 0x2000
	s_add_u32 s20, s26, 0xb0000
	v_lshl_add_u64 v[222:223], s[26:27], 0, v[176:177]
	s_addc_u32 s21, s27, 0
	s_add_i32 s83, s66, s40
	global_load_lds_dwordx4 v[222:223], off
	v_lshl_add_u64 v[224:225], s[20:21], 0, v[180:181]
	s_mov_b32 m0, s83
	v_lshl_add_u64 v[226:227], s[36:37], 0, v[178:179]
	global_load_lds_dwordx4 v[224:225], off
	v_lshl_add_u64 v[224:225], s[20:21], 0, v[176:177]
	s_add_i32 m0, s83, 0x2000
	s_nop 0
	global_load_lds_dwordx4 v[224:225], off
	v_lshl_add_u64 v[224:225], s[36:37], 0, v[182:183]
	s_mov_b32 m0, s43
	s_nop 0
	global_load_lds_dwordx4 v[224:225], off
	s_mov_b32 m0, s44
	s_nop 0
	global_load_lds_dwordx4 v[226:227], off
	s_waitcnt vmcnt(8)
	s_waitcnt lgkmcnt(0)
	s_setprio 1
	s_barrier
	v_mfma_f32_16x16x32_bf16 v[60:63], v[112:115], v[160:163], 0
	v_mfma_f32_16x16x32_bf16 v[56:59], v[136:139], v[160:163], 0
	v_mfma_f32_16x16x32_bf16 v[44:47], v[112:115], v[168:171], 0
	v_mfma_f32_16x16x32_bf16 v[40:43], v[136:139], v[168:171], 0
	v_mfma_f32_16x16x32_bf16 v[28:31], v[112:115], v[206:209], 0
	v_mfma_f32_16x16x32_bf16 v[24:27], v[136:139], v[206:209], 0
	v_mfma_f32_16x16x32_bf16 v[12:15], v[112:115], v[214:217], 0
	v_mfma_f32_16x16x32_bf16 v[8:11], v[136:139], v[214:217], 0
	v_mfma_f32_16x16x32_bf16 v[60:63], v[116:119], v[164:167], v[60:63]
	v_mfma_f32_16x16x32_bf16 v[56:59], v[140:143], v[164:167], v[56:59]
	v_mfma_f32_16x16x32_bf16 v[44:47], v[116:119], v[172:175], v[44:47]
	v_mfma_f32_16x16x32_bf16 v[40:43], v[140:143], v[172:175], v[40:43]
	v_mfma_f32_16x16x32_bf16 v[28:31], v[116:119], v[210:213], v[28:31]
	v_mfma_f32_16x16x32_bf16 v[24:27], v[140:143], v[210:213], v[24:27]
	v_mfma_f32_16x16x32_bf16 v[12:15], v[116:119], v[218:221], v[12:15]
	v_mfma_f32_16x16x32_bf16 v[8:11], v[140:143], v[218:221], v[8:11]
	v_mfma_f32_16x16x32_bf16 v[52:55], v[144:147], v[160:163], 0
	v_mfma_f32_16x16x32_bf16 v[48:51], v[152:155], v[160:163], 0
	v_mfma_f32_16x16x32_bf16 v[36:39], v[144:147], v[168:171], 0
	v_mfma_f32_16x16x32_bf16 v[32:35], v[152:155], v[168:171], 0
	v_mfma_f32_16x16x32_bf16 v[20:23], v[144:147], v[206:209], 0
	v_mfma_f32_16x16x32_bf16 v[16:19], v[152:155], v[206:209], 0
	v_mfma_f32_16x16x32_bf16 v[4:7], v[144:147], v[214:217], 0
	v_mfma_f32_16x16x32_bf16 v[0:3], v[152:155], v[214:217], 0
	v_mfma_f32_16x16x32_bf16 v[52:55], v[148:151], v[164:167], v[52:55]
	v_mfma_f32_16x16x32_bf16 v[48:51], v[156:159], v[164:167], v[48:51]
	v_mfma_f32_16x16x32_bf16 v[36:39], v[148:151], v[172:175], v[36:39]
	v_mfma_f32_16x16x32_bf16 v[32:35], v[156:159], v[172:175], v[32:35]
	v_mfma_f32_16x16x32_bf16 v[20:23], v[148:151], v[210:213], v[20:23]
	v_mfma_f32_16x16x32_bf16 v[16:19], v[156:159], v[210:213], v[16:19]
	v_mfma_f32_16x16x32_bf16 v[4:7], v[148:151], v[218:221], v[4:7]
	v_mfma_f32_16x16x32_bf16 v[0:3], v[156:159], v[218:221], v[0:3]
	s_barrier
	s_setprio 0
	s_add_i32 s83, 0, 0x18000
	s_add_i32 s85, 0, 0x1c000
	v_add_u32_e32 v140, s83, v202
	v_add_u32_e32 v156, s85, v202
	ds_read_b128 v[112:115], v140
	ds_read_b128 v[116:119], v140 offset:1024
	ds_read_b128 v[136:139], v140 offset:2048
	ds_read_b128 v[140:143], v140 offset:3072
	ds_read_b128 v[144:147], v156
	ds_read_b128 v[148:151], v156 offset:1024
	ds_read_b128 v[152:155], v156 offset:2048
	ds_read_b128 v[156:159], v156 offset:3072
	s_add_u32 s20, s36, 0xb0000
	s_addc_u32 s21, s37, 0
	s_mov_b32 m0, s45
	v_lshl_add_u64 v[230:231], s[20:21], 0, v[182:183]
	ds_read_b128 v[160:163], v205 offset:32768
	ds_read_b128 v[164:167], v205 offset:33792
	ds_read_b128 v[168:171], v205 offset:34816
	ds_read_b128 v[172:175], v205 offset:35840
	ds_read_b128 v[206:209], v205 offset:36864
	ds_read_b128 v[210:213], v205 offset:37888
	ds_read_b128 v[214:217], v205 offset:38912
	ds_read_b128 v[218:221], v205 offset:39936
	global_load_lds_dwordx4 v[230:231], off
	v_lshl_add_u64 v[230:231], s[20:21], 0, v[178:179]
	s_mov_b32 m0, s46
	s_nop 0
	global_load_lds_dwordx4 v[230:231], off
	s_waitcnt vmcnt(8)
	s_waitcnt lgkmcnt(0)
	s_setprio 1
	s_barrier
	v_mfma_f32_16x16x32_bf16 v[132:135], v[112:115], v[160:163], v[132:135]
	v_mfma_f32_16x16x32_bf16 v[128:131], v[136:139], v[160:163], v[128:131]
	v_mfma_f32_16x16x32_bf16 v[108:111], v[112:115], v[168:171], v[108:111]
	v_mfma_f32_16x16x32_bf16 v[104:107], v[136:139], v[168:171], v[104:107]
	v_mfma_f32_16x16x32_bf16 v[92:95], v[112:115], v[206:209], v[92:95]
	v_mfma_f32_16x16x32_bf16 v[88:91], v[136:139], v[206:209], v[88:91]
	v_mfma_f32_16x16x32_bf16 v[76:79], v[112:115], v[214:217], v[76:79]
	v_mfma_f32_16x16x32_bf16 v[72:75], v[136:139], v[214:217], v[72:75]
	v_mfma_f32_16x16x32_bf16 v[132:135], v[116:119], v[164:167], v[132:135]
	v_mfma_f32_16x16x32_bf16 v[128:131], v[140:143], v[164:167], v[128:131]
	v_mfma_f32_16x16x32_bf16 v[108:111], v[116:119], v[172:175], v[108:111]
	v_mfma_f32_16x16x32_bf16 v[104:107], v[140:143], v[172:175], v[104:107]
	v_mfma_f32_16x16x32_bf16 v[92:95], v[116:119], v[210:213], v[92:95]
	v_mfma_f32_16x16x32_bf16 v[88:91], v[140:143], v[210:213], v[88:91]
	v_mfma_f32_16x16x32_bf16 v[76:79], v[116:119], v[218:221], v[76:79]
	v_mfma_f32_16x16x32_bf16 v[72:75], v[140:143], v[218:221], v[72:75]
	v_mfma_f32_16x16x32_bf16 v[124:127], v[144:147], v[160:163], v[124:127]
	v_mfma_f32_16x16x32_bf16 v[120:123], v[152:155], v[160:163], v[120:123]
	v_mfma_f32_16x16x32_bf16 v[100:103], v[144:147], v[168:171], v[100:103]
	v_mfma_f32_16x16x32_bf16 v[96:99], v[152:155], v[168:171], v[96:99]
	v_mfma_f32_16x16x32_bf16 v[84:87], v[144:147], v[206:209], v[84:87]
	v_mfma_f32_16x16x32_bf16 v[80:83], v[152:155], v[206:209], v[80:83]
	v_mfma_f32_16x16x32_bf16 v[68:71], v[144:147], v[214:217], v[68:71]
	v_mfma_f32_16x16x32_bf16 v[64:67], v[152:155], v[214:217], v[64:67]
	v_mfma_f32_16x16x32_bf16 v[124:127], v[148:151], v[164:167], v[124:127]
	v_mfma_f32_16x16x32_bf16 v[120:123], v[156:159], v[164:167], v[120:123]
	v_mfma_f32_16x16x32_bf16 v[100:103], v[148:151], v[172:175], v[100:103]
	v_mfma_f32_16x16x32_bf16 v[96:99], v[156:159], v[172:175], v[96:99]
	v_mfma_f32_16x16x32_bf16 v[84:87], v[148:151], v[210:213], v[84:87]
	v_mfma_f32_16x16x32_bf16 v[80:83], v[156:159], v[210:213], v[80:83]
	v_mfma_f32_16x16x32_bf16 v[68:71], v[148:151], v[218:221], v[68:71]
	v_mfma_f32_16x16x32_bf16 v[64:67], v[156:159], v[218:221], v[64:67]
	s_barrier
	s_setprio 0
	s_add_i32 s20, s83, s40
	v_lshl_add_u64 v[200:201], v[200:201], 0, s[14:15]
	s_mov_b32 m0, s20
	ds_read_b128 v[160:163], v205 offset:49152
	ds_read_b128 v[164:167], v205 offset:50176
	ds_read_b128 v[168:171], v205 offset:51200
	ds_read_b128 v[172:175], v205 offset:52224
	ds_read_b128 v[206:209], v205 offset:53248
	ds_read_b128 v[210:213], v205 offset:54272
	ds_read_b128 v[214:217], v205 offset:55296
	ds_read_b128 v[218:221], v205 offset:56320
	global_load_lds_dwordx4 v[200:201], off
	s_add_i32 m0, s20, 0x2000
	s_add_u32 s20, s26, 0xb0080
	v_lshl_add_u64 v[200:201], v[222:223], 0, s[14:15]
	s_addc_u32 s21, s27, 0
	s_add_i32 s26, s85, s40
	global_load_lds_dwordx4 v[200:201], off
	v_lshl_add_u64 v[200:201], s[20:21], 0, v[180:181]
	s_mov_b32 m0, s26
	s_nop 0
	global_load_lds_dwordx4 v[200:201], off
	v_lshl_add_u64 v[200:201], s[20:21], 0, v[176:177]
	s_add_i32 m0, s26, 0x2000
	s_nop 0
	global_load_lds_dwordx4 v[200:201], off
	v_lshl_add_u64 v[200:201], v[224:225], 0, s[14:15]
	s_mov_b32 m0, s52
	s_nop 0
	global_load_lds_dwordx4 v[200:201], off
	v_lshl_add_u64 v[200:201], v[226:227], 0, s[14:15]
	s_mov_b32 m0, s53
	s_nop 0
	global_load_lds_dwordx4 v[200:201], off
	s_waitcnt vmcnt(8)
	s_waitcnt lgkmcnt(0)
	s_setprio 1
	s_barrier
	v_mfma_f32_16x16x32_bf16 v[60:63], v[112:115], v[160:163], v[60:63]
	v_mfma_f32_16x16x32_bf16 v[56:59], v[136:139], v[160:163], v[56:59]
	v_mfma_f32_16x16x32_bf16 v[44:47], v[112:115], v[168:171], v[44:47]
	v_mfma_f32_16x16x32_bf16 v[40:43], v[136:139], v[168:171], v[40:43]
	v_mfma_f32_16x16x32_bf16 v[28:31], v[112:115], v[206:209], v[28:31]
	v_mfma_f32_16x16x32_bf16 v[24:27], v[136:139], v[206:209], v[24:27]
	v_mfma_f32_16x16x32_bf16 v[12:15], v[112:115], v[214:217], v[12:15]
	v_mfma_f32_16x16x32_bf16 v[8:11], v[136:139], v[214:217], v[8:11]
	v_mfma_f32_16x16x32_bf16 v[60:63], v[116:119], v[164:167], v[60:63]
	v_mfma_f32_16x16x32_bf16 v[56:59], v[140:143], v[164:167], v[56:59]
	v_mfma_f32_16x16x32_bf16 v[44:47], v[116:119], v[172:175], v[44:47]
	v_mfma_f32_16x16x32_bf16 v[40:43], v[140:143], v[172:175], v[40:43]
	v_mfma_f32_16x16x32_bf16 v[28:31], v[116:119], v[210:213], v[28:31]
	v_mfma_f32_16x16x32_bf16 v[24:27], v[140:143], v[210:213], v[24:27]
	v_mfma_f32_16x16x32_bf16 v[12:15], v[116:119], v[218:221], v[12:15]
	v_mfma_f32_16x16x32_bf16 v[8:11], v[140:143], v[218:221], v[8:11]
	v_mfma_f32_16x16x32_bf16 v[52:55], v[144:147], v[160:163], v[52:55]
	v_mfma_f32_16x16x32_bf16 v[48:51], v[152:155], v[160:163], v[48:51]
	v_mfma_f32_16x16x32_bf16 v[36:39], v[144:147], v[168:171], v[36:39]
	v_mfma_f32_16x16x32_bf16 v[32:35], v[152:155], v[168:171], v[32:35]
	v_mfma_f32_16x16x32_bf16 v[20:23], v[144:147], v[206:209], v[20:23]
	v_mfma_f32_16x16x32_bf16 v[16:19], v[152:155], v[206:209], v[16:19]
	v_mfma_f32_16x16x32_bf16 v[4:7], v[144:147], v[214:217], v[4:7]
	v_mfma_f32_16x16x32_bf16 v[0:3], v[152:155], v[214:217], v[0:3]
	v_mfma_f32_16x16x32_bf16 v[52:55], v[148:151], v[164:167], v[52:55]
	v_mfma_f32_16x16x32_bf16 v[48:51], v[156:159], v[164:167], v[48:51]
	v_mfma_f32_16x16x32_bf16 v[36:39], v[148:151], v[172:175], v[36:39]
	v_mfma_f32_16x16x32_bf16 v[32:35], v[156:159], v[172:175], v[32:35]
	v_mfma_f32_16x16x32_bf16 v[20:23], v[148:151], v[210:213], v[20:23]
	v_mfma_f32_16x16x32_bf16 v[16:19], v[156:159], v[210:213], v[16:19]
	v_mfma_f32_16x16x32_bf16 v[4:7], v[148:151], v[218:221], v[4:7]
	v_mfma_f32_16x16x32_bf16 v[0:3], v[156:159], v[218:221], v[0:3]
	s_barrier
	s_setprio 0
	s_add_i32 s82, s82, 2
	s_add_u32 s80, s80, 0x100
	s_addc_u32 s81, s81, 0
	s_cmp_gt_u32 s82, 41
	s_mov_b64 s[20:21], s[22:23]
.LBB0_836:
	ds_read_b128 v[112:115], v203
	ds_read_b128 v[116:119], v203 offset:1024
	ds_read_b128 v[136:139], v203 offset:2048
	ds_read_b128 v[140:143], v203 offset:3072
	ds_read_b128 v[144:147], v204
	ds_read_b128 v[148:151], v204 offset:1024
	ds_read_b128 v[152:155], v204 offset:2048
	ds_read_b128 v[156:159], v204 offset:3072
	s_add_u32 s22, s20, 0x100
	s_addc_u32 s23, s21, 0
	s_cmp_eq_u32 s82, 40
	s_cselect_b32 s37, s7, s23
	s_cselect_b32 s36, s6, s22
	s_cselect_b32 s27, s19, s81
	s_cselect_b32 s26, s18, s80
	v_lshl_add_u64 v[200:201], s[20:21], 0, v[186:187]
	s_add_i32 m0, s43, 0xc000
	ds_read_b128 v[160:163], v205
	ds_read_b128 v[164:167], v205 offset:1024
	ds_read_b128 v[168:171], v205 offset:2048
	ds_read_b128 v[172:175], v205 offset:3072
	ds_read_b128 v[206:209], v205 offset:4096
	ds_read_b128 v[210:213], v205 offset:5120
	ds_read_b128 v[214:217], v205 offset:6144
	ds_read_b128 v[218:221], v205 offset:7168
	global_load_lds_dwordx4 v[200:201], off
	v_lshl_add_u64 v[200:201], s[20:21], 0, v[188:189]
	s_add_i32 m0, s43, 0xe000
	s_nop 0
	global_load_lds_dwordx4 v[200:201], off
	s_waitcnt vmcnt(8)
	s_waitcnt lgkmcnt(0)
	s_setprio 1
	s_barrier
	v_mfma_f32_16x16x32_bf16 v[132:135], v[112:115], v[160:163], v[132:135]
	v_mfma_f32_16x16x32_bf16 v[128:131], v[136:139], v[160:163], v[128:131]
	v_mfma_f32_16x16x32_bf16 v[108:111], v[112:115], v[168:171], v[108:111]
	v_mfma_f32_16x16x32_bf16 v[104:107], v[136:139], v[168:171], v[104:107]
	v_mfma_f32_16x16x32_bf16 v[92:95], v[112:115], v[206:209], v[92:95]
	v_mfma_f32_16x16x32_bf16 v[88:91], v[136:139], v[206:209], v[88:91]
	v_mfma_f32_16x16x32_bf16 v[76:79], v[112:115], v[214:217], v[76:79]
	v_mfma_f32_16x16x32_bf16 v[72:75], v[136:139], v[214:217], v[72:75]
	v_mfma_f32_16x16x32_bf16 v[132:135], v[116:119], v[164:167], v[132:135]
	v_mfma_f32_16x16x32_bf16 v[128:131], v[140:143], v[164:167], v[128:131]
	v_mfma_f32_16x16x32_bf16 v[108:111], v[116:119], v[172:175], v[108:111]
	v_mfma_f32_16x16x32_bf16 v[104:107], v[140:143], v[172:175], v[104:107]
	v_mfma_f32_16x16x32_bf16 v[92:95], v[116:119], v[210:213], v[92:95]
	v_mfma_f32_16x16x32_bf16 v[88:91], v[140:143], v[210:213], v[88:91]
	v_mfma_f32_16x16x32_bf16 v[76:79], v[116:119], v[218:221], v[76:79]
	v_mfma_f32_16x16x32_bf16 v[72:75], v[140:143], v[218:221], v[72:75]
	v_mfma_f32_16x16x32_bf16 v[124:127], v[144:147], v[160:163], v[124:127]
	v_mfma_f32_16x16x32_bf16 v[120:123], v[152:155], v[160:163], v[120:123]
	v_mfma_f32_16x16x32_bf16 v[100:103], v[144:147], v[168:171], v[100:103]
	v_mfma_f32_16x16x32_bf16 v[96:99], v[152:155], v[168:171], v[96:99]
	v_mfma_f32_16x16x32_bf16 v[84:87], v[144:147], v[206:209], v[84:87]
	v_mfma_f32_16x16x32_bf16 v[80:83], v[152:155], v[206:209], v[80:83]
	v_mfma_f32_16x16x32_bf16 v[68:71], v[144:147], v[214:217], v[68:71]
	v_mfma_f32_16x16x32_bf16 v[64:67], v[152:155], v[214:217], v[64:67]
	v_mfma_f32_16x16x32_bf16 v[124:127], v[148:151], v[164:167], v[124:127]
	v_mfma_f32_16x16x32_bf16 v[120:123], v[156:159], v[164:167], v[120:123]
	v_mfma_f32_16x16x32_bf16 v[100:103], v[148:151], v[172:175], v[100:103]
	v_mfma_f32_16x16x32_bf16 v[96:99], v[156:159], v[172:175], v[96:99]
	v_mfma_f32_16x16x32_bf16 v[84:87], v[148:151], v[210:213], v[84:87]
	v_mfma_f32_16x16x32_bf16 v[80:83], v[156:159], v[210:213], v[80:83]
	v_mfma_f32_16x16x32_bf16 v[68:71], v[148:151], v[218:221], v[68:71]
	v_mfma_f32_16x16x32_bf16 v[64:67], v[156:159], v[218:221], v[64:67]
	s_barrier
	s_setprio 0
	s_add_i32 s20, s59, s40
	v_lshl_add_u64 v[200:201], s[26:27], 0, v[180:181]
	s_mov_b32 m0, s20
	ds_read_b128 v[160:163], v205 offset:16384
	ds_read_b128 v[164:167], v205 offset:17408
	ds_read_b128 v[168:171], v205 offset:18432
	ds_read_b128 v[172:175], v205 offset:19456
	ds_read_b128 v[206:209], v205 offset:20480
	ds_read_b128 v[210:213], v205 offset:21504
	ds_read_b128 v[214:217], v205 offset:22528
	ds_read_b128 v[218:221], v205 offset:23552
	global_load_lds_dwordx4 v[200:201], off
	s_add_i32 m0, s20, 0x2000
	s_add_u32 s20, s26, 0xb0000
	v_lshl_add_u64 v[222:223], s[26:27], 0, v[176:177]
	s_addc_u32 s21, s27, 0
	s_add_i32 s83, s66, s40
	global_load_lds_dwordx4 v[222:223], off
	v_lshl_add_u64 v[224:225], s[20:21], 0, v[180:181]
	s_mov_b32 m0, s83
	v_lshl_add_u64 v[226:227], s[36:37], 0, v[178:179]
	global_load_lds_dwordx4 v[224:225], off
	v_lshl_add_u64 v[224:225], s[20:21], 0, v[176:177]
	s_add_i32 m0, s83, 0x2000
	s_nop 0
	global_load_lds_dwordx4 v[224:225], off
	v_lshl_add_u64 v[224:225], s[36:37], 0, v[182:183]
	s_mov_b32 m0, s43
	s_nop 0
	global_load_lds_dwordx4 v[224:225], off
	s_mov_b32 m0, s44
	s_nop 0
	global_load_lds_dwordx4 v[226:227], off
	s_waitcnt vmcnt(8)
	s_waitcnt lgkmcnt(0)
	s_setprio 1
	s_barrier
	v_mfma_f32_16x16x32_bf16 v[60:63], v[112:115], v[160:163], v[60:63]
	v_mfma_f32_16x16x32_bf16 v[56:59], v[136:139], v[160:163], v[56:59]
	v_mfma_f32_16x16x32_bf16 v[44:47], v[112:115], v[168:171], v[44:47]
	v_mfma_f32_16x16x32_bf16 v[40:43], v[136:139], v[168:171], v[40:43]
	v_mfma_f32_16x16x32_bf16 v[28:31], v[112:115], v[206:209], v[28:31]
	v_mfma_f32_16x16x32_bf16 v[24:27], v[136:139], v[206:209], v[24:27]
	v_mfma_f32_16x16x32_bf16 v[12:15], v[112:115], v[214:217], v[12:15]
	v_mfma_f32_16x16x32_bf16 v[8:11], v[136:139], v[214:217], v[8:11]
	v_mfma_f32_16x16x32_bf16 v[60:63], v[116:119], v[164:167], v[60:63]
	v_mfma_f32_16x16x32_bf16 v[56:59], v[140:143], v[164:167], v[56:59]
	v_mfma_f32_16x16x32_bf16 v[44:47], v[116:119], v[172:175], v[44:47]
	v_mfma_f32_16x16x32_bf16 v[40:43], v[140:143], v[172:175], v[40:43]
	v_mfma_f32_16x16x32_bf16 v[28:31], v[116:119], v[210:213], v[28:31]
	v_mfma_f32_16x16x32_bf16 v[24:27], v[140:143], v[210:213], v[24:27]
	v_mfma_f32_16x16x32_bf16 v[12:15], v[116:119], v[218:221], v[12:15]
	v_mfma_f32_16x16x32_bf16 v[8:11], v[140:143], v[218:221], v[8:11]
	v_mfma_f32_16x16x32_bf16 v[52:55], v[144:147], v[160:163], v[52:55]
	v_mfma_f32_16x16x32_bf16 v[48:51], v[152:155], v[160:163], v[48:51]
	v_mfma_f32_16x16x32_bf16 v[36:39], v[144:147], v[168:171], v[36:39]
	v_mfma_f32_16x16x32_bf16 v[32:35], v[152:155], v[168:171], v[32:35]
	v_mfma_f32_16x16x32_bf16 v[20:23], v[144:147], v[206:209], v[20:23]
	v_mfma_f32_16x16x32_bf16 v[16:19], v[152:155], v[206:209], v[16:19]
	v_mfma_f32_16x16x32_bf16 v[4:7], v[144:147], v[214:217], v[4:7]
	v_mfma_f32_16x16x32_bf16 v[0:3], v[152:155], v[214:217], v[0:3]
	v_mfma_f32_16x16x32_bf16 v[52:55], v[148:151], v[164:167], v[52:55]
	v_mfma_f32_16x16x32_bf16 v[48:51], v[156:159], v[164:167], v[48:51]
	v_mfma_f32_16x16x32_bf16 v[36:39], v[148:151], v[172:175], v[36:39]
	v_mfma_f32_16x16x32_bf16 v[32:35], v[156:159], v[172:175], v[32:35]
	v_mfma_f32_16x16x32_bf16 v[20:23], v[148:151], v[210:213], v[20:23]
	v_mfma_f32_16x16x32_bf16 v[16:19], v[156:159], v[210:213], v[16:19]
	v_mfma_f32_16x16x32_bf16 v[4:7], v[148:151], v[218:221], v[4:7]
	v_mfma_f32_16x16x32_bf16 v[0:3], v[156:159], v[218:221], v[0:3]
	s_barrier
	s_setprio 0
	s_add_i32 s83, 0, 0x18000
	s_add_i32 s85, 0, 0x1c000
	v_add_u32_e32 v140, s83, v202
	v_add_u32_e32 v156, s85, v202
	ds_read_b128 v[112:115], v140
	ds_read_b128 v[116:119], v140 offset:1024
	ds_read_b128 v[136:139], v140 offset:2048
	ds_read_b128 v[140:143], v140 offset:3072
	ds_read_b128 v[144:147], v156
	ds_read_b128 v[148:151], v156 offset:1024
	ds_read_b128 v[152:155], v156 offset:2048
	ds_read_b128 v[156:159], v156 offset:3072
	s_add_u32 s20, s36, 0xb0000
	s_addc_u32 s21, s37, 0
	s_mov_b32 m0, s45
	v_lshl_add_u64 v[230:231], s[20:21], 0, v[182:183]
	ds_read_b128 v[160:163], v205 offset:32768
	ds_read_b128 v[164:167], v205 offset:33792
	ds_read_b128 v[168:171], v205 offset:34816
	ds_read_b128 v[172:175], v205 offset:35840
	ds_read_b128 v[206:209], v205 offset:36864
	ds_read_b128 v[210:213], v205 offset:37888
	ds_read_b128 v[214:217], v205 offset:38912
	ds_read_b128 v[218:221], v205 offset:39936
	global_load_lds_dwordx4 v[230:231], off
	v_lshl_add_u64 v[230:231], s[20:21], 0, v[178:179]
	s_mov_b32 m0, s46
	s_nop 0
	global_load_lds_dwordx4 v[230:231], off
	s_waitcnt vmcnt(8)
	s_waitcnt lgkmcnt(0)
	s_setprio 1
	s_barrier
	v_mfma_f32_16x16x32_bf16 v[132:135], v[112:115], v[160:163], v[132:135]
	v_mfma_f32_16x16x32_bf16 v[128:131], v[136:139], v[160:163], v[128:131]
	v_mfma_f32_16x16x32_bf16 v[108:111], v[112:115], v[168:171], v[108:111]
	v_mfma_f32_16x16x32_bf16 v[104:107], v[136:139], v[168:171], v[104:107]
	v_mfma_f32_16x16x32_bf16 v[92:95], v[112:115], v[206:209], v[92:95]
	v_mfma_f32_16x16x32_bf16 v[88:91], v[136:139], v[206:209], v[88:91]
	v_mfma_f32_16x16x32_bf16 v[76:79], v[112:115], v[214:217], v[76:79]
	v_mfma_f32_16x16x32_bf16 v[72:75], v[136:139], v[214:217], v[72:75]
	v_mfma_f32_16x16x32_bf16 v[132:135], v[116:119], v[164:167], v[132:135]
	v_mfma_f32_16x16x32_bf16 v[128:131], v[140:143], v[164:167], v[128:131]
	v_mfma_f32_16x16x32_bf16 v[108:111], v[116:119], v[172:175], v[108:111]
	v_mfma_f32_16x16x32_bf16 v[104:107], v[140:143], v[172:175], v[104:107]
	v_mfma_f32_16x16x32_bf16 v[92:95], v[116:119], v[210:213], v[92:95]
	v_mfma_f32_16x16x32_bf16 v[88:91], v[140:143], v[210:213], v[88:91]
	v_mfma_f32_16x16x32_bf16 v[76:79], v[116:119], v[218:221], v[76:79]
	v_mfma_f32_16x16x32_bf16 v[72:75], v[140:143], v[218:221], v[72:75]
	v_mfma_f32_16x16x32_bf16 v[124:127], v[144:147], v[160:163], v[124:127]
	v_mfma_f32_16x16x32_bf16 v[120:123], v[152:155], v[160:163], v[120:123]
	v_mfma_f32_16x16x32_bf16 v[100:103], v[144:147], v[168:171], v[100:103]
	v_mfma_f32_16x16x32_bf16 v[96:99], v[152:155], v[168:171], v[96:99]
	v_mfma_f32_16x16x32_bf16 v[84:87], v[144:147], v[206:209], v[84:87]
	v_mfma_f32_16x16x32_bf16 v[80:83], v[152:155], v[206:209], v[80:83]
	v_mfma_f32_16x16x32_bf16 v[68:71], v[144:147], v[214:217], v[68:71]
	v_mfma_f32_16x16x32_bf16 v[64:67], v[152:155], v[214:217], v[64:67]
	v_mfma_f32_16x16x32_bf16 v[124:127], v[148:151], v[164:167], v[124:127]
	v_mfma_f32_16x16x32_bf16 v[120:123], v[156:159], v[164:167], v[120:123]
	v_mfma_f32_16x16x32_bf16 v[100:103], v[148:151], v[172:175], v[100:103]
	v_mfma_f32_16x16x32_bf16 v[96:99], v[156:159], v[172:175], v[96:99]
	v_mfma_f32_16x16x32_bf16 v[84:87], v[148:151], v[210:213], v[84:87]
	v_mfma_f32_16x16x32_bf16 v[80:83], v[156:159], v[210:213], v[80:83]
	v_mfma_f32_16x16x32_bf16 v[68:71], v[148:151], v[218:221], v[68:71]
	v_mfma_f32_16x16x32_bf16 v[64:67], v[156:159], v[218:221], v[64:67]
	s_barrier
	s_setprio 0
	s_add_i32 s20, s83, s40
	v_lshl_add_u64 v[200:201], v[200:201], 0, s[14:15]
	s_mov_b32 m0, s20
	ds_read_b128 v[160:163], v205 offset:49152
	ds_read_b128 v[164:167], v205 offset:50176
	ds_read_b128 v[168:171], v205 offset:51200
	ds_read_b128 v[172:175], v205 offset:52224
	ds_read_b128 v[206:209], v205 offset:53248
	ds_read_b128 v[210:213], v205 offset:54272
	ds_read_b128 v[214:217], v205 offset:55296
	ds_read_b128 v[218:221], v205 offset:56320
	global_load_lds_dwordx4 v[200:201], off
	s_add_i32 m0, s20, 0x2000
	s_add_u32 s20, s26, 0xb0080
	v_lshl_add_u64 v[200:201], v[222:223], 0, s[14:15]
	s_addc_u32 s21, s27, 0
	s_add_i32 s26, s85, s40
	global_load_lds_dwordx4 v[200:201], off
	v_lshl_add_u64 v[200:201], s[20:21], 0, v[180:181]
	s_mov_b32 m0, s26
	s_nop 0
	global_load_lds_dwordx4 v[200:201], off
	v_lshl_add_u64 v[200:201], s[20:21], 0, v[176:177]
	s_add_i32 m0, s26, 0x2000
	s_nop 0
	global_load_lds_dwordx4 v[200:201], off
	v_lshl_add_u64 v[200:201], v[224:225], 0, s[14:15]
	s_mov_b32 m0, s52
	s_nop 0
	global_load_lds_dwordx4 v[200:201], off
	v_lshl_add_u64 v[200:201], v[226:227], 0, s[14:15]
	s_mov_b32 m0, s53
	s_nop 0
	global_load_lds_dwordx4 v[200:201], off
	s_waitcnt vmcnt(8)
	s_waitcnt lgkmcnt(0)
	s_setprio 1
	s_barrier
	v_mfma_f32_16x16x32_bf16 v[60:63], v[112:115], v[160:163], v[60:63]
	v_mfma_f32_16x16x32_bf16 v[56:59], v[136:139], v[160:163], v[56:59]
	v_mfma_f32_16x16x32_bf16 v[44:47], v[112:115], v[168:171], v[44:47]
	v_mfma_f32_16x16x32_bf16 v[40:43], v[136:139], v[168:171], v[40:43]
	v_mfma_f32_16x16x32_bf16 v[28:31], v[112:115], v[206:209], v[28:31]
	v_mfma_f32_16x16x32_bf16 v[24:27], v[136:139], v[206:209], v[24:27]
	v_mfma_f32_16x16x32_bf16 v[12:15], v[112:115], v[214:217], v[12:15]
	v_mfma_f32_16x16x32_bf16 v[8:11], v[136:139], v[214:217], v[8:11]
	v_mfma_f32_16x16x32_bf16 v[60:63], v[116:119], v[164:167], v[60:63]
	v_mfma_f32_16x16x32_bf16 v[56:59], v[140:143], v[164:167], v[56:59]
	v_mfma_f32_16x16x32_bf16 v[44:47], v[116:119], v[172:175], v[44:47]
	v_mfma_f32_16x16x32_bf16 v[40:43], v[140:143], v[172:175], v[40:43]
	v_mfma_f32_16x16x32_bf16 v[28:31], v[116:119], v[210:213], v[28:31]
	v_mfma_f32_16x16x32_bf16 v[24:27], v[140:143], v[210:213], v[24:27]
	v_mfma_f32_16x16x32_bf16 v[12:15], v[116:119], v[218:221], v[12:15]
	v_mfma_f32_16x16x32_bf16 v[8:11], v[140:143], v[218:221], v[8:11]
	v_mfma_f32_16x16x32_bf16 v[52:55], v[144:147], v[160:163], v[52:55]
	v_mfma_f32_16x16x32_bf16 v[48:51], v[152:155], v[160:163], v[48:51]
	v_mfma_f32_16x16x32_bf16 v[36:39], v[144:147], v[168:171], v[36:39]
	v_mfma_f32_16x16x32_bf16 v[32:35], v[152:155], v[168:171], v[32:35]
	v_mfma_f32_16x16x32_bf16 v[20:23], v[144:147], v[206:209], v[20:23]
	v_mfma_f32_16x16x32_bf16 v[16:19], v[152:155], v[206:209], v[16:19]
	v_mfma_f32_16x16x32_bf16 v[4:7], v[144:147], v[214:217], v[4:7]
	v_mfma_f32_16x16x32_bf16 v[0:3], v[152:155], v[214:217], v[0:3]
	v_mfma_f32_16x16x32_bf16 v[52:55], v[148:151], v[164:167], v[52:55]
	v_mfma_f32_16x16x32_bf16 v[48:51], v[156:159], v[164:167], v[48:51]
	v_mfma_f32_16x16x32_bf16 v[36:39], v[148:151], v[172:175], v[36:39]
	v_mfma_f32_16x16x32_bf16 v[32:35], v[156:159], v[172:175], v[32:35]
	v_mfma_f32_16x16x32_bf16 v[20:23], v[148:151], v[210:213], v[20:23]
	v_mfma_f32_16x16x32_bf16 v[16:19], v[156:159], v[210:213], v[16:19]
	v_mfma_f32_16x16x32_bf16 v[4:7], v[148:151], v[218:221], v[4:7]
	v_mfma_f32_16x16x32_bf16 v[0:3], v[156:159], v[218:221], v[0:3]
	s_barrier
	s_setprio 0
	s_add_i32 s82, s82, 2
	s_add_u32 s80, s80, 0x100
	s_addc_u32 s81, s81, 0
	s_cmp_gt_u32 s82, 41
	s_mov_b64 s[20:21], s[22:23]
	s_cbranch_scc0 .LBB0_836
	s_and_b64 vcc, exec, s[16:17]
	s_cbranch_vccz .LBB0_839
	s_barrier
